# v80 + 222 single-element f32->bf16 bit-trick sites (bfe+add3 -> global_store_short_d16_hi) replaced by v_cvt_pk_bf16_f32 + global_store_short (P2 / mLSTM output phases)
# speedup vs baseline: 1.0020x; 1.0020x over previous
.LBB0_644:
	s_or_b64 exec, exec, s[0:1]
	s_waitcnt lgkmcnt(0)
	v_add_u32_e32 v72, v161, v178
	ds_read_b128 v[64:67], v72
	ds_read_b128 v[68:71], v72 offset:32
	s_lshl_b64 s[0:1], s[18:19], 1
	s_add_u32 s0, s46, s0
	s_addc_u32 s1, s47, s1
	s_waitcnt lgkmcnt(1)
	v_rcp_f32_e32 v102, v64
	v_rcp_f32_e32 v98, v65
	v_rcp_f32_e32 v96, v66
	v_rcp_f32_e32 v94, v67
	ds_read_b128 v[64:67], v72 offset:64
	s_waitcnt lgkmcnt(1)
	v_rcp_f32_e32 v92, v68
	v_rcp_f32_e32 v90, v69
	s_add_u32 s0, s0, s88
	v_ashrrev_i32_e32 v161, 31, v160
	s_waitcnt lgkmcnt(0)
	v_rcp_f32_e32 v84, v64
	v_rcp_f32_e32 v82, v65
	v_rcp_f32_e32 v80, v66
	v_rcp_f32_e32 v78, v67
	ds_read_b128 v[64:67], v72 offset:96
	s_addc_u32 s1, s1, 0
	v_lshlrev_b32_e32 v178, 1, v165
	v_rcp_f32_e32 v88, v70
	v_rcp_f32_e32 v86, v71
	s_waitcnt lgkmcnt(0)
	v_rcp_f32_e32 v68, v66
	v_rcp_f32_e32 v66, v67
	v_lshlrev_b32_e32 v67, 2, v165
	global_load_dword v69, v67, s[8:9]
	v_rcp_f32_e32 v76, v64
	v_rcp_f32_e32 v74, v65
	v_lshlrev_b64 v[64:65], 12, v[160:161]
	v_lshl_add_u64 v[100:101], s[0:1], 0, v[64:65]
	v_lshl_add_u64 v[64:65], s[28:29], 0, v[64:65]
	v_lshlrev_b32_e32 v70, 14, v164
	v_lshl_add_u64 v[72:73], v[64:65], 0, v[178:179]
	v_mov_b32_e32 v71, v179
	v_lshl_add_u64 v[104:105], v[72:73], 0, v[70:71]
	v_mov_b32_e32 v108, v32
	v_mov_b32_e32 v109, v48
	v_mov_b32_e32 v110, v16
	v_mov_b32_e32 v111, v0
	v_lshl_add_u64 v[106:107], v[100:101], 0, v[178:179]
	s_mov_b64 s[0:1], 0xc00
	v_pk_mul_f32 v[108:109], v[108:109], v[102:103] op_sel_hi:[1,0]
	v_pk_mul_f32 v[102:103], v[110:111], v[102:103] op_sel_hi:[1,0]
	v_or_b32_e32 v178, 0x1000, v70
	v_lshl_add_u64 v[64:65], v[106:107], 0, s[0:1]
	s_mov_b32 s0, 0x358637bd
	s_brev_b32 s6, 60
	s_mov_b32 s88, 0x800000
	s_waitcnt vmcnt(0)
	v_mul_f32_e32 v77, v197, v69
	global_load_dword v69, v67, s[8:9] offset:128
	s_waitcnt vmcnt(0)
	v_mul_f32_e32 v75, v197, v69
	global_load_dword v69, v67, s[8:9] offset:256
	s_waitcnt vmcnt(0)
	v_mul_f32_e32 v69, v197, v69
	global_load_dword v67, v67, s[8:9] offset:384
	s_nop 0
	global_load_ushort v79, v[104:105], off
	global_load_ushort v81, v[104:105], off offset:64
	global_load_ushort v32, v[104:105], off offset:128
	global_load_ushort v48, v[104:105], off offset:192
	s_waitcnt vmcnt(3)
	v_lshlrev_b32_e32 v100, 16, v79
	s_waitcnt vmcnt(1)
	v_lshlrev_b32_e32 v104, 16, v32
	s_waitcnt vmcnt(0)
	v_lshlrev_b32_e32 v105, 16, v48
	v_pk_fma_f32 v[104:105], v[184:185], v[102:103], v[104:105] neg_lo:[1,0,0] neg_hi:[1,0,0]
	v_lshl_add_u64 v[102:103], v[106:107], 0, v[70:71]
	v_lshl_add_u64 v[106:107], v[72:73], 0, v[178:179]
	global_load_ushort v0, v[106:107], off
	global_load_ushort v16, v[106:107], off offset:64
	v_mov_b32_e32 v48, v33
	v_lshlrev_b32_e32 v101, 16, v81
	v_pk_mul_f32 v[32:33], v[48:49], v[98:99] op_sel_hi:[1,0]
	v_pk_fma_f32 v[100:101], v[184:185], v[108:109], v[100:101] neg_lo:[1,0,0] neg_hi:[1,0,0]
	v_pk_mul_f32 v[110:111], v[104:105], v[104:105]
	v_pk_mul_f32 v[108:109], v[100:101], v[100:101]
	v_mul_f32_e32 v67, v197, v67
	s_waitcnt vmcnt(1)
	v_lshlrev_b32_e32 v112, 16, v0
	s_waitcnt vmcnt(0)
	v_lshlrev_b32_e32 v113, 16, v16
	global_load_ushort v0, v[106:107], off offset:128
	global_load_ushort v16, v[106:107], off offset:192
	v_pk_fma_f32 v[32:33], v[184:185], v[32:33], v[112:113] neg_lo:[1,0,0] neg_hi:[1,0,0]
	s_waitcnt vmcnt(1)
	v_lshlrev_b32_e32 v106, 16, v0
	v_mov_b32_e32 v0, v17
	s_waitcnt vmcnt(0)
	v_lshlrev_b32_e32 v107, 16, v16
	v_pk_mul_f32 v[0:1], v[0:1], v[98:99] op_sel_hi:[1,0]
	v_pk_mul_f32 v[48:49], v[32:33], v[32:33]
	v_pk_fma_f32 v[16:17], v[184:185], v[0:1], v[106:107] neg_lo:[1,0,0] neg_hi:[1,0,0]
	v_mov_b32_e32 v98, v48
	v_pk_mul_f32 v[0:1], v[16:17], v[16:17]
	v_mov_b32_e32 v99, v108
	v_mov_b32_e32 v108, v49
	v_pk_add_f32 v[48:49], v[98:99], v[108:109]
	v_mov_b32_e32 v98, v0
	v_mov_b32_e32 v99, v110
	v_pk_add_f32 v[48:49], v[48:49], v[98:99]
	v_mov_b32_e32 v110, v1
	v_pk_add_f32 v[0:1], v[48:49], v[110:111]
	ds_bpermute_b32 v49, v191, v1
	ds_bpermute_b32 v48, v191, v0
	s_waitcnt lgkmcnt(0)
	v_pk_add_f32 v[0:1], v[0:1], v[48:49]
	ds_bpermute_b32 v49, v192, v1
	ds_bpermute_b32 v48, v192, v0
	s_waitcnt lgkmcnt(0)
	v_pk_add_f32 v[0:1], v[0:1], v[48:49]
	ds_bpermute_b32 v49, v193, v1
	ds_bpermute_b32 v48, v193, v0
	s_waitcnt lgkmcnt(0)
	v_pk_add_f32 v[0:1], v[0:1], v[48:49]
	ds_bpermute_b32 v49, v194, v1
	ds_bpermute_b32 v48, v194, v0
	s_waitcnt lgkmcnt(0)
	v_pk_add_f32 v[0:1], v[0:1], v[48:49]
	ds_bpermute_b32 v49, v195, v1
	ds_bpermute_b32 v48, v195, v0
	s_waitcnt lgkmcnt(0)
	v_pk_add_f32 v[48:49], v[0:1], v[48:49]
	v_mov_b64_e32 v[0:1], s[0:1]
	v_pk_fma_f32 v[48:49], v[48:49], s[6:7], v[0:1] op_sel_hi:[1,0,0]
	s_nop 0
	v_mul_f32_e32 v71, 0x4b800000, v49
	v_cmp_gt_f32_e64 s[0:1], s88, v49
	v_cmp_gt_f32_e32 vcc, s88, v48
	s_nop 0
	v_cndmask_b32_e64 v49, v49, v71, s[0:1]
	v_rsq_f32_e32 v49, v49
	s_nop 0
	v_mul_f32_e32 v71, 0x45800000, v49
	v_cndmask_b32_e64 v49, v49, v71, s[0:1]
	v_mul_f32_e32 v71, v100, v49
	v_mul_f32_e32 v71, v77, v71
	s_nop 0
	v_cvt_pk_bf16_f32 v71, v71, v71
	global_store_short v[102:103], v71, off offset:3072
	v_mul_f32_e32 v71, v101, v49
	v_mul_f32_e32 v71, v75, v71
	v_cvt_pk_bf16_f32 v71, v71, v71
	global_store_short v[102:103], v71, off offset:3136
	v_mul_f32_e32 v71, v104, v49
	v_mul_f32_e32 v71, v69, v71
	v_mul_f32_e32 v49, v105, v49
	v_cvt_pk_bf16_f32 v71, v71, v71
	v_mul_f32_e32 v49, v67, v49
	global_store_short v[102:103], v71, off offset:3200
	s_nop 0
	v_cvt_pk_bf16_f32 v49, v49, v49
	global_store_short v[102:103], v49, off offset:3264
	v_mul_f32_e32 v49, 0x4b800000, v48
	v_cndmask_b32_e32 v48, v48, v49, vcc
	v_rsq_f32_e32 v48, v48
	s_nop 0
	v_mul_f32_e32 v49, 0x45800000, v48
	v_cndmask_b32_e32 v71, v48, v49, vcc
	v_mul_f32_e32 v32, v32, v71
	v_mul_f32_e32 v32, v77, v32
	s_nop 0
	v_lshl_add_u64 v[48:49], v[64:65], 0, v[178:179]
	v_cvt_pk_bf16_f32 v32, v32, v32
	global_store_short v[48:49], v32, off
	v_mul_f32_e32 v32, v33, v71
	v_mul_f32_e32 v32, v75, v32
	v_mul_f32_e32 v16, v16, v71
	v_cvt_pk_bf16_f32 v32, v32, v32
	v_mul_f32_e32 v16, v69, v16
	global_store_short v[48:49], v32, off offset:64
	v_cvt_pk_bf16_f32 v16, v16, v16
	global_store_short v[48:49], v16, off offset:128
	v_mul_f32_e32 v16, v17, v71
	v_mul_f32_e32 v16, v67, v16
	v_cvt_pk_bf16_f32 v16, v16, v16
	v_or_b32_e32 v178, 0x2000, v70
	global_store_short v[48:49], v16, off offset:192
	v_lshl_add_u64 v[16:17], v[72:73], 0, v[178:179]
	global_load_ushort v32, v[16:17], off
	global_load_ushort v33, v[16:17], off offset:64
	v_mov_b32_e32 v48, v34
	v_mov_b32_e32 v49, v50
	v_pk_mul_f32 v[48:49], v[48:49], v[96:97] op_sel_hi:[1,0]
	v_lshl_add_u64 v[100:101], v[64:65], 0, v[178:179]
	v_or_b32_e32 v178, 0x3000, v70
	v_lshl_add_u64 v[102:103], v[72:73], 0, v[178:179]
	v_mov_b32_e32 v50, v35
	v_pk_mul_f32 v[34:35], v[50:51], v[94:95] op_sel_hi:[1,0]
	s_waitcnt vmcnt(1)
	v_lshlrev_b32_e32 v32, 16, v32
	s_waitcnt vmcnt(0)
	v_lshlrev_b32_e32 v33, 16, v33
	v_pk_fma_f32 v[48:49], v[184:185], v[48:49], v[32:33] neg_lo:[1,0,0] neg_hi:[1,0,0]
	global_load_ushort v32, v[16:17], off offset:128
	s_nop 0
	global_load_ushort v16, v[16:17], off offset:192
	v_mov_b32_e32 v33, v2
	v_pk_mul_f32 v[98:99], v[48:49], v[48:49]
	s_waitcnt vmcnt(0)
	v_lshlrev_b32_e32 v17, 16, v16
	v_lshlrev_b32_e32 v16, 16, v32
	v_mov_b32_e32 v32, v18
	v_pk_mul_f32 v[32:33], v[32:33], v[96:97] op_sel_hi:[1,0]
	s_nop 0
	v_pk_fma_f32 v[32:33], v[184:185], v[32:33], v[16:17] neg_lo:[1,0,0] neg_hi:[1,0,0]
	global_load_ushort v2, v[102:103], off
	global_load_ushort v16, v[102:103], off offset:64
	v_pk_mul_f32 v[96:97], v[32:33], v[32:33]
	s_waitcnt vmcnt(0)
	v_lshlrev_b32_e32 v17, 16, v16
	v_lshlrev_b32_e32 v16, 16, v2
	global_load_ushort v2, v[102:103], off offset:128
	global_load_ushort v18, v[102:103], off offset:192
	v_pk_fma_f32 v[16:17], v[184:185], v[34:35], v[16:17] neg_lo:[1,0,0] neg_hi:[1,0,0]
	s_waitcnt vmcnt(1)
	v_lshlrev_b32_e32 v50, 16, v2
	v_mov_b32_e32 v2, v19
	s_waitcnt vmcnt(0)
	v_lshlrev_b32_e32 v51, 16, v18
	v_pk_mul_f32 v[2:3], v[2:3], v[94:95] op_sel_hi:[1,0]
	v_pk_mul_f32 v[34:35], v[16:17], v[16:17]
	v_pk_fma_f32 v[2:3], v[184:185], v[2:3], v[50:51] neg_lo:[1,0,0] neg_hi:[1,0,0]
	v_mov_b32_e32 v50, v34
	v_pk_mul_f32 v[18:19], v[2:3], v[2:3]
	v_mov_b32_e32 v51, v98
	v_mov_b32_e32 v98, v35
	v_pk_add_f32 v[34:35], v[50:51], v[98:99]
	v_mov_b32_e32 v50, v18
	v_mov_b32_e32 v51, v96
	v_pk_add_f32 v[34:35], v[34:35], v[50:51]
	v_mov_b32_e32 v96, v19
	v_pk_add_f32 v[18:19], v[34:35], v[96:97]
	ds_bpermute_b32 v35, v191, v19
	ds_bpermute_b32 v34, v191, v18
	s_waitcnt lgkmcnt(0)
	v_pk_add_f32 v[18:19], v[18:19], v[34:35]
	ds_bpermute_b32 v35, v192, v19
	ds_bpermute_b32 v34, v192, v18
	s_waitcnt lgkmcnt(0)
	v_pk_add_f32 v[18:19], v[18:19], v[34:35]
	ds_bpermute_b32 v35, v193, v19
	ds_bpermute_b32 v34, v193, v18
	s_waitcnt lgkmcnt(0)
	v_pk_add_f32 v[18:19], v[18:19], v[34:35]
	ds_bpermute_b32 v35, v194, v19
	ds_bpermute_b32 v34, v194, v18
	s_waitcnt lgkmcnt(0)
	v_pk_add_f32 v[18:19], v[18:19], v[34:35]
	ds_bpermute_b32 v35, v195, v19
	ds_bpermute_b32 v34, v195, v18
	s_waitcnt lgkmcnt(0)
	v_pk_add_f32 v[18:19], v[18:19], v[34:35]
	s_nop 0
	v_pk_fma_f32 v[18:19], v[18:19], s[6:7], v[0:1] op_sel_hi:[1,0,0]
	s_nop 0
	v_mul_f32_e32 v34, 0x4b800000, v19
	v_cmp_gt_f32_e64 s[0:1], s88, v19
	v_cmp_gt_f32_e32 vcc, s88, v18
	s_nop 0
	v_cndmask_b32_e64 v19, v19, v34, s[0:1]
	v_rsq_f32_e32 v19, v19
	s_nop 0
	v_mul_f32_e32 v34, 0x45800000, v19
	v_cndmask_b32_e64 v19, v19, v34, s[0:1]
	v_mul_f32_e32 v34, v48, v19
	v_mul_f32_e32 v34, v77, v34
	s_nop 0
	v_cvt_pk_bf16_f32 v34, v34, v34
	global_store_short v[100:101], v34, off
	v_mul_f32_e32 v34, v49, v19
	v_mul_f32_e32 v34, v75, v34
	v_mul_f32_e32 v32, v32, v19
	v_cvt_pk_bf16_f32 v34, v34, v34
	v_mul_f32_e32 v32, v69, v32
	global_store_short v[100:101], v34, off offset:64
	v_mul_f32_e32 v19, v33, v19
	v_cvt_pk_bf16_f32 v32, v32, v32
	v_mul_f32_e32 v19, v67, v19
	global_store_short v[100:101], v32, off offset:128
	s_nop 0
	v_cvt_pk_bf16_f32 v19, v19, v19
	global_store_short v[100:101], v19, off offset:192
	v_mul_f32_e32 v19, 0x4b800000, v18
	v_cndmask_b32_e32 v18, v18, v19, vcc
	v_rsq_f32_e32 v18, v18
	s_nop 0
	v_mul_f32_e32 v19, 0x45800000, v18
	v_cndmask_b32_e32 v32, v18, v19, vcc
	v_mul_f32_e32 v16, v16, v32
	v_mul_f32_e32 v16, v77, v16
	s_nop 0
	v_lshl_add_u64 v[18:19], v[64:65], 0, v[178:179]
	v_cvt_pk_bf16_f32 v16, v16, v16
	global_store_short v[18:19], v16, off
	v_mul_f32_e32 v16, v17, v32
	v_mul_f32_e32 v16, v75, v16
	v_mul_f32_e32 v2, v2, v32
	v_cvt_pk_bf16_f32 v16, v16, v16
	v_mul_f32_e32 v2, v69, v2
	global_store_short v[18:19], v16, off offset:64
	v_cvt_pk_bf16_f32 v2, v2, v2
	global_store_short v[18:19], v2, off offset:128
	v_mul_f32_e32 v2, v3, v32
	v_mul_f32_e32 v2, v67, v2
	v_cvt_pk_bf16_f32 v2, v2, v2
	v_or_b32_e32 v178, 0x8000, v70
	global_store_short v[18:19], v2, off offset:192
	v_lshl_add_u64 v[2:3], v[72:73], 0, v[178:179]
	global_load_ushort v16, v[2:3], off
	global_load_ushort v17, v[2:3], off offset:64
	global_load_ushort v32, v[2:3], off offset:128
	s_nop 0
	global_load_ushort v2, v[2:3], off offset:192
	v_mov_b32_e32 v33, v4
	v_lshl_add_u64 v[34:35], v[64:65], 0, v[178:179]
	v_or_b32_e32 v178, 0x9000, v70
	v_lshl_add_u64 v[50:51], v[72:73], 0, v[178:179]
	v_mov_b32_e32 v18, v36
	v_mov_b32_e32 v19, v52
	v_mov_b32_e32 v52, v37
	v_pk_mul_f32 v[18:19], v[18:19], v[92:93] op_sel_hi:[1,0]
	v_pk_mul_f32 v[36:37], v[52:53], v[90:91] op_sel_hi:[1,0]
	s_waitcnt vmcnt(3)
	v_lshlrev_b32_e32 v16, 16, v16
	s_waitcnt vmcnt(2)
	v_lshlrev_b32_e32 v17, 16, v17
	s_waitcnt vmcnt(0)
	v_lshlrev_b32_e32 v3, 16, v2
	v_lshlrev_b32_e32 v2, 16, v32
	v_mov_b32_e32 v32, v20
	v_pk_mul_f32 v[32:33], v[32:33], v[92:93] op_sel_hi:[1,0]
	v_pk_fma_f32 v[16:17], v[184:185], v[18:19], v[16:17] neg_lo:[1,0,0] neg_hi:[1,0,0]
	v_pk_fma_f32 v[32:33], v[184:185], v[32:33], v[2:3] neg_lo:[1,0,0] neg_hi:[1,0,0]
	global_load_ushort v2, v[50:51], off
	global_load_ushort v3, v[50:51], off offset:64
	global_load_ushort v4, v[50:51], off offset:128
	global_load_ushort v20, v[50:51], off offset:192
	v_pk_mul_f32 v[18:19], v[16:17], v[16:17]
	v_pk_mul_f32 v[48:49], v[32:33], v[32:33]
	s_waitcnt vmcnt(3)
	v_lshlrev_b32_e32 v2, 16, v2
	s_waitcnt vmcnt(2)
	v_lshlrev_b32_e32 v3, 16, v3
	s_waitcnt vmcnt(1)
	v_lshlrev_b32_e32 v50, 16, v4
	v_mov_b32_e32 v4, v21
	v_pk_fma_f32 v[2:3], v[184:185], v[36:37], v[2:3] neg_lo:[1,0,0] neg_hi:[1,0,0]
	s_waitcnt vmcnt(0)
	v_lshlrev_b32_e32 v51, 16, v20
	v_pk_mul_f32 v[4:5], v[4:5], v[90:91] op_sel_hi:[1,0]
	v_pk_mul_f32 v[36:37], v[2:3], v[2:3]
	v_pk_fma_f32 v[4:5], v[184:185], v[4:5], v[50:51] neg_lo:[1,0,0] neg_hi:[1,0,0]
	v_mov_b32_e32 v50, v36
	v_pk_mul_f32 v[20:21], v[4:5], v[4:5]
	v_mov_b32_e32 v51, v18
	v_mov_b32_e32 v18, v37
	v_pk_add_f32 v[18:19], v[50:51], v[18:19]
	v_mov_b32_e32 v36, v20
	v_mov_b32_e32 v37, v48
	v_pk_add_f32 v[18:19], v[18:19], v[36:37]
	v_mov_b32_e32 v48, v21
	v_pk_add_f32 v[18:19], v[18:19], v[48:49]
	ds_bpermute_b32 v21, v191, v19
	ds_bpermute_b32 v20, v191, v18
	s_waitcnt lgkmcnt(0)
	v_pk_add_f32 v[18:19], v[18:19], v[20:21]
	ds_bpermute_b32 v21, v192, v19
	ds_bpermute_b32 v20, v192, v18
	s_waitcnt lgkmcnt(0)
	v_pk_add_f32 v[18:19], v[18:19], v[20:21]
	ds_bpermute_b32 v21, v193, v19
	ds_bpermute_b32 v20, v193, v18
	s_waitcnt lgkmcnt(0)
	v_pk_add_f32 v[18:19], v[18:19], v[20:21]
	ds_bpermute_b32 v21, v194, v19
	ds_bpermute_b32 v20, v194, v18
	s_waitcnt lgkmcnt(0)
	v_pk_add_f32 v[18:19], v[18:19], v[20:21]
	ds_bpermute_b32 v21, v195, v19
	ds_bpermute_b32 v20, v195, v18
	s_waitcnt lgkmcnt(0)
	v_pk_add_f32 v[18:19], v[18:19], v[20:21]
	s_nop 0
	v_pk_fma_f32 v[18:19], v[18:19], s[6:7], v[0:1] op_sel_hi:[1,0,0]
	s_nop 0
	v_mul_f32_e32 v20, 0x4b800000, v19
	v_cmp_gt_f32_e64 s[0:1], s88, v19
	v_cmp_gt_f32_e32 vcc, s88, v18
	s_nop 0
	v_cndmask_b32_e64 v19, v19, v20, s[0:1]
	v_rsq_f32_e32 v19, v19
	s_nop 0
	v_mul_f32_e32 v20, 0x45800000, v19
	v_cndmask_b32_e64 v19, v19, v20, s[0:1]
	v_mul_f32_e32 v16, v16, v19
	v_mul_f32_e32 v16, v77, v16
	s_nop 0
	v_cvt_pk_bf16_f32 v16, v16, v16
	global_store_short v[34:35], v16, off
	v_mul_f32_e32 v16, v17, v19
	v_mul_f32_e32 v16, v75, v16
	v_cvt_pk_bf16_f32 v16, v16, v16
	global_store_short v[34:35], v16, off offset:64
	v_mul_f32_e32 v16, v32, v19
	v_mul_f32_e32 v16, v69, v16
	v_cvt_pk_bf16_f32 v16, v16, v16
	global_store_short v[34:35], v16, off offset:128
	v_mul_f32_e32 v16, v33, v19
	v_mul_f32_e32 v16, v67, v16
	s_nop 0
	v_cvt_pk_bf16_f32 v16, v16, v16
	global_store_short v[34:35], v16, off offset:192
	v_mul_f32_e32 v16, 0x4b800000, v18
	v_cndmask_b32_e32 v16, v18, v16, vcc
	v_rsq_f32_e32 v16, v16
	s_nop 0
	v_mul_f32_e32 v17, 0x45800000, v16
	v_cndmask_b32_e32 v18, v16, v17, vcc
	v_mul_f32_e32 v2, v2, v18
	v_mul_f32_e32 v2, v77, v2
	s_nop 0
	v_lshl_add_u64 v[16:17], v[64:65], 0, v[178:179]
	v_cvt_pk_bf16_f32 v2, v2, v2
	global_store_short v[16:17], v2, off
	v_mul_f32_e32 v2, v3, v18
	v_mul_f32_e32 v2, v75, v2
	v_cvt_pk_bf16_f32 v2, v2, v2
	global_store_short v[16:17], v2, off offset:64
	v_mul_f32_e32 v2, v4, v18
	v_mul_f32_e32 v2, v69, v2
	v_cvt_pk_bf16_f32 v2, v2, v2
	global_store_short v[16:17], v2, off offset:128
	v_mul_f32_e32 v2, v5, v18
	v_mul_f32_e32 v2, v67, v2
	v_cvt_pk_bf16_f32 v2, v2, v2
	v_or_b32_e32 v178, 0xa000, v70
	global_store_short v[16:17], v2, off offset:192
	v_lshl_add_u64 v[2:3], v[72:73], 0, v[178:179]
	global_load_ushort v4, v[2:3], off
	global_load_ushort v5, v[2:3], off offset:64
	global_load_ushort v18, v[2:3], off offset:128
	s_nop 0
	global_load_ushort v2, v[2:3], off offset:192
	v_mov_b32_e32 v19, v6
	v_lshl_add_u64 v[20:21], v[64:65], 0, v[178:179]
	v_or_b32_e32 v178, 0xb000, v70
	v_lshl_add_u64 v[36:37], v[72:73], 0, v[178:179]
	v_mov_b32_e32 v16, v38
	v_mov_b32_e32 v17, v54
	v_mov_b32_e32 v54, v39
	v_pk_mul_f32 v[16:17], v[16:17], v[88:89] op_sel_hi:[1,0]
	v_pk_mul_f32 v[34:35], v[54:55], v[86:87] op_sel_hi:[1,0]
	s_waitcnt vmcnt(3)
	v_lshlrev_b32_e32 v4, 16, v4
	s_waitcnt vmcnt(2)
	v_lshlrev_b32_e32 v5, 16, v5
	s_waitcnt vmcnt(0)
	v_lshlrev_b32_e32 v3, 16, v2
	v_lshlrev_b32_e32 v2, 16, v18
	v_mov_b32_e32 v18, v22
	v_pk_mul_f32 v[18:19], v[18:19], v[88:89] op_sel_hi:[1,0]
	v_pk_fma_f32 v[4:5], v[184:185], v[16:17], v[4:5] neg_lo:[1,0,0] neg_hi:[1,0,0]
	v_pk_fma_f32 v[18:19], v[184:185], v[18:19], v[2:3] neg_lo:[1,0,0] neg_hi:[1,0,0]
	global_load_ushort v2, v[36:37], off
	global_load_ushort v3, v[36:37], off offset:64
	global_load_ushort v6, v[36:37], off offset:128
	global_load_ushort v22, v[36:37], off offset:192
	v_pk_mul_f32 v[16:17], v[4:5], v[4:5]
	v_pk_mul_f32 v[32:33], v[18:19], v[18:19]
	s_waitcnt vmcnt(3)
	v_lshlrev_b32_e32 v2, 16, v2
	s_waitcnt vmcnt(2)
	v_lshlrev_b32_e32 v3, 16, v3
	s_waitcnt vmcnt(1)
	v_lshlrev_b32_e32 v36, 16, v6
	v_mov_b32_e32 v6, v23
	v_pk_fma_f32 v[2:3], v[184:185], v[34:35], v[2:3] neg_lo:[1,0,0] neg_hi:[1,0,0]
	s_waitcnt vmcnt(0)
	v_lshlrev_b32_e32 v37, 16, v22
	v_pk_mul_f32 v[6:7], v[6:7], v[86:87] op_sel_hi:[1,0]
	v_pk_mul_f32 v[34:35], v[2:3], v[2:3]
	v_pk_fma_f32 v[6:7], v[184:185], v[6:7], v[36:37] neg_lo:[1,0,0] neg_hi:[1,0,0]
	v_mov_b32_e32 v36, v34
	v_pk_mul_f32 v[22:23], v[6:7], v[6:7]
	v_mov_b32_e32 v37, v16
	v_mov_b32_e32 v16, v35
	v_pk_add_f32 v[16:17], v[36:37], v[16:17]
	v_mov_b32_e32 v34, v22
	v_mov_b32_e32 v35, v32
	v_pk_add_f32 v[16:17], v[16:17], v[34:35]
	v_mov_b32_e32 v32, v23
	v_pk_add_f32 v[16:17], v[16:17], v[32:33]
	ds_bpermute_b32 v23, v191, v17
	ds_bpermute_b32 v22, v191, v16
	s_waitcnt lgkmcnt(0)
	v_pk_add_f32 v[16:17], v[16:17], v[22:23]
	ds_bpermute_b32 v23, v192, v17
	ds_bpermute_b32 v22, v192, v16
	s_waitcnt lgkmcnt(0)
	v_pk_add_f32 v[16:17], v[16:17], v[22:23]
	ds_bpermute_b32 v23, v193, v17
	ds_bpermute_b32 v22, v193, v16
	s_waitcnt lgkmcnt(0)
	v_pk_add_f32 v[16:17], v[16:17], v[22:23]
	ds_bpermute_b32 v23, v194, v17
	ds_bpermute_b32 v22, v194, v16
	s_waitcnt lgkmcnt(0)
	v_pk_add_f32 v[16:17], v[16:17], v[22:23]
	ds_bpermute_b32 v23, v195, v17
	ds_bpermute_b32 v22, v195, v16
	s_waitcnt lgkmcnt(0)
	v_pk_add_f32 v[16:17], v[16:17], v[22:23]
	s_nop 0
	v_pk_fma_f32 v[16:17], v[16:17], s[6:7], v[0:1] op_sel_hi:[1,0,0]
	s_nop 0
	v_mul_f32_e32 v22, 0x4b800000, v17
	v_cmp_gt_f32_e64 s[0:1], s88, v17
	v_cmp_gt_f32_e32 vcc, s88, v16
	s_nop 0
	v_cndmask_b32_e64 v17, v17, v22, s[0:1]
	v_rsq_f32_e32 v17, v17
	s_nop 0
	v_mul_f32_e32 v22, 0x45800000, v17
	v_cndmask_b32_e64 v17, v17, v22, s[0:1]
	v_mul_f32_e32 v4, v4, v17
	v_mul_f32_e32 v4, v77, v4
	s_nop 0
	v_cvt_pk_bf16_f32 v4, v4, v4
	global_store_short v[20:21], v4, off
	v_mul_f32_e32 v4, v5, v17
	v_mul_f32_e32 v4, v75, v4
	v_cvt_pk_bf16_f32 v4, v4, v4
	global_store_short v[20:21], v4, off offset:64
	v_mul_f32_e32 v4, v18, v17
	v_mul_f32_e32 v4, v69, v4
	v_cvt_pk_bf16_f32 v4, v4, v4
	global_store_short v[20:21], v4, off offset:128
	v_mul_f32_e32 v4, v19, v17
	v_mul_f32_e32 v4, v67, v4
	s_nop 0
	v_cvt_pk_bf16_f32 v4, v4, v4
	global_store_short v[20:21], v4, off offset:192
	v_mul_f32_e32 v4, 0x4b800000, v16
	v_cndmask_b32_e32 v4, v16, v4, vcc
	v_rsq_f32_e32 v4, v4
	s_nop 0
	v_mul_f32_e32 v5, 0x45800000, v4
	v_cndmask_b32_e32 v16, v4, v5, vcc
	v_mul_f32_e32 v2, v2, v16
	v_mul_f32_e32 v2, v77, v2
	s_nop 0
	v_lshl_add_u64 v[4:5], v[64:65], 0, v[178:179]
	v_cvt_pk_bf16_f32 v2, v2, v2
	global_store_short v[4:5], v2, off
	v_mul_f32_e32 v2, v3, v16
	v_mul_f32_e32 v2, v75, v2
	v_cvt_pk_bf16_f32 v2, v2, v2
	global_store_short v[4:5], v2, off offset:64
	v_mul_f32_e32 v2, v6, v16
	v_mul_f32_e32 v2, v69, v2
	v_cvt_pk_bf16_f32 v2, v2, v2
	global_store_short v[4:5], v2, off offset:128
	v_mul_f32_e32 v2, v7, v16
	v_mul_f32_e32 v2, v67, v2
	v_cvt_pk_bf16_f32 v2, v2, v2
	v_or_b32_e32 v178, 0x10000, v70
	global_store_short v[4:5], v2, off offset:192
	v_lshl_add_u64 v[2:3], v[72:73], 0, v[178:179]
	global_load_ushort v4, v[2:3], off
	global_load_ushort v5, v[2:3], off offset:64
	global_load_ushort v16, v[2:3], off offset:128
	s_nop 0
	global_load_ushort v2, v[2:3], off offset:192
	v_mov_b32_e32 v17, v8
	v_lshl_add_u64 v[18:19], v[64:65], 0, v[178:179]
	v_or_b32_e32 v178, 0x11000, v70
	v_lshl_add_u64 v[32:33], v[72:73], 0, v[178:179]
	v_mov_b32_e32 v6, v40
	v_mov_b32_e32 v7, v56
	v_mov_b32_e32 v56, v41
	v_pk_mul_f32 v[6:7], v[6:7], v[84:85] op_sel_hi:[1,0]
	v_pk_mul_f32 v[22:23], v[56:57], v[82:83] op_sel_hi:[1,0]
	s_waitcnt vmcnt(3)
	v_lshlrev_b32_e32 v4, 16, v4
	s_waitcnt vmcnt(2)
	v_lshlrev_b32_e32 v5, 16, v5
	s_waitcnt vmcnt(0)
	v_lshlrev_b32_e32 v3, 16, v2
	v_lshlrev_b32_e32 v2, 16, v16
	v_mov_b32_e32 v16, v24
	v_pk_mul_f32 v[16:17], v[16:17], v[84:85] op_sel_hi:[1,0]
	v_pk_fma_f32 v[4:5], v[184:185], v[6:7], v[4:5] neg_lo:[1,0,0] neg_hi:[1,0,0]
	v_pk_fma_f32 v[16:17], v[184:185], v[16:17], v[2:3] neg_lo:[1,0,0] neg_hi:[1,0,0]
	global_load_ushort v2, v[32:33], off
	global_load_ushort v3, v[32:33], off offset:64
	global_load_ushort v8, v[32:33], off offset:128
	global_load_ushort v24, v[32:33], off offset:192
	v_pk_mul_f32 v[6:7], v[4:5], v[4:5]
	v_pk_mul_f32 v[20:21], v[16:17], v[16:17]
	s_waitcnt vmcnt(3)
	v_lshlrev_b32_e32 v2, 16, v2
	s_waitcnt vmcnt(2)
	v_lshlrev_b32_e32 v3, 16, v3
	s_waitcnt vmcnt(1)
	v_lshlrev_b32_e32 v32, 16, v8
	v_mov_b32_e32 v8, v25
	v_pk_fma_f32 v[2:3], v[184:185], v[22:23], v[2:3] neg_lo:[1,0,0] neg_hi:[1,0,0]
	s_waitcnt vmcnt(0)
	v_lshlrev_b32_e32 v33, 16, v24
	v_pk_mul_f32 v[8:9], v[8:9], v[82:83] op_sel_hi:[1,0]
	v_pk_mul_f32 v[22:23], v[2:3], v[2:3]
	v_pk_fma_f32 v[8:9], v[184:185], v[8:9], v[32:33] neg_lo:[1,0,0] neg_hi:[1,0,0]
	v_mov_b32_e32 v32, v22
	v_pk_mul_f32 v[24:25], v[8:9], v[8:9]
	v_mov_b32_e32 v33, v6
	v_mov_b32_e32 v6, v23
	v_pk_add_f32 v[6:7], v[32:33], v[6:7]
	v_mov_b32_e32 v22, v24
	v_mov_b32_e32 v23, v20
	v_pk_add_f32 v[6:7], v[6:7], v[22:23]
	v_mov_b32_e32 v20, v25
	v_pk_add_f32 v[6:7], v[6:7], v[20:21]
	ds_bpermute_b32 v21, v191, v7
	ds_bpermute_b32 v20, v191, v6
	s_waitcnt lgkmcnt(0)
	v_pk_add_f32 v[6:7], v[6:7], v[20:21]
	ds_bpermute_b32 v21, v192, v7
	ds_bpermute_b32 v20, v192, v6
	s_waitcnt lgkmcnt(0)
	v_pk_add_f32 v[6:7], v[6:7], v[20:21]
	ds_bpermute_b32 v21, v193, v7
	ds_bpermute_b32 v20, v193, v6
	s_waitcnt lgkmcnt(0)
	v_pk_add_f32 v[6:7], v[6:7], v[20:21]
	ds_bpermute_b32 v21, v194, v7
	ds_bpermute_b32 v20, v194, v6
	s_waitcnt lgkmcnt(0)
	v_pk_add_f32 v[6:7], v[6:7], v[20:21]
	ds_bpermute_b32 v21, v195, v7
	ds_bpermute_b32 v20, v195, v6
	s_waitcnt lgkmcnt(0)
	v_pk_add_f32 v[6:7], v[6:7], v[20:21]
	s_nop 0
	v_pk_fma_f32 v[6:7], v[6:7], s[6:7], v[0:1] op_sel_hi:[1,0,0]
	s_nop 0
	v_mul_f32_e32 v20, 0x4b800000, v7
	v_cmp_gt_f32_e64 s[0:1], s88, v7
	v_cmp_gt_f32_e32 vcc, s88, v6
	s_nop 0
	v_cndmask_b32_e64 v7, v7, v20, s[0:1]
	v_rsq_f32_e32 v7, v7
	s_nop 0
	v_mul_f32_e32 v20, 0x45800000, v7
	v_cndmask_b32_e64 v7, v7, v20, s[0:1]
	v_mul_f32_e32 v4, v4, v7
	v_mul_f32_e32 v4, v77, v4
	s_nop 0
	v_cvt_pk_bf16_f32 v4, v4, v4
	global_store_short v[18:19], v4, off
	v_mul_f32_e32 v4, v5, v7
	v_mul_f32_e32 v4, v75, v4
	v_cvt_pk_bf16_f32 v4, v4, v4
	global_store_short v[18:19], v4, off offset:64
	v_mul_f32_e32 v4, v16, v7
	v_mul_f32_e32 v4, v69, v4
	v_cvt_pk_bf16_f32 v4, v4, v4
	global_store_short v[18:19], v4, off offset:128
	v_mul_f32_e32 v4, v17, v7
	v_mul_f32_e32 v4, v67, v4
	s_nop 0
	v_cvt_pk_bf16_f32 v4, v4, v4
	global_store_short v[18:19], v4, off offset:192
	v_mul_f32_e32 v4, 0x4b800000, v6
	v_cndmask_b32_e32 v4, v6, v4, vcc
	v_rsq_f32_e32 v4, v4
	s_nop 0
	v_mul_f32_e32 v5, 0x45800000, v4
	v_cndmask_b32_e32 v6, v4, v5, vcc
	v_mul_f32_e32 v2, v2, v6
	v_mul_f32_e32 v2, v77, v2
	s_nop 0
	v_lshl_add_u64 v[4:5], v[64:65], 0, v[178:179]
	v_cvt_pk_bf16_f32 v2, v2, v2
	global_store_short v[4:5], v2, off
	v_mul_f32_e32 v2, v3, v6
	v_mul_f32_e32 v2, v75, v2
	v_cvt_pk_bf16_f32 v2, v2, v2
	global_store_short v[4:5], v2, off offset:64
	v_mul_f32_e32 v2, v8, v6
	v_mul_f32_e32 v2, v69, v2
	v_cvt_pk_bf16_f32 v2, v2, v2
	global_store_short v[4:5], v2, off offset:128
	v_mul_f32_e32 v2, v9, v6
	v_mul_f32_e32 v2, v67, v2
	v_cvt_pk_bf16_f32 v2, v2, v2
	v_or_b32_e32 v178, 0x12000, v70
	global_store_short v[4:5], v2, off offset:192
	v_lshl_add_u64 v[2:3], v[72:73], 0, v[178:179]
	global_load_ushort v4, v[2:3], off
	global_load_ushort v5, v[2:3], off offset:64
	global_load_ushort v8, v[2:3], off offset:128
	s_nop 0
	global_load_ushort v2, v[2:3], off offset:192
	v_mov_b32_e32 v9, v10
	v_lshl_add_u64 v[16:17], v[64:65], 0, v[178:179]
	v_or_b32_e32 v178, 0x13000, v70
	v_lshl_add_u64 v[22:23], v[72:73], 0, v[178:179]
	v_mov_b32_e32 v6, v42
	v_mov_b32_e32 v7, v58
	v_mov_b32_e32 v58, v43
	v_pk_mul_f32 v[6:7], v[6:7], v[80:81] op_sel_hi:[1,0]
	v_pk_mul_f32 v[20:21], v[58:59], v[78:79] op_sel_hi:[1,0]
	s_waitcnt vmcnt(3)
	v_lshlrev_b32_e32 v4, 16, v4
	s_waitcnt vmcnt(2)
	v_lshlrev_b32_e32 v5, 16, v5
	s_waitcnt vmcnt(0)
	v_lshlrev_b32_e32 v3, 16, v2
	v_lshlrev_b32_e32 v2, 16, v8
	v_mov_b32_e32 v8, v26
	v_pk_mul_f32 v[8:9], v[8:9], v[80:81] op_sel_hi:[1,0]
	v_pk_fma_f32 v[4:5], v[184:185], v[6:7], v[4:5] neg_lo:[1,0,0] neg_hi:[1,0,0]
	v_pk_fma_f32 v[8:9], v[184:185], v[8:9], v[2:3] neg_lo:[1,0,0] neg_hi:[1,0,0]
	global_load_ushort v2, v[22:23], off
	global_load_ushort v3, v[22:23], off offset:64
	global_load_ushort v10, v[22:23], off offset:128
	s_nop 0
	global_load_ushort v22, v[22:23], off offset:192
	v_pk_mul_f32 v[6:7], v[4:5], v[4:5]
	v_pk_mul_f32 v[18:19], v[8:9], v[8:9]
	v_mov_b32_e32 v25, v6
	s_waitcnt vmcnt(3)
	v_lshlrev_b32_e32 v2, 16, v2
	s_waitcnt vmcnt(2)
	v_lshlrev_b32_e32 v3, 16, v3
	s_waitcnt vmcnt(0)
	v_lshlrev_b32_e32 v23, 16, v22
	v_lshlrev_b32_e32 v22, 16, v10
	v_mov_b32_e32 v10, v27
	v_pk_fma_f32 v[2:3], v[184:185], v[20:21], v[2:3] neg_lo:[1,0,0] neg_hi:[1,0,0]
	v_pk_mul_f32 v[10:11], v[10:11], v[78:79] op_sel_hi:[1,0]
	v_pk_mul_f32 v[20:21], v[2:3], v[2:3]
	v_pk_fma_f32 v[10:11], v[184:185], v[10:11], v[22:23] neg_lo:[1,0,0] neg_hi:[1,0,0]
	v_mov_b32_e32 v24, v20
	v_pk_mul_f32 v[22:23], v[10:11], v[10:11]
	v_mov_b32_e32 v6, v21
	v_pk_add_f32 v[6:7], v[24:25], v[6:7]
	v_mov_b32_e32 v20, v22
	v_mov_b32_e32 v21, v18
	v_pk_add_f32 v[6:7], v[6:7], v[20:21]
	v_mov_b32_e32 v18, v23
	v_pk_add_f32 v[6:7], v[6:7], v[18:19]
	ds_bpermute_b32 v19, v191, v7
	ds_bpermute_b32 v18, v191, v6
	s_waitcnt lgkmcnt(0)
	v_pk_add_f32 v[6:7], v[6:7], v[18:19]
	ds_bpermute_b32 v19, v192, v7
	ds_bpermute_b32 v18, v192, v6
	s_waitcnt lgkmcnt(0)
	v_pk_add_f32 v[6:7], v[6:7], v[18:19]
	ds_bpermute_b32 v19, v193, v7
	ds_bpermute_b32 v18, v193, v6
	s_waitcnt lgkmcnt(0)
	v_pk_add_f32 v[6:7], v[6:7], v[18:19]
	ds_bpermute_b32 v19, v194, v7
	ds_bpermute_b32 v18, v194, v6
	s_waitcnt lgkmcnt(0)
	v_pk_add_f32 v[6:7], v[6:7], v[18:19]
	ds_bpermute_b32 v19, v195, v7
	ds_bpermute_b32 v18, v195, v6
	s_waitcnt lgkmcnt(0)
	v_pk_add_f32 v[6:7], v[6:7], v[18:19]
	s_nop 0
	v_pk_fma_f32 v[6:7], v[6:7], s[6:7], v[0:1] op_sel_hi:[1,0,0]
	s_nop 0
	v_mul_f32_e32 v18, 0x4b800000, v7
	v_cmp_gt_f32_e64 s[0:1], s88, v7
	v_cmp_gt_f32_e32 vcc, s88, v6
	s_nop 0
	v_cndmask_b32_e64 v7, v7, v18, s[0:1]
	v_rsq_f32_e32 v7, v7
	s_nop 0
	v_mul_f32_e32 v18, 0x45800000, v7
	v_cndmask_b32_e64 v7, v7, v18, s[0:1]
	v_mul_f32_e32 v4, v4, v7
	v_mul_f32_e32 v4, v77, v4
	s_nop 0
	v_cvt_pk_bf16_f32 v4, v4, v4
	global_store_short v[16:17], v4, off
	v_mul_f32_e32 v4, v5, v7
	v_mul_f32_e32 v4, v75, v4
	v_cvt_pk_bf16_f32 v4, v4, v4
	global_store_short v[16:17], v4, off offset:64
	v_mul_f32_e32 v4, v8, v7
	v_mul_f32_e32 v4, v69, v4
	v_cvt_pk_bf16_f32 v4, v4, v4
	global_store_short v[16:17], v4, off offset:128
	v_mul_f32_e32 v4, v9, v7
	v_mul_f32_e32 v4, v67, v4
	s_nop 0
	v_cvt_pk_bf16_f32 v4, v4, v4
	global_store_short v[16:17], v4, off offset:192
	v_mul_f32_e32 v4, 0x4b800000, v6
	v_cndmask_b32_e32 v4, v6, v4, vcc
	v_rsq_f32_e32 v4, v4
	v_mov_b32_e32 v9, v12
	v_mul_f32_e32 v5, 0x45800000, v4
	v_cndmask_b32_e32 v6, v4, v5, vcc
	v_mul_f32_e32 v2, v2, v6
	v_mul_f32_e32 v2, v77, v2
	s_nop 0
	v_lshl_add_u64 v[4:5], v[64:65], 0, v[178:179]
	v_cvt_pk_bf16_f32 v2, v2, v2
	global_store_short v[4:5], v2, off
	v_mul_f32_e32 v2, v3, v6
	v_mul_f32_e32 v2, v75, v2
	v_cvt_pk_bf16_f32 v2, v2, v2
	global_store_short v[4:5], v2, off offset:64
	v_mul_f32_e32 v2, v10, v6
	v_mul_f32_e32 v2, v69, v2
	v_cvt_pk_bf16_f32 v2, v2, v2
	global_store_short v[4:5], v2, off offset:128
	v_mul_f32_e32 v2, v11, v6
	v_mul_f32_e32 v2, v67, v2
	v_cvt_pk_bf16_f32 v2, v2, v2
	v_or_b32_e32 v178, 0x18000, v70
	global_store_short v[4:5], v2, off offset:192
	v_lshl_add_u64 v[2:3], v[72:73], 0, v[178:179]
	global_load_ushort v4, v[2:3], off
	global_load_ushort v5, v[2:3], off offset:64
	global_load_ushort v8, v[2:3], off offset:128
	s_nop 0
	global_load_ushort v2, v[2:3], off offset:192
	v_lshl_add_u64 v[10:11], v[64:65], 0, v[178:179]
	v_or_b32_e32 v178, 0x19000, v70
	v_lshl_add_u64 v[20:21], v[72:73], 0, v[178:179]
	v_mov_b32_e32 v6, v44
	v_mov_b32_e32 v7, v60
	v_mov_b32_e32 v60, v45
	v_pk_mul_f32 v[6:7], v[6:7], v[76:77] op_sel_hi:[1,0]
	v_pk_mul_f32 v[18:19], v[60:61], v[74:75] op_sel_hi:[1,0]
	s_waitcnt vmcnt(3)
	v_lshlrev_b32_e32 v4, 16, v4
	s_waitcnt vmcnt(2)
	v_lshlrev_b32_e32 v5, 16, v5
	s_waitcnt vmcnt(0)
	v_lshlrev_b32_e32 v3, 16, v2
	v_lshlrev_b32_e32 v2, 16, v8
	v_mov_b32_e32 v8, v28
	v_pk_mul_f32 v[8:9], v[8:9], v[76:77] op_sel_hi:[1,0]
	v_pk_fma_f32 v[4:5], v[184:185], v[6:7], v[4:5] neg_lo:[1,0,0] neg_hi:[1,0,0]
	v_pk_fma_f32 v[8:9], v[184:185], v[8:9], v[2:3] neg_lo:[1,0,0] neg_hi:[1,0,0]
	global_load_ushort v2, v[20:21], off
	global_load_ushort v3, v[20:21], off offset:64
	global_load_ushort v12, v[20:21], off offset:128
	s_nop 0
	global_load_ushort v20, v[20:21], off offset:192
	v_pk_mul_f32 v[6:7], v[4:5], v[4:5]
	v_pk_mul_f32 v[16:17], v[8:9], v[8:9]
	v_mov_b32_e32 v23, v6
	s_waitcnt vmcnt(3)
	v_lshlrev_b32_e32 v2, 16, v2
	s_waitcnt vmcnt(2)
	v_lshlrev_b32_e32 v3, 16, v3
	s_waitcnt vmcnt(0)
	v_lshlrev_b32_e32 v21, 16, v20
	v_lshlrev_b32_e32 v20, 16, v12
	v_mov_b32_e32 v12, v29
	v_pk_fma_f32 v[2:3], v[184:185], v[18:19], v[2:3] neg_lo:[1,0,0] neg_hi:[1,0,0]
	v_pk_mul_f32 v[12:13], v[12:13], v[74:75] op_sel_hi:[1,0]
	v_pk_mul_f32 v[18:19], v[2:3], v[2:3]
	v_pk_fma_f32 v[12:13], v[184:185], v[12:13], v[20:21] neg_lo:[1,0,0] neg_hi:[1,0,0]
	v_mov_b32_e32 v22, v18
	v_pk_mul_f32 v[20:21], v[12:13], v[12:13]
	v_mov_b32_e32 v6, v19
	v_pk_add_f32 v[6:7], v[22:23], v[6:7]
	v_mov_b32_e32 v18, v20
	v_mov_b32_e32 v19, v16
	v_pk_add_f32 v[6:7], v[6:7], v[18:19]
	v_mov_b32_e32 v16, v21
	v_pk_add_f32 v[6:7], v[6:7], v[16:17]
	ds_bpermute_b32 v17, v191, v7
	ds_bpermute_b32 v16, v191, v6
	s_waitcnt lgkmcnt(0)
	v_pk_add_f32 v[6:7], v[6:7], v[16:17]
	ds_bpermute_b32 v17, v192, v7
	ds_bpermute_b32 v16, v192, v6
	s_waitcnt lgkmcnt(0)
	v_pk_add_f32 v[6:7], v[6:7], v[16:17]
	ds_bpermute_b32 v17, v193, v7
	ds_bpermute_b32 v16, v193, v6
	s_waitcnt lgkmcnt(0)
	v_pk_add_f32 v[6:7], v[6:7], v[16:17]
	ds_bpermute_b32 v17, v194, v7
	ds_bpermute_b32 v16, v194, v6
	s_waitcnt lgkmcnt(0)
	v_pk_add_f32 v[6:7], v[6:7], v[16:17]
	ds_bpermute_b32 v17, v195, v7
	ds_bpermute_b32 v16, v195, v6
	s_waitcnt lgkmcnt(0)
	v_pk_add_f32 v[6:7], v[6:7], v[16:17]
	s_nop 0
	v_pk_fma_f32 v[6:7], v[6:7], s[6:7], v[0:1] op_sel_hi:[1,0,0]
	s_nop 0
	v_mul_f32_e32 v16, 0x4b800000, v7
	v_cmp_gt_f32_e64 s[0:1], s88, v7
	v_cmp_gt_f32_e32 vcc, s88, v6
	s_nop 0
	v_cndmask_b32_e64 v7, v7, v16, s[0:1]
	v_rsq_f32_e32 v7, v7
	s_nop 0
	v_mul_f32_e32 v16, 0x45800000, v7
	v_cndmask_b32_e64 v7, v7, v16, s[0:1]
	v_mul_f32_e32 v4, v4, v7
	v_mul_f32_e32 v4, v77, v4
	s_nop 0
	v_cvt_pk_bf16_f32 v4, v4, v4
	global_store_short v[10:11], v4, off
	v_mul_f32_e32 v4, v5, v7
	v_mul_f32_e32 v4, v75, v4
	v_cvt_pk_bf16_f32 v4, v4, v4
	global_store_short v[10:11], v4, off offset:64
	v_mul_f32_e32 v4, v8, v7
	v_mul_f32_e32 v4, v69, v4
	v_cvt_pk_bf16_f32 v4, v4, v4
	global_store_short v[10:11], v4, off offset:128
	v_mul_f32_e32 v4, v9, v7
	v_mul_f32_e32 v4, v67, v4
	s_nop 0
	v_cvt_pk_bf16_f32 v4, v4, v4
	global_store_short v[10:11], v4, off offset:192
	v_mul_f32_e32 v4, 0x4b800000, v6
	v_cndmask_b32_e32 v4, v6, v4, vcc
	v_rsq_f32_e32 v4, v4
	s_nop 0
	v_mul_f32_e32 v5, 0x45800000, v4
	v_cndmask_b32_e32 v6, v4, v5, vcc
	v_mul_f32_e32 v2, v2, v6
	v_mul_f32_e32 v2, v77, v2
	s_nop 0
	v_lshl_add_u64 v[4:5], v[64:65], 0, v[178:179]
	v_cvt_pk_bf16_f32 v2, v2, v2
	global_store_short v[4:5], v2, off
	v_mul_f32_e32 v2, v3, v6
	v_mul_f32_e32 v2, v75, v2
	v_cvt_pk_bf16_f32 v2, v2, v2
	global_store_short v[4:5], v2, off offset:64
	v_mul_f32_e32 v2, v12, v6
	v_mul_f32_e32 v2, v69, v2
	v_cvt_pk_bf16_f32 v2, v2, v2
	global_store_short v[4:5], v2, off offset:128
	v_mul_f32_e32 v2, v13, v6
	v_mul_f32_e32 v2, v67, v2
	v_cvt_pk_bf16_f32 v2, v2, v2
	v_or_b32_e32 v178, 0x1a000, v70
	global_store_short v[4:5], v2, off offset:192
	v_lshl_add_u64 v[4:5], v[72:73], 0, v[178:179]
	global_load_ushort v2, v[4:5], off
	global_load_ushort v3, v[4:5], off offset:64
	v_mov_b32_e32 v6, v46
	v_mov_b32_e32 v7, v62
	v_pk_mul_f32 v[6:7], v[6:7], v[68:69] op_sel_hi:[1,0]
	v_lshl_add_u64 v[8:9], v[64:65], 0, v[178:179]
	v_or_b32_e32 v178, 0x1b000, v70
	v_lshl_add_u64 v[18:19], v[72:73], 0, v[178:179]
	v_mov_b32_e32 v62, v47
	v_pk_mul_f32 v[16:17], v[62:63], v[66:67] op_sel_hi:[1,0]
	s_waitcnt vmcnt(1)
	v_lshlrev_b32_e32 v2, 16, v2
	s_waitcnt vmcnt(0)
	v_lshlrev_b32_e32 v3, 16, v3
	v_pk_fma_f32 v[2:3], v[184:185], v[6:7], v[2:3] neg_lo:[1,0,0] neg_hi:[1,0,0]
	global_load_ushort v6, v[4:5], off offset:128
	s_nop 0
	global_load_ushort v4, v[4:5], off offset:192
	v_mov_b32_e32 v7, v14
	v_pk_mul_f32 v[10:11], v[2:3], v[2:3]
	s_waitcnt vmcnt(0)
	v_lshlrev_b32_e32 v5, 16, v4
	v_lshlrev_b32_e32 v4, 16, v6
	v_mov_b32_e32 v6, v30
	v_pk_mul_f32 v[6:7], v[6:7], v[68:69] op_sel_hi:[1,0]
	v_mov_b32_e32 v21, v10
	v_pk_fma_f32 v[4:5], v[184:185], v[6:7], v[4:5] neg_lo:[1,0,0] neg_hi:[1,0,0]
	global_load_ushort v6, v[18:19], off
	global_load_ushort v7, v[18:19], off offset:64
	global_load_ushort v14, v[18:19], off offset:128
	s_nop 0
	global_load_ushort v18, v[18:19], off offset:192
	v_pk_mul_f32 v[12:13], v[4:5], v[4:5]
	s_waitcnt vmcnt(3)
	v_lshlrev_b32_e32 v6, 16, v6
	s_waitcnt vmcnt(2)
	v_lshlrev_b32_e32 v7, 16, v7
	s_waitcnt vmcnt(0)
	v_lshlrev_b32_e32 v19, 16, v18
	v_lshlrev_b32_e32 v18, 16, v14
	v_mov_b32_e32 v14, v31
	v_pk_fma_f32 v[6:7], v[184:185], v[16:17], v[6:7] neg_lo:[1,0,0] neg_hi:[1,0,0]
	v_pk_mul_f32 v[14:15], v[14:15], v[66:67] op_sel_hi:[1,0]
	v_pk_mul_f32 v[16:17], v[6:7], v[6:7]
	v_pk_fma_f32 v[14:15], v[184:185], v[14:15], v[18:19] neg_lo:[1,0,0] neg_hi:[1,0,0]
	v_mov_b32_e32 v20, v16
	v_pk_mul_f32 v[18:19], v[14:15], v[14:15]
	v_mov_b32_e32 v10, v17
	v_pk_add_f32 v[10:11], v[20:21], v[10:11]
	v_mov_b32_e32 v16, v18
	v_mov_b32_e32 v17, v12
	v_pk_add_f32 v[10:11], v[10:11], v[16:17]
	v_mov_b32_e32 v12, v19
	v_pk_add_f32 v[10:11], v[10:11], v[12:13]
	ds_bpermute_b32 v13, v191, v11
	ds_bpermute_b32 v12, v191, v10
	s_waitcnt lgkmcnt(0)
	v_pk_add_f32 v[10:11], v[10:11], v[12:13]
	ds_bpermute_b32 v13, v192, v11
	ds_bpermute_b32 v12, v192, v10
	s_waitcnt lgkmcnt(0)
	v_pk_add_f32 v[10:11], v[10:11], v[12:13]
	ds_bpermute_b32 v13, v193, v11
	ds_bpermute_b32 v12, v193, v10
	s_waitcnt lgkmcnt(0)
	v_pk_add_f32 v[10:11], v[10:11], v[12:13]
	ds_bpermute_b32 v13, v194, v11
	ds_bpermute_b32 v12, v194, v10
	s_waitcnt lgkmcnt(0)
	v_pk_add_f32 v[10:11], v[10:11], v[12:13]
	ds_bpermute_b32 v13, v195, v11
	ds_bpermute_b32 v12, v195, v10
	s_waitcnt lgkmcnt(0)
	v_pk_add_f32 v[10:11], v[10:11], v[12:13]
	s_nop 0
	v_pk_fma_f32 v[0:1], v[10:11], s[6:7], v[0:1] op_sel_hi:[1,0,0]
	s_nop 0
	v_mul_f32_e32 v10, 0x4b800000, v1
	v_cmp_gt_f32_e64 s[0:1], s88, v1
	v_cmp_gt_f32_e32 vcc, s88, v0
	s_nop 0
	v_cndmask_b32_e64 v1, v1, v10, s[0:1]
	v_rsq_f32_e32 v1, v1
	s_nop 0
	v_mul_f32_e32 v10, 0x45800000, v1
	v_cndmask_b32_e64 v1, v1, v10, s[0:1]
	v_mul_f32_e32 v2, v2, v1
	v_mul_f32_e32 v2, v77, v2
	s_nop 0
	v_cvt_pk_bf16_f32 v2, v2, v2
	global_store_short v[8:9], v2, off
	v_mul_f32_e32 v2, v3, v1
	v_mul_f32_e32 v2, v75, v2
	v_cvt_pk_bf16_f32 v2, v2, v2
	global_store_short v[8:9], v2, off offset:64
	v_mul_f32_e32 v2, v4, v1
	v_mul_f32_e32 v2, v69, v2
	v_mul_f32_e32 v1, v5, v1
	v_cvt_pk_bf16_f32 v2, v2, v2
	v_mul_f32_e32 v1, v67, v1
	global_store_short v[8:9], v2, off offset:128
	s_nop 0
	v_cvt_pk_bf16_f32 v1, v1, v1
	global_store_short v[8:9], v1, off offset:192
	v_mul_f32_e32 v1, 0x4b800000, v0
	v_cndmask_b32_e32 v0, v0, v1, vcc
	v_rsq_f32_e32 v0, v0
	s_nop 0
	v_mul_f32_e32 v1, 0x45800000, v0
	v_cndmask_b32_e32 v2, v0, v1, vcc
	v_mul_f32_e32 v3, v6, v2
	v_mul_f32_e32 v3, v77, v3
	s_nop 0
	v_lshl_add_u64 v[0:1], v[64:65], 0, v[178:179]
	v_cvt_pk_bf16_f32 v3, v3, v3
	global_store_short v[0:1], v3, off
	v_mul_f32_e32 v3, v7, v2
	v_mul_f32_e32 v3, v75, v3
	v_cvt_pk_bf16_f32 v3, v3, v3
	global_store_short v[0:1], v3, off offset:64
	v_mul_f32_e32 v3, v14, v2
	v_mul_f32_e32 v3, v69, v3
	v_mul_f32_e32 v2, v15, v2
	v_cvt_pk_bf16_f32 v3, v3, v3
	v_mul_f32_e32 v2, v67, v2
	global_store_short v[0:1], v3, off offset:128
	v_bfe_u32 v3, v2, 16, 1
	v_add3_u32 v2, v2, v3, s65
	global_store_short_d16_hi v[0:1], v2, off offset:192

.LBB0_650:
	s_or_b64 exec, exec, s[0:1]
	s_waitcnt lgkmcnt(0)
	v_add_u32_e32 v72, v187, v178
	ds_read_b128 v[64:67], v72
	ds_read_b128 v[68:71], v72 offset:32
	s_lshl_b64 s[0:1], s[22:23], 12
	s_add_u32 s0, s46, s0
	s_addc_u32 s1, s47, s1
	s_waitcnt lgkmcnt(1)
	v_rcp_f32_e32 v73, v64
	v_rcp_f32_e32 v74, v65
	v_rcp_f32_e32 v75, v66
	v_rcp_f32_e32 v76, v67
	ds_read_b128 v[64:67], v72 offset:64
	s_lshl_b32 s7, s34, 1
	s_add_u32 s0, s0, s7
	v_ashrrev_i32_e32 v187, 31, v186
	s_addc_u32 s1, s1, 0
	s_waitcnt lgkmcnt(1)
	v_rcp_f32_e32 v77, v68
	v_rcp_f32_e32 v78, v69
	v_rcp_f32_e32 v79, v70
	v_rcp_f32_e32 v80, v71
	ds_read_b128 v[68:71], v72 offset:96
	s_waitcnt lgkmcnt(1)
	v_rcp_f32_e32 v72, v64
	v_rcp_f32_e32 v81, v65
	v_lshlrev_b64 v[64:65], 12, v[186:187]
	v_lshl_add_u64 v[64:65], s[0:1], 0, v[64:65]
	v_lshlrev_b32_e32 v178, 1, v199
	v_rcp_f32_e32 v82, v66
	v_rcp_f32_e32 v83, v67
	v_lshlrev_b32_e32 v66, 14, v198
	v_lshl_add_u64 v[64:65], v[64:65], 0, v[178:179]
	v_mov_b32_e32 v67, v179
	v_mul_f32_e32 v0, v0, v73
	v_lshl_add_u64 v[64:65], v[64:65], 0, v[66:67]
	s_nop 0
	v_cvt_pk_bf16_f32 v0, v0, v0
	global_store_short v[64:65], v0, off
	v_mul_f32_e32 v0, v48, v73
	v_cvt_pk_bf16_f32 v0, v0, v0
	global_store_short v[64:65], v0, off offset:64
	v_mul_f32_e32 v0, v32, v73
	v_cvt_pk_bf16_f32 v0, v0, v0
	global_store_short v[64:65], v0, off offset:128
	v_mul_f32_e32 v0, v16, v73
	v_cvt_pk_bf16_f32 v0, v0, v0
	global_store_short v[64:65], v0, off offset:192
	v_mul_f32_e32 v0, v1, v74
	s_nop 0
	s_movk_i32 s0, 0x1000
	v_cvt_pk_bf16_f32 v16, v0, v0
	v_add_co_u32_e32 v0, vcc, s0, v64
	s_movk_i32 s0, 0x3000
	s_nop 0
	v_addc_co_u32_e32 v1, vcc, 0, v65, vcc
	v_add_co_u32_e32 v66, vcc, s89, v64
	s_waitcnt lgkmcnt(0)
	v_rcp_f32_e32 v68, v68
	v_addc_co_u32_e32 v67, vcc, 0, v65, vcc
	global_store_short v[66:67], v16, off offset:-4096
	v_mul_f32_e32 v16, v49, v74
	s_nop 0
	v_cvt_pk_bf16_f32 v16, v16, v16
	global_store_short v[0:1], v16, off offset:64
	v_mul_f32_e32 v16, v33, v74
	v_cvt_pk_bf16_f32 v16, v16, v16
	global_store_short v[0:1], v16, off offset:128
	v_mul_f32_e32 v16, v17, v74
	v_cvt_pk_bf16_f32 v16, v16, v16
	global_store_short v[0:1], v16, off offset:192
	v_mul_f32_e32 v0, v2, v75
	v_cvt_pk_bf16_f32 v0, v0, v0
	global_store_short v[66:67], v0, off
	v_mul_f32_e32 v0, v50, v75
	v_cvt_pk_bf16_f32 v0, v0, v0
	global_store_short v[66:67], v0, off offset:64
	v_mul_f32_e32 v0, v34, v75
	v_cvt_pk_bf16_f32 v0, v0, v0
	global_store_short v[66:67], v0, off offset:128
	v_mul_f32_e32 v0, v18, v75
	v_cvt_pk_bf16_f32 v0, v0, v0
	global_store_short v[66:67], v0, off offset:192
	v_mul_f32_e32 v0, v3, v76
	s_nop 0
	v_cvt_pk_bf16_f32 v2, v0, v0
	v_add_co_u32_e32 v0, vcc, s0, v64
	s_mov_b32 s0, 0x8000
	s_nop 0
	v_addc_co_u32_e32 v1, vcc, 0, v65, vcc
	global_store_short v[0:1], v2, off
	v_mul_f32_e32 v2, v51, v76
	s_nop 0
	v_cvt_pk_bf16_f32 v2, v2, v2
	global_store_short v[0:1], v2, off offset:64
	v_mul_f32_e32 v2, v35, v76
	v_cvt_pk_bf16_f32 v2, v2, v2
	global_store_short v[0:1], v2, off offset:128
	v_mul_f32_e32 v2, v19, v76
	v_cvt_pk_bf16_f32 v2, v2, v2
	global_store_short v[0:1], v2, off offset:192
	v_mul_f32_e32 v0, v4, v77
	s_nop 0
	v_cvt_pk_bf16_f32 v4, v0, v0
	v_add_co_u32_e32 v0, vcc, s0, v64
	s_mov_b32 s0, 0x9000
	s_nop 0
	v_addc_co_u32_e32 v1, vcc, 0, v65, vcc
	v_add_co_u32_e32 v2, vcc, s0, v64
	s_mov_b32 s0, 0xa000
	s_nop 0
	v_addc_co_u32_e32 v3, vcc, 0, v65, vcc
	global_store_short v[2:3], v4, off offset:-4096
	v_mul_f32_e32 v4, v52, v77
	s_nop 0
	v_cvt_pk_bf16_f32 v4, v4, v4
	global_store_short v[0:1], v4, off offset:64
	v_mul_f32_e32 v4, v36, v77
	v_cvt_pk_bf16_f32 v4, v4, v4
	global_store_short v[0:1], v4, off offset:128
	v_mul_f32_e32 v4, v20, v77
	v_cvt_pk_bf16_f32 v4, v4, v4
	global_store_short v[0:1], v4, off offset:192
	v_mul_f32_e32 v0, v5, v78
	v_cvt_pk_bf16_f32 v0, v0, v0
	global_store_short v[2:3], v0, off
	v_mul_f32_e32 v0, v53, v78
	v_cvt_pk_bf16_f32 v0, v0, v0
	global_store_short v[2:3], v0, off offset:64
	v_mul_f32_e32 v0, v37, v78
	v_cvt_pk_bf16_f32 v0, v0, v0
	global_store_short v[2:3], v0, off offset:128
	v_mul_f32_e32 v0, v21, v78
	v_cvt_pk_bf16_f32 v0, v0, v0
	global_store_short v[2:3], v0, off offset:192
	v_mul_f32_e32 v0, v6, v79
	s_nop 0
	v_cvt_pk_bf16_f32 v4, v0, v0
	v_add_co_u32_e32 v0, vcc, s0, v64
	s_mov_b32 s0, 0xb000
	s_nop 0
	v_addc_co_u32_e32 v1, vcc, 0, v65, vcc
	v_add_co_u32_e32 v2, vcc, s0, v64
	s_mov_b32 s0, 0x11000
	s_nop 0
	v_addc_co_u32_e32 v3, vcc, 0, v65, vcc
	global_store_short v[2:3], v4, off offset:-4096
	v_mul_f32_e32 v4, v54, v79
	s_nop 0
	v_cvt_pk_bf16_f32 v4, v4, v4
	global_store_short v[0:1], v4, off offset:64
	v_mul_f32_e32 v4, v38, v79
	v_cvt_pk_bf16_f32 v4, v4, v4
	global_store_short v[0:1], v4, off offset:128
	v_mul_f32_e32 v4, v22, v79
	v_cvt_pk_bf16_f32 v4, v4, v4
	global_store_short v[0:1], v4, off offset:192
	v_mul_f32_e32 v0, v7, v80
	v_cvt_pk_bf16_f32 v0, v0, v0
	global_store_short v[2:3], v0, off
	v_mul_f32_e32 v0, v55, v80
	v_cvt_pk_bf16_f32 v0, v0, v0
	global_store_short v[2:3], v0, off offset:64
	v_mul_f32_e32 v0, v39, v80
	v_cvt_pk_bf16_f32 v0, v0, v0
	global_store_short v[2:3], v0, off offset:128
	v_mul_f32_e32 v0, v23, v80
	v_cvt_pk_bf16_f32 v0, v0, v0
	global_store_short v[2:3], v0, off offset:192
	v_mul_f32_e32 v0, v8, v72
	s_nop 0
	v_cvt_pk_bf16_f32 v4, v0, v0
	v_add_co_u32_e32 v0, vcc, s93, v64
	v_rcp_f32_e32 v69, v69
	s_nop 0
	v_addc_co_u32_e32 v1, vcc, 0, v65, vcc
	v_add_co_u32_e32 v2, vcc, s0, v64
	s_mov_b32 s0, 0x12000
	s_nop 0
	v_addc_co_u32_e32 v3, vcc, 0, v65, vcc
	global_store_short v[2:3], v4, off offset:-4096
	v_mul_f32_e32 v4, v56, v72
	s_nop 0
	v_cvt_pk_bf16_f32 v4, v4, v4
	global_store_short v[0:1], v4, off offset:64
	v_mul_f32_e32 v4, v40, v72
	v_cvt_pk_bf16_f32 v4, v4, v4
	global_store_short v[0:1], v4, off offset:128
	v_mul_f32_e32 v4, v24, v72
	v_cvt_pk_bf16_f32 v4, v4, v4
	global_store_short v[0:1], v4, off offset:192
	v_mul_f32_e32 v0, v9, v81
	v_cvt_pk_bf16_f32 v0, v0, v0
	global_store_short v[2:3], v0, off
	v_mul_f32_e32 v0, v57, v81
	v_cvt_pk_bf16_f32 v0, v0, v0
	global_store_short v[2:3], v0, off offset:64
	v_mul_f32_e32 v0, v41, v81
	v_cvt_pk_bf16_f32 v0, v0, v0
	global_store_short v[2:3], v0, off offset:128
	v_mul_f32_e32 v0, v25, v81
	v_cvt_pk_bf16_f32 v0, v0, v0
	global_store_short v[2:3], v0, off offset:192
	v_mul_f32_e32 v0, v10, v82
	s_nop 0
	v_cvt_pk_bf16_f32 v4, v0, v0
	v_add_co_u32_e32 v0, vcc, s0, v64
	s_mov_b32 s0, 0x13000
	s_nop 0
	v_addc_co_u32_e32 v1, vcc, 0, v65, vcc
	v_add_co_u32_e32 v2, vcc, s0, v64
	s_mov_b32 s0, 0x19000
	s_nop 0
	v_addc_co_u32_e32 v3, vcc, 0, v65, vcc
	global_store_short v[2:3], v4, off offset:-4096
	v_mul_f32_e32 v4, v58, v82
	s_nop 0
	v_cvt_pk_bf16_f32 v4, v4, v4
	global_store_short v[0:1], v4, off offset:64
	v_mul_f32_e32 v4, v42, v82
	v_cvt_pk_bf16_f32 v4, v4, v4
	global_store_short v[0:1], v4, off offset:128
	v_mul_f32_e32 v4, v26, v82
	v_cvt_pk_bf16_f32 v4, v4, v4
	global_store_short v[0:1], v4, off offset:192
	v_mul_f32_e32 v0, v11, v83
	v_cvt_pk_bf16_f32 v0, v0, v0
	global_store_short v[2:3], v0, off
	v_mul_f32_e32 v0, v59, v83
	v_cvt_pk_bf16_f32 v0, v0, v0
	global_store_short v[2:3], v0, off offset:64
	v_mul_f32_e32 v0, v43, v83
	v_cvt_pk_bf16_f32 v0, v0, v0
	global_store_short v[2:3], v0, off offset:128
	v_mul_f32_e32 v0, v27, v83
	v_cvt_pk_bf16_f32 v0, v0, v0
	global_store_short v[2:3], v0, off offset:192
	v_mul_f32_e32 v0, v12, v68
	s_nop 0
	v_cvt_pk_bf16_f32 v4, v0, v0
	v_add_co_u32_e32 v0, vcc, s92, v64
	v_rcp_f32_e32 v70, v70
	s_nop 0
	v_addc_co_u32_e32 v1, vcc, 0, v65, vcc
	v_add_co_u32_e32 v2, vcc, s0, v64
	s_mov_b32 s0, 0x1a000
	s_nop 0
	v_addc_co_u32_e32 v3, vcc, 0, v65, vcc
	global_store_short v[2:3], v4, off offset:-4096
	v_mul_f32_e32 v4, v60, v68
	s_nop 0
	v_cvt_pk_bf16_f32 v4, v4, v4
	global_store_short v[0:1], v4, off offset:64
	v_mul_f32_e32 v4, v44, v68
	v_cvt_pk_bf16_f32 v4, v4, v4
	global_store_short v[0:1], v4, off offset:128
	v_mul_f32_e32 v4, v28, v68
	v_cvt_pk_bf16_f32 v4, v4, v4
	global_store_short v[0:1], v4, off offset:192
	v_mul_f32_e32 v0, v13, v69
	v_cvt_pk_bf16_f32 v0, v0, v0
	global_store_short v[2:3], v0, off
	v_mul_f32_e32 v0, v61, v69
	v_cvt_pk_bf16_f32 v0, v0, v0
	global_store_short v[2:3], v0, off offset:64
	v_mul_f32_e32 v0, v45, v69
	v_cvt_pk_bf16_f32 v0, v0, v0
	global_store_short v[2:3], v0, off offset:128
	v_mul_f32_e32 v0, v29, v69
	v_cvt_pk_bf16_f32 v0, v0, v0
	global_store_short v[2:3], v0, off offset:192
	v_mul_f32_e32 v0, v14, v70
	s_nop 0
	v_cvt_pk_bf16_f32 v4, v0, v0
	v_add_co_u32_e32 v0, vcc, s0, v64
	s_mov_b32 s0, 0x1b000
	s_nop 0
	v_addc_co_u32_e32 v1, vcc, 0, v65, vcc
	v_add_co_u32_e32 v2, vcc, s0, v64
	v_rcp_f32_e32 v71, v71
	s_nop 0
	v_addc_co_u32_e32 v3, vcc, 0, v65, vcc
	global_store_short v[2:3], v4, off offset:-4096
	v_mul_f32_e32 v4, v62, v70
	s_nop 0
	v_cvt_pk_bf16_f32 v4, v4, v4
	global_store_short v[0:1], v4, off offset:64
	v_mul_f32_e32 v4, v46, v70
	v_cvt_pk_bf16_f32 v4, v4, v4
	global_store_short v[0:1], v4, off offset:128
	v_mul_f32_e32 v4, v30, v70
	v_bfe_u32 v5, v4, 16, 1
	v_add3_u32 v4, v4, v5, s65
	global_store_short_d16_hi v[0:1], v4, off offset:192
	v_mul_f32_e32 v0, v15, v71
	v_cvt_pk_bf16_f32 v0, v0, v0
	global_store_short v[2:3], v0, off
	v_mul_f32_e32 v0, v63, v71
	v_cvt_pk_bf16_f32 v0, v0, v0
	global_store_short v[2:3], v0, off offset:64
	v_mul_f32_e32 v0, v47, v71
	v_cvt_pk_bf16_f32 v0, v0, v0
	global_store_short v[2:3], v0, off offset:128
	v_mul_f32_e32 v0, v31, v71
	v_bfe_u32 v1, v0, 16, 1
	s_and_b64 s[0:1], s[18:19], s[20:21]
	s_mov_b32 s6, 1
	v_add3_u32 v0, v0, v1, s65
	s_mov_b64 s[20:21], 0
	s_and_b64 vcc, exec, s[0:1]
	global_store_short_d16_hi v[2:3], v0, off offset:192
	s_cbranch_vccz .LBB0_676

.LBB0_700:
	s_waitcnt lgkmcnt(0)
	v_cndmask_b32_e64 v99, v99, v148, s[0:1]
	v_mul_f32_e32 v99, 0xbe38aa3b, v99
	v_fmamk_f32 v80, v80, 0x3e38aa3b, v99
	v_fmamk_f32 v81, v81, 0x3e38aa3b, v99
	v_fmamk_f32 v100, v82, 0x3e38aa3b, v99
	v_exp_f32_e32 v82, v80
	v_fmamk_f32 v101, v84, 0x3e38aa3b, v99
	v_exp_f32_e32 v84, v81
	v_fmamk_f32 v83, v83, 0x3e38aa3b, v99
	v_exp_f32_e32 v80, v100
	v_fmamk_f32 v64, v64, 0x3e38aa3b, v99
	v_exp_f32_e32 v83, v83
	v_fmamk_f32 v102, v85, 0x3e38aa3b, v99
	v_fmamk_f32 v111, v94, 0x3e38aa3b, v99
	v_fmamk_f32 v94, v75, 0x3e38aa3b, v99
	v_exp_f32_e32 v75, v101
	v_exp_f32_e32 v100, v64
	v_add_f32_e32 v64, 0, v82
	v_fmamk_f32 v103, v86, 0x3e38aa3b, v99
	v_exp_f32_e32 v81, v102
	v_add_f32_e32 v64, v84, v64
	v_fmamk_f32 v104, v87, 0x3e38aa3b, v99
	v_fmamk_f32 v110, v93, 0x3e38aa3b, v99
	v_fmamk_f32 v93, v74, 0x3e38aa3b, v99
	v_exp_f32_e32 v74, v103
	v_add_f32_e32 v64, v80, v64
	v_fmamk_f32 v105, v88, 0x3e38aa3b, v99
	v_fmamk_f32 v112, v95, 0x3e38aa3b, v99
	v_fmamk_f32 v95, v76, 0x3e38aa3b, v99
	v_exp_f32_e32 v76, v104
	v_add_f32_e32 v64, v83, v64
	v_fmamk_f32 v106, v89, 0x3e38aa3b, v99
	v_fmamk_f32 v107, v90, 0x3e38aa3b, v99
	v_fmamk_f32 v90, v71, 0x3e38aa3b, v99
	v_exp_f32_e32 v71, v105
	v_add_f32_e32 v64, v75, v64
	v_fmamk_f32 v109, v92, 0x3e38aa3b, v99
	v_fmamk_f32 v92, v73, 0x3e38aa3b, v99
	v_exp_f32_e32 v73, v106
	v_add_f32_e32 v64, v81, v64
	v_fmamk_f32 v108, v91, 0x3e38aa3b, v99
	v_fmamk_f32 v88, v69, 0x3e38aa3b, v99
	v_exp_f32_e32 v69, v107
	v_add_f32_e32 v64, v74, v64
	v_fmamk_f32 v91, v72, 0x3e38aa3b, v99
	v_exp_f32_e32 v72, v108
	v_add_f32_e32 v64, v76, v64
	v_fmamk_f32 v86, v67, 0x3e38aa3b, v99
	v_exp_f32_e32 v67, v109
	v_add_f32_e32 v64, v71, v64
	v_fmamk_f32 v89, v70, 0x3e38aa3b, v99
	v_exp_f32_e32 v70, v110
	v_add_f32_e32 v64, v73, v64
	v_fmamk_f32 v85, v66, 0x3e38aa3b, v99
	v_exp_f32_e32 v66, v111
	v_add_f32_e32 v64, v69, v64
	v_fmamk_f32 v87, v68, 0x3e38aa3b, v99
	v_exp_f32_e32 v68, v112
	v_add_f32_e32 v64, v72, v64
	v_fmamk_f32 v65, v65, 0x3e38aa3b, v99
	v_add_f32_e32 v64, v67, v64
	v_exp_f32_e32 v101, v65
	v_add_f32_e32 v64, v70, v64
	v_exp_f32_e32 v85, v85
	v_add_f32_e32 v64, v66, v64
	v_exp_f32_e32 v86, v86
	v_add_f32_e32 v64, v68, v64
	v_exp_f32_e32 v87, v87
	v_add_f32_e32 v64, v100, v64
	v_exp_f32_e32 v88, v88
	v_add_f32_e32 v64, v101, v64
	v_exp_f32_e32 v89, v89
	v_add_f32_e32 v64, v85, v64
	v_exp_f32_e32 v90, v90
	v_add_f32_e32 v64, v86, v64
	v_exp_f32_e32 v91, v91
	v_add_f32_e32 v64, v87, v64
	v_exp_f32_e32 v92, v92
	v_add_f32_e32 v64, v88, v64
	v_exp_f32_e32 v93, v93
	v_add_f32_e32 v64, v89, v64
	v_exp_f32_e32 v94, v94
	v_add_f32_e32 v64, v90, v64
	v_fmamk_f32 v77, v77, 0x3e38aa3b, v99
	v_exp_f32_e32 v95, v95
	v_add_f32_e32 v64, v91, v64
	v_fmamk_f32 v78, v78, 0x3e38aa3b, v99
	v_exp_f32_e32 v102, v77
	v_add_f32_e32 v64, v92, v64
	v_fmac_f32_e32 v99, 0x3e38aa3b, v79
	v_exp_f32_e32 v103, v78
	v_add_f32_e32 v64, v93, v64
	v_exp_f32_e32 v99, v99
	v_add_f32_e32 v64, v94, v64
	v_add_f32_e32 v64, v95, v64
	v_add_f32_e32 v64, v102, v64
	v_add_f32_e32 v64, v103, v64
	v_add_f32_e32 v64, v99, v64
	v_mov_b32_e32 v65, v64
	s_nop 1
	v_permlane32_swap_b32_e32 v64, v65
	v_cvt_pk_bf16_f32 v78, v82, v84
	v_cvt_pk_bf16_f32 v79, v80, v83
	v_cvt_pk_bf16_f32 v80, v75, v81
	v_cvt_pk_bf16_f32 v81, v74, v76
	v_cvt_pk_bf16_f32 v74, v71, v73
	v_cvt_pk_bf16_f32 v75, v69, v72
	v_cvt_pk_bf16_f32 v76, v67, v70
	v_cvt_pk_bf16_f32 v77, v66, v68
	v_cvt_pk_bf16_f32 v66, v100, v101
	v_cvt_pk_bf16_f32 v67, v85, v86
	v_cvt_pk_bf16_f32 v68, v87, v88
	v_cvt_pk_bf16_f32 v69, v89, v90
	v_cvt_pk_bf16_f32 v70, v91, v92
	v_cvt_pk_bf16_f32 v71, v93, v94
	v_cvt_pk_bf16_f32 v72, v95, v102
	v_cvt_pk_bf16_f32 v73, v103, v99
	s_nop 0
	v_permlane32_swap_b32_e32 v78, v80
	v_permlane32_swap_b32_e32 v79, v81
	v_permlane32_swap_b32_e32 v74, v76
	v_permlane32_swap_b32_e32 v75, v77
	v_permlane32_swap_b32_e32 v66, v68
	v_permlane32_swap_b32_e32 v67, v69
	v_permlane32_swap_b32_e32 v70, v72
	v_permlane32_swap_b32_e32 v71, v73
	ds_read_b64_tr_b16 v[82:83], v168 offset:0
	ds_read_b64_tr_b16 v[84:85], v168 offset:0x800
	ds_read_b64_tr_b16 v[86:87], v168 offset:0x1000
	ds_read_b64_tr_b16 v[88:89], v168 offset:0x1800
	ds_read_b64_tr_b16 v[90:91], v168 offset:0x2000
	ds_read_b64_tr_b16 v[92:93], v168 offset:0x2800
	ds_read_b64_tr_b16 v[100:101], v168 offset:0x3000
	ds_read_b64_tr_b16 v[102:103], v168 offset:0x3800
	s_nop 0
	s_waitcnt lgkmcnt(6)
	v_mfma_f32_32x32x16_bf16 v[0:15], v[78:81], v[82:85], v[0:15]
	ds_read_b64_tr_b16 v[82:83], v168 offset:0x200
	ds_read_b64_tr_b16 v[84:85], v168 offset:0xa00
	s_waitcnt lgkmcnt(6)
	v_mfma_f32_32x32x16_bf16 v[0:15], v[74:77], v[86:89], v[0:15]
	ds_read_b64_tr_b16 v[86:87], v168 offset:0x1200
	ds_read_b64_tr_b16 v[88:89], v168 offset:0x1a00
	s_waitcnt lgkmcnt(6)
	v_mfma_f32_32x32x16_bf16 v[0:15], v[66:69], v[90:93], v[0:15]
	ds_read_b64_tr_b16 v[90:91], v168 offset:0x2200
	ds_read_b64_tr_b16 v[92:93], v168 offset:0x2a00
	s_waitcnt lgkmcnt(6)
	v_mfma_f32_32x32x16_bf16 v[0:15], v[70:73], v[100:103], v[0:15]
	ds_read_b64_tr_b16 v[100:101], v168 offset:0x3200
	ds_read_b64_tr_b16 v[102:103], v168 offset:0x3a00
	s_waitcnt lgkmcnt(6)
	v_mfma_f32_32x32x16_bf16 v[48:63], v[78:81], v[82:85], v[48:63]
	ds_read_b64_tr_b16 v[82:83], v168 offset:0x400
	ds_read_b64_tr_b16 v[84:85], v168 offset:0xc00
	s_waitcnt lgkmcnt(6)
	v_mfma_f32_32x32x16_bf16 v[48:63], v[74:77], v[86:89], v[48:63]
	ds_read_b64_tr_b16 v[86:87], v168 offset:0x1400
	ds_read_b64_tr_b16 v[88:89], v168 offset:0x1c00
	s_waitcnt lgkmcnt(6)
	v_mfma_f32_32x32x16_bf16 v[48:63], v[66:69], v[90:93], v[48:63]
	ds_read_b64_tr_b16 v[90:91], v168 offset:0x2400
	ds_read_b64_tr_b16 v[92:93], v168 offset:0x2c00
	s_waitcnt lgkmcnt(6)
	v_mfma_f32_32x32x16_bf16 v[48:63], v[70:73], v[100:103], v[48:63]
	ds_read_b64_tr_b16 v[100:101], v168 offset:0x3400
	ds_read_b64_tr_b16 v[102:103], v168 offset:0x3c00
	s_waitcnt lgkmcnt(6)
	v_mfma_f32_32x32x16_bf16 v[32:47], v[78:81], v[82:85], v[32:47]
	ds_read_b64_tr_b16 v[82:83], v168 offset:0x600
	ds_read_b64_tr_b16 v[84:85], v168 offset:0xe00
	s_waitcnt lgkmcnt(6)
	v_mfma_f32_32x32x16_bf16 v[32:47], v[74:77], v[86:89], v[32:47]
	ds_read_b64_tr_b16 v[86:87], v168 offset:0x1600
	ds_read_b64_tr_b16 v[88:89], v168 offset:0x1e00
	s_waitcnt lgkmcnt(6)
	v_mfma_f32_32x32x16_bf16 v[32:47], v[66:69], v[90:93], v[32:47]
	ds_read_b64_tr_b16 v[90:91], v168 offset:0x2600
	ds_read_b64_tr_b16 v[92:93], v168 offset:0x2e00
	s_waitcnt lgkmcnt(6)
	v_mfma_f32_32x32x16_bf16 v[32:47], v[70:73], v[100:103], v[32:47]
	ds_read_b64_tr_b16 v[100:101], v168 offset:0x3600
	ds_read_b64_tr_b16 v[102:103], v168 offset:0x3e00
	s_waitcnt lgkmcnt(6)
	v_mfma_f32_32x32x16_bf16 v[16:31], v[78:81], v[82:85], v[16:31]
	s_waitcnt lgkmcnt(4)
	v_mfma_f32_32x32x16_bf16 v[16:31], v[74:77], v[86:89], v[16:31]
	s_waitcnt lgkmcnt(2)
	v_mfma_f32_32x32x16_bf16 v[16:31], v[66:69], v[90:93], v[16:31]
	s_waitcnt lgkmcnt(0)
	v_mfma_f32_32x32x16_bf16 v[16:31], v[70:73], v[100:103], v[16:31]
	s_and_saveexec_b64 s[0:1], s[6:7]
	v_add_f32_e32 v66, v96, v97
	v_fmac_f32_e32 v66, v167, v144
	v_add_f32_e32 v64, v64, v65
	v_fmac_f32_e32 v64, v66, v98
	ds_write_b32 v166, v64
	s_or_b64 exec, exec, s[0:1]
	s_waitcnt lgkmcnt(0)
	v_add_u32_e32 v72, v161, v178
	ds_read_b128 v[64:67], v72
	ds_read_b128 v[68:71], v72 offset:32
	s_lshl_b64 s[0:1], s[20:21], 12
	s_add_u32 s0, s74, s0
	s_addc_u32 s1, s75, s1
	s_waitcnt lgkmcnt(1)
	v_rcp_f32_e32 v73, v64
	v_rcp_f32_e32 v74, v65
	v_rcp_f32_e32 v75, v66
	v_rcp_f32_e32 v76, v67
	ds_read_b128 v[64:67], v72 offset:64
	s_add_u32 s28, s0, s88
	v_ashrrev_i32_e32 v161, 31, v160
	s_addc_u32 s29, s1, 0
	s_waitcnt lgkmcnt(1)
	v_rcp_f32_e32 v77, v68
	v_rcp_f32_e32 v78, v69
	v_rcp_f32_e32 v79, v70
	v_rcp_f32_e32 v80, v71
	ds_read_b128 v[68:71], v72 offset:96
	s_waitcnt lgkmcnt(1)
	v_rcp_f32_e32 v72, v64
	v_rcp_f32_e32 v81, v65
	v_lshlrev_b64 v[64:65], 12, v[160:161]
	v_lshl_add_u64 v[64:65], s[28:29], 0, v[64:65]
	v_lshlrev_b32_e32 v178, 1, v165
	v_rcp_f32_e32 v82, v66
	v_rcp_f32_e32 v83, v67
	v_lshlrev_b32_e32 v66, 14, v164
	v_lshl_add_u64 v[64:65], v[64:65], 0, v[178:179]
	v_mov_b32_e32 v67, v179
	v_mul_f32_e32 v0, v0, v73
	v_lshl_add_u64 v[64:65], v[64:65], 0, v[66:67]
	s_nop 0
	v_cvt_pk_bf16_f32 v0, v0, v0
	global_store_short v[64:65], v0, off
	v_mul_f32_e32 v0, v48, v73
	v_cvt_pk_bf16_f32 v0, v0, v0
	global_store_short v[64:65], v0, off offset:64
	v_mul_f32_e32 v0, v32, v73
	v_cvt_pk_bf16_f32 v0, v0, v0
	global_store_short v[64:65], v0, off offset:128
	v_mul_f32_e32 v0, v16, v73
	v_cvt_pk_bf16_f32 v0, v0, v0
	global_store_short v[64:65], v0, off offset:192
	v_mul_f32_e32 v0, v1, v74
	s_nop 0
	s_movk_i32 s0, 0x1000
	v_cvt_pk_bf16_f32 v16, v0, v0
	v_add_co_u32_e32 v0, vcc, s0, v64
	s_movk_i32 s0, 0x3000
	s_nop 0
	v_addc_co_u32_e32 v1, vcc, 0, v65, vcc
	v_add_co_u32_e32 v66, vcc, s93, v64
	s_mov_b32 s93, 0x10000
	s_nop 0
	v_addc_co_u32_e32 v67, vcc, 0, v65, vcc
	global_store_short v[66:67], v16, off offset:-4096
	v_mul_f32_e32 v16, v49, v74
	s_nop 0
	v_cvt_pk_bf16_f32 v16, v16, v16
	global_store_short v[0:1], v16, off offset:64
	v_mul_f32_e32 v16, v33, v74
	v_cvt_pk_bf16_f32 v16, v16, v16
	global_store_short v[0:1], v16, off offset:128
	v_mul_f32_e32 v16, v17, v74
	v_cvt_pk_bf16_f32 v16, v16, v16
	global_store_short v[0:1], v16, off offset:192
	v_mul_f32_e32 v0, v2, v75
	v_cvt_pk_bf16_f32 v0, v0, v0
	global_store_short v[66:67], v0, off
	v_mul_f32_e32 v0, v50, v75
	v_cvt_pk_bf16_f32 v0, v0, v0
	global_store_short v[66:67], v0, off offset:64
	v_mul_f32_e32 v0, v34, v75
	v_cvt_pk_bf16_f32 v0, v0, v0
	global_store_short v[66:67], v0, off offset:128
	v_mul_f32_e32 v0, v18, v75
	v_cvt_pk_bf16_f32 v0, v0, v0
	global_store_short v[66:67], v0, off offset:192
	v_mul_f32_e32 v0, v3, v76
	s_nop 0
	v_cvt_pk_bf16_f32 v2, v0, v0
	v_add_co_u32_e32 v0, vcc, s0, v64
	s_mov_b32 s0, 0x8000
	s_nop 0
	v_addc_co_u32_e32 v1, vcc, 0, v65, vcc
	global_store_short v[0:1], v2, off
	v_mul_f32_e32 v2, v51, v76
	s_nop 0
	v_cvt_pk_bf16_f32 v2, v2, v2
	global_store_short v[0:1], v2, off offset:64
	v_mul_f32_e32 v2, v35, v76
	v_cvt_pk_bf16_f32 v2, v2, v2
	global_store_short v[0:1], v2, off offset:128
	v_mul_f32_e32 v2, v19, v76
	v_cvt_pk_bf16_f32 v2, v2, v2
	global_store_short v[0:1], v2, off offset:192
	v_mul_f32_e32 v0, v4, v77
	s_nop 0
	v_cvt_pk_bf16_f32 v4, v0, v0
	v_add_co_u32_e32 v0, vcc, s0, v64
	s_mov_b32 s0, 0x9000
	s_nop 0
	v_addc_co_u32_e32 v1, vcc, 0, v65, vcc
	v_add_co_u32_e32 v2, vcc, s0, v64
	s_mov_b32 s0, 0xa000
	s_nop 0
	v_addc_co_u32_e32 v3, vcc, 0, v65, vcc
	global_store_short v[2:3], v4, off offset:-4096
	v_mul_f32_e32 v4, v52, v77
	s_nop 0
	v_cvt_pk_bf16_f32 v4, v4, v4
	global_store_short v[0:1], v4, off offset:64
	v_mul_f32_e32 v4, v36, v77
	v_cvt_pk_bf16_f32 v4, v4, v4
	global_store_short v[0:1], v4, off offset:128
	v_mul_f32_e32 v4, v20, v77
	v_cvt_pk_bf16_f32 v4, v4, v4
	global_store_short v[0:1], v4, off offset:192
	v_mul_f32_e32 v0, v5, v78
	v_cvt_pk_bf16_f32 v0, v0, v0
	global_store_short v[2:3], v0, off
	v_mul_f32_e32 v0, v53, v78
	v_cvt_pk_bf16_f32 v0, v0, v0
	global_store_short v[2:3], v0, off offset:64
	v_mul_f32_e32 v0, v37, v78
	v_cvt_pk_bf16_f32 v0, v0, v0
	global_store_short v[2:3], v0, off offset:128
	v_mul_f32_e32 v0, v21, v78
	v_cvt_pk_bf16_f32 v0, v0, v0
	global_store_short v[2:3], v0, off offset:192
	v_mul_f32_e32 v0, v6, v79
	s_nop 0
	v_cvt_pk_bf16_f32 v4, v0, v0
	v_add_co_u32_e32 v0, vcc, s0, v64
	s_mov_b32 s0, 0xb000
	s_nop 0
	v_addc_co_u32_e32 v1, vcc, 0, v65, vcc
	v_add_co_u32_e32 v2, vcc, s0, v64
	s_mov_b32 s0, 0x11000
	s_nop 0
	v_addc_co_u32_e32 v3, vcc, 0, v65, vcc
	global_store_short v[2:3], v4, off offset:-4096
	v_mul_f32_e32 v4, v54, v79
	s_nop 0
	v_cvt_pk_bf16_f32 v4, v4, v4
	global_store_short v[0:1], v4, off offset:64
	v_mul_f32_e32 v4, v38, v79
	v_cvt_pk_bf16_f32 v4, v4, v4
	global_store_short v[0:1], v4, off offset:128
	v_mul_f32_e32 v4, v22, v79
	v_cvt_pk_bf16_f32 v4, v4, v4
	global_store_short v[0:1], v4, off offset:192
	v_mul_f32_e32 v0, v7, v80
	v_cvt_pk_bf16_f32 v0, v0, v0
	global_store_short v[2:3], v0, off
	v_mul_f32_e32 v0, v55, v80
	v_cvt_pk_bf16_f32 v0, v0, v0
	global_store_short v[2:3], v0, off offset:64
	v_mul_f32_e32 v0, v39, v80
	v_cvt_pk_bf16_f32 v0, v0, v0
	global_store_short v[2:3], v0, off offset:128
	v_mul_f32_e32 v0, v23, v80
	v_cvt_pk_bf16_f32 v0, v0, v0
	global_store_short v[2:3], v0, off offset:192
	v_mul_f32_e32 v0, v8, v72
	s_nop 0
	v_cvt_pk_bf16_f32 v4, v0, v0
	v_add_co_u32_e32 v0, vcc, s93, v64
	s_waitcnt lgkmcnt(0)
	v_rcp_f32_e32 v68, v68
	v_addc_co_u32_e32 v1, vcc, 0, v65, vcc
	v_add_co_u32_e32 v2, vcc, s0, v64
	s_mov_b32 s0, 0x12000
	s_nop 0
	v_addc_co_u32_e32 v3, vcc, 0, v65, vcc
	global_store_short v[2:3], v4, off offset:-4096
	v_mul_f32_e32 v4, v56, v72
	s_nop 0
	v_cvt_pk_bf16_f32 v4, v4, v4
	global_store_short v[0:1], v4, off offset:64
	v_mul_f32_e32 v4, v40, v72
	v_cvt_pk_bf16_f32 v4, v4, v4
	global_store_short v[0:1], v4, off offset:128
	v_mul_f32_e32 v4, v24, v72
	v_cvt_pk_bf16_f32 v4, v4, v4
	global_store_short v[0:1], v4, off offset:192
	v_mul_f32_e32 v0, v9, v81
	v_cvt_pk_bf16_f32 v0, v0, v0
	global_store_short v[2:3], v0, off
	v_mul_f32_e32 v0, v57, v81
	v_cvt_pk_bf16_f32 v0, v0, v0
	global_store_short v[2:3], v0, off offset:64
	v_mul_f32_e32 v0, v41, v81
	v_cvt_pk_bf16_f32 v0, v0, v0
	global_store_short v[2:3], v0, off offset:128
	v_mul_f32_e32 v0, v25, v81
	v_cvt_pk_bf16_f32 v0, v0, v0
	global_store_short v[2:3], v0, off offset:192
	v_mul_f32_e32 v0, v10, v82
	s_nop 0
	v_cvt_pk_bf16_f32 v4, v0, v0
	v_add_co_u32_e32 v0, vcc, s0, v64
	s_mov_b32 s0, 0x13000
	s_nop 0
	v_addc_co_u32_e32 v1, vcc, 0, v65, vcc
	v_add_co_u32_e32 v2, vcc, s0, v64
	s_mov_b32 s0, 0x19000
	s_nop 0
	v_addc_co_u32_e32 v3, vcc, 0, v65, vcc
	global_store_short v[2:3], v4, off offset:-4096
	v_mul_f32_e32 v4, v58, v82
	s_nop 0
	v_cvt_pk_bf16_f32 v4, v4, v4
	global_store_short v[0:1], v4, off offset:64
	v_mul_f32_e32 v4, v42, v82
	v_cvt_pk_bf16_f32 v4, v4, v4
	global_store_short v[0:1], v4, off offset:128
	v_mul_f32_e32 v4, v26, v82
	v_cvt_pk_bf16_f32 v4, v4, v4
	global_store_short v[0:1], v4, off offset:192
	v_mul_f32_e32 v0, v11, v83
	v_cvt_pk_bf16_f32 v0, v0, v0
	global_store_short v[2:3], v0, off
	v_mul_f32_e32 v0, v59, v83
	v_cvt_pk_bf16_f32 v0, v0, v0
	global_store_short v[2:3], v0, off offset:64
	v_mul_f32_e32 v0, v43, v83
	v_cvt_pk_bf16_f32 v0, v0, v0
	global_store_short v[2:3], v0, off offset:128
	v_mul_f32_e32 v0, v27, v83
	v_cvt_pk_bf16_f32 v0, v0, v0
	global_store_short v[2:3], v0, off offset:192
	v_mul_f32_e32 v0, v12, v68
	s_nop 0
	v_cvt_pk_bf16_f32 v4, v0, v0
	v_add_co_u32_e32 v0, vcc, s92, v64
	v_rcp_f32_e32 v69, v69
	s_nop 0
	v_addc_co_u32_e32 v1, vcc, 0, v65, vcc
	v_add_co_u32_e32 v2, vcc, s0, v64
	v_rcp_f32_e32 v70, v70
	s_nop 0
	v_addc_co_u32_e32 v3, vcc, 0, v65, vcc
	global_store_short v[2:3], v4, off offset:-4096
	v_mul_f32_e32 v4, v60, v68
	s_nop 0
	v_cvt_pk_bf16_f32 v4, v4, v4
	global_store_short v[0:1], v4, off offset:64
	v_mul_f32_e32 v4, v44, v68
	v_cvt_pk_bf16_f32 v4, v4, v4
	global_store_short v[0:1], v4, off offset:128
	v_mul_f32_e32 v4, v28, v68
	v_cvt_pk_bf16_f32 v4, v4, v4
	global_store_short v[0:1], v4, off offset:192
	v_mul_f32_e32 v0, v13, v69
	v_cvt_pk_bf16_f32 v0, v0, v0
	global_store_short v[2:3], v0, off
	v_mul_f32_e32 v0, v61, v69
	v_cvt_pk_bf16_f32 v0, v0, v0
	global_store_short v[2:3], v0, off offset:64
	v_mul_f32_e32 v0, v45, v69
	v_cvt_pk_bf16_f32 v0, v0, v0
	global_store_short v[2:3], v0, off offset:128
	v_mul_f32_e32 v0, v29, v69
	v_cvt_pk_bf16_f32 v0, v0, v0
	global_store_short v[2:3], v0, off offset:192
	v_mul_f32_e32 v0, v14, v70
	s_nop 0
	s_mov_b32 s0, 0x1a000
	v_cvt_pk_bf16_f32 v4, v0, v0
	v_add_co_u32_e32 v0, vcc, s0, v64
	s_mov_b32 s0, 0x1b000
	s_nop 0
	v_addc_co_u32_e32 v1, vcc, 0, v65, vcc
	v_add_co_u32_e32 v2, vcc, s0, v64
	v_rcp_f32_e32 v71, v71
	s_nop 0
	v_addc_co_u32_e32 v3, vcc, 0, v65, vcc
	global_store_short v[2:3], v4, off offset:-4096
	v_mul_f32_e32 v4, v62, v70
	s_nop 0
	v_cvt_pk_bf16_f32 v4, v4, v4
	global_store_short v[0:1], v4, off offset:64
	v_mul_f32_e32 v4, v46, v70
	v_cvt_pk_bf16_f32 v4, v4, v4
	global_store_short v[0:1], v4, off offset:128
	v_mul_f32_e32 v4, v30, v70
	v_cvt_pk_bf16_f32 v4, v4, v4
	global_store_short v[0:1], v4, off offset:192
	v_mul_f32_e32 v0, v15, v71
	v_cvt_pk_bf16_f32 v0, v0, v0
	global_store_short v[2:3], v0, off
	v_mul_f32_e32 v0, v63, v71
	v_cvt_pk_bf16_f32 v0, v0, v0
	global_store_short v[2:3], v0, off offset:64
	v_mul_f32_e32 v0, v47, v71
	v_cvt_pk_bf16_f32 v0, v0, v0
	global_store_short v[2:3], v0, off offset:128
	v_mul_f32_e32 v0, v31, v71
	v_cvt_pk_bf16_f32 v0, v0, v0
	v_mov_b32_e32 v50, v176
	global_store_short v[2:3], v0, off offset:192
	s_waitcnt vmcnt(63) expcnt(7) lgkmcnt(15)
	s_barrier
	s_movk_i32 s0, 0xffe0
	v_ashrrev_i32_e32 v16, 1, v50
	v_bfe_u32 v164, v50, 5, 1
	v_bfi_b32 v2, s0, v16, v50
	v_mov_b64_e32 v[0:1], s[30:31]
	v_mad_i64_i32 v[0:1], s[0:1], v2, s91, v[0:1]
	v_lshlrev_b32_e32 v178, 4, v164
	v_lshl_add_u64 v[12:13], v[0:1], 0, v[178:179]
	global_load_dwordx4 v[0:3], v[12:13], off offset:128
	global_load_dwordx4 v[4:7], v[12:13], off offset:160
	global_load_dwordx4 v[8:11], v[12:13], off offset:192
	s_nop 0
	global_load_dwordx4 v[12:15], v[12:13], off offset:224
	v_and_b32_e32 v165, 31, v50
	v_and_b32_e32 v160, 0xffffffe0, v16
	s_mov_b64 s[0:1], -1
	s_and_b64 vcc, exec, s[34:35]
	s_cbranch_vccz .LBB0_704
	v_lshlrev_b32_e32 v22, 3, v164
	s_and_b64 s[0:1], s[18:19], exec
	s_cselect_b32 s0, s81, 0
	v_cvt_f32_ubyte0_e32 v17, v22
	v_or_b32_e32 v16, s0, v165
	v_mul_f32_e32 v19, 0xbf549a78, v17
	s_mov_b32 s0, 0xc2fc0000
	v_cmp_gt_f32_e32 vcc, s0, v19
	v_add_u32_e32 v18, v16, v160
	v_ashrrev_i32_e32 v16, 6, v18
	v_cndmask_b32_e32 v20, 0, v217, vcc
	v_fmac_f32_e32 v20, 0xbf549a78, v17
	v_exp_f32_e32 v17, v20
	v_cvt_f32_i32_e32 v23, v16
	v_cndmask_b32_e32 v19, 0, v218, vcc
	v_and_b32_e32 v25, 63, v18
	v_ldexp_f32 v24, v17, v19
	v_mul_f32_e32 v16, v24, v23
	v_mul_f32_e32 v17, 0.15915494, v16
	v_cos_f32_e32 v16, v17
	v_sin_f32_e32 v17, v17
	s_waitcnt vmcnt(1)
	v_lshlrev_b32_e32 v19, 16, v8
	v_lshlrev_b32_e32 v18, 16, v0
	v_cvt_f32_ubyte0_e32 v25, v25
	v_pk_mul_f32 v[20:21], v[16:17], v[18:19]
	s_nop 0
	v_sub_f32_e32 v26, v20, v21
	v_mov_b32_e32 v20, v17
	v_or_b32_e32 v17, 1, v22
	v_cvt_f32_ubyte0_e32 v17, v17
	v_mul_f32_e32 v21, 0xbf549a78, v17
	v_cmp_gt_f32_e32 vcc, s0, v21
	s_nop 1
	v_cndmask_b32_e32 v21, 0, v217, vcc
	v_fmac_f32_e32 v21, 0xbf549a78, v17
	v_exp_f32_e32 v27, v21
	v_mov_b32_e32 v21, v16
	v_pk_mul_f32 v[16:17], v[20:21], v[18:19]
	v_cndmask_b32_e32 v18, 0, v218, vcc
	v_ldexp_f32 v27, v27, v18
	v_mul_f32_e32 v18, v27, v23
	v_mul_f32_e32 v19, 0.15915494, v18
	v_cos_f32_e32 v18, v19
	v_sin_f32_e32 v19, v19
	v_add_f32_e32 v28, v16, v17
	v_and_b32_e32 v17, 0xffff0000, v8
	v_and_b32_e32 v16, 0xffff0000, v0
	v_pk_mul_f32 v[20:21], v[18:19], v[16:17]
	s_nop 0
	v_sub_f32_e32 v29, v20, v21
	v_mov_b32_e32 v20, v19
	v_or_b32_e32 v19, 2, v22
	v_cvt_f32_ubyte0_e32 v19, v19
	v_mul_f32_e32 v21, 0xbf549a78, v19
	v_cmp_gt_f32_e32 vcc, s0, v21
	v_cvt_pk_bf16_f32 v100, v26, v29
	s_nop 1
	v_cndmask_b32_e32 v21, 0, v217, vcc
	v_fmac_f32_e32 v21, 0xbf549a78, v19
	v_exp_f32_e32 v19, v21
	v_mov_b32_e32 v21, v18
	v_cndmask_b32_e32 v18, 0, v218, vcc
	v_pk_mul_f32 v[16:17], v[20:21], v[16:17]
	v_ldexp_f32 v30, v19, v18
	v_mul_f32_e32 v18, v30, v23
	v_mul_f32_e32 v19, 0.15915494, v18
	v_cos_f32_e32 v18, v19
	v_sin_f32_e32 v19, v19
	v_add_f32_e32 v31, v16, v17
	v_lshlrev_b32_e32 v17, 16, v9
	v_lshlrev_b32_e32 v16, 16, v1
	v_pk_mul_f32 v[20:21], v[18:19], v[16:17]
	s_nop 0
	v_sub_f32_e32 v32, v20, v21
	v_mov_b32_e32 v20, v19
	v_or_b32_e32 v19, 3, v22
	v_cvt_f32_ubyte0_e32 v19, v19
	v_mul_f32_e32 v21, 0xbf549a78, v19
	v_cmp_gt_f32_e32 vcc, s0, v21
	s_nop 1
	v_cndmask_b32_e32 v21, 0, v217, vcc
	v_fmac_f32_e32 v21, 0xbf549a78, v19
	v_exp_f32_e32 v19, v21
	v_mov_b32_e32 v21, v18
	v_cndmask_b32_e32 v18, 0, v218, vcc
	v_pk_mul_f32 v[16:17], v[20:21], v[16:17]
	v_ldexp_f32 v33, v19, v18
	v_mul_f32_e32 v18, v33, v23
	v_mul_f32_e32 v19, 0.15915494, v18
	v_cos_f32_e32 v18, v19
	v_sin_f32_e32 v19, v19
	v_add_f32_e32 v34, v16, v17
	v_and_b32_e32 v17, 0xffff0000, v9
	v_and_b32_e32 v16, 0xffff0000, v1
	v_pk_mul_f32 v[20:21], v[18:19], v[16:17]
	s_nop 0
	v_sub_f32_e32 v35, v20, v21
	v_mov_b32_e32 v20, v19
	v_or_b32_e32 v19, 4, v22
	v_cvt_f32_ubyte0_e32 v19, v19
	v_mul_f32_e32 v21, 0xbf549a78, v19
	v_cmp_gt_f32_e32 vcc, s0, v21
	v_cvt_pk_bf16_f32 v101, v32, v35
	s_nop 1
	v_cndmask_b32_e32 v21, 0, v217, vcc
	v_fmac_f32_e32 v21, 0xbf549a78, v19
	v_exp_f32_e32 v19, v21
	v_mov_b32_e32 v21, v18
	v_cndmask_b32_e32 v18, 0, v218, vcc
	v_pk_mul_f32 v[16:17], v[20:21], v[16:17]
	v_ldexp_f32 v36, v19, v18
	v_mul_f32_e32 v18, v36, v23
	v_mul_f32_e32 v19, 0.15915494, v18
	v_cos_f32_e32 v18, v19
	v_sin_f32_e32 v19, v19
	v_add_f32_e32 v37, v16, v17
	v_lshlrev_b32_e32 v17, 16, v10
	v_lshlrev_b32_e32 v16, 16, v2
	v_pk_mul_f32 v[20:21], v[18:19], v[16:17]
	s_nop 0
	v_sub_f32_e32 v38, v20, v21
	v_mov_b32_e32 v20, v19
	v_or_b32_e32 v19, 5, v22
	v_cvt_f32_ubyte0_e32 v19, v19
	v_mul_f32_e32 v21, 0xbf549a78, v19
	v_cmp_gt_f32_e32 vcc, s0, v21
	s_nop 1
	v_cndmask_b32_e32 v21, 0, v217, vcc
	v_fmac_f32_e32 v21, 0xbf549a78, v19
	v_exp_f32_e32 v19, v21
	v_mov_b32_e32 v21, v18
	v_cndmask_b32_e32 v18, 0, v218, vcc
	v_pk_mul_f32 v[16:17], v[20:21], v[16:17]
	v_ldexp_f32 v39, v19, v18
	v_mul_f32_e32 v18, v39, v23
	v_mul_f32_e32 v19, 0.15915494, v18
	v_cos_f32_e32 v18, v19
	v_sin_f32_e32 v19, v19
	v_add_f32_e32 v40, v16, v17
	v_and_b32_e32 v17, 0xffff0000, v10
	v_and_b32_e32 v16, 0xffff0000, v2
	v_pk_mul_f32 v[20:21], v[18:19], v[16:17]
	s_nop 0
	v_sub_f32_e32 v41, v20, v21
	v_mov_b32_e32 v20, v19
	v_or_b32_e32 v19, 6, v22
	v_cvt_f32_ubyte0_e32 v19, v19
	v_mul_f32_e32 v21, 0xbf549a78, v19
	v_cmp_gt_f32_e32 vcc, s0, v21
	v_cvt_pk_bf16_f32 v102, v38, v41
	s_nop 1
	v_cndmask_b32_e32 v21, 0, v217, vcc
	v_fmac_f32_e32 v21, 0xbf549a78, v19
	v_exp_f32_e32 v19, v21
	v_mov_b32_e32 v21, v18
	v_cndmask_b32_e32 v18, 0, v218, vcc
	v_pk_mul_f32 v[16:17], v[20:21], v[16:17]
	v_ldexp_f32 v42, v19, v18
	v_mul_f32_e32 v18, v42, v23
	v_mul_f32_e32 v19, 0.15915494, v18
	v_cos_f32_e32 v18, v19
	v_sin_f32_e32 v19, v19
	v_add_f32_e32 v43, v16, v17
	v_lshlrev_b32_e32 v17, 16, v11
	v_lshlrev_b32_e32 v16, 16, v3
	v_pk_mul_f32 v[20:21], v[18:19], v[16:17]
	s_nop 0
	v_sub_f32_e32 v44, v20, v21
	v_mov_b32_e32 v20, v19
	v_or_b32_e32 v19, 7, v22
	v_cvt_f32_ubyte0_e32 v19, v19
	v_mul_f32_e32 v21, 0xbf549a78, v19
	v_cmp_gt_f32_e32 vcc, s0, v21
	s_mov_b64 s[0:1], 0
	s_nop 0
	v_cndmask_b32_e32 v21, 0, v217, vcc
	v_fmac_f32_e32 v21, 0xbf549a78, v19
	v_exp_f32_e32 v19, v21
	v_mov_b32_e32 v21, v18
	v_cndmask_b32_e32 v18, 0, v218, vcc
	v_pk_mul_f32 v[16:17], v[20:21], v[16:17]
	v_ldexp_f32 v22, v19, v18
	v_mul_f32_e32 v18, v22, v23
	v_mul_f32_e32 v19, 0.15915494, v18
	v_cos_f32_e32 v18, v19
	v_sin_f32_e32 v19, v19
	v_add_f32_e32 v23, v16, v17
	v_and_b32_e32 v17, 0xffff0000, v11
	v_and_b32_e32 v16, 0xffff0000, v3
	v_pk_mul_f32 v[20:21], v[18:19], v[16:17]
	s_nop 0
	v_sub_f32_e32 v45, v20, v21
	v_mov_b32_e32 v20, v19
	v_mov_b32_e32 v21, v18
	v_pk_mul_f32 v[16:17], v[20:21], v[16:17]
	v_cvt_pk_bf16_f32 v103, v44, v45
	v_cvt_pk_bf16_f32 v96, v28, v31
	v_cvt_pk_bf16_f32 v97, v34, v37
	v_cvt_pk_bf16_f32 v98, v40, v43
	s_waitcnt vmcnt(0)
	v_lshlrev_b32_e32 v19, 16, v12
	v_add_f32_e32 v18, v16, v17
	v_mul_f32_e32 v16, v24, v25
	v_mul_f32_e32 v17, 0.15915494, v16
	v_cos_f32_e32 v16, v17
	v_sin_f32_e32 v17, v17
	v_cvt_pk_bf16_f32 v99, v23, v18
	v_lshlrev_b32_e32 v18, 16, v4
	v_pk_mul_f32 v[20:21], v[16:17], v[18:19]
	s_nop 0
	v_sub_f32_e32 v23, v20, v21
	v_mov_b32_e32 v20, v17
	v_mov_b32_e32 v21, v16
	v_pk_mul_f32 v[16:17], v[20:21], v[18:19]
	v_mul_f32_e32 v18, v27, v25
	v_mul_f32_e32 v19, 0.15915494, v18
	v_cos_f32_e32 v18, v19
	v_sin_f32_e32 v19, v19
	v_add_f32_e32 v24, v16, v17
	v_and_b32_e32 v17, 0xffff0000, v12
	v_and_b32_e32 v16, 0xffff0000, v4
	v_pk_mul_f32 v[20:21], v[18:19], v[16:17]
	s_nop 0
	v_sub_f32_e32 v26, v20, v21
	v_mov_b32_e32 v21, v18
	v_mul_f32_e32 v18, v30, v25
	v_mov_b32_e32 v20, v19
	v_mul_f32_e32 v19, 0.15915494, v18
	v_cos_f32_e32 v18, v19
	v_sin_f32_e32 v19, v19
	v_pk_mul_f32 v[16:17], v[20:21], v[16:17]
	v_cvt_pk_bf16_f32 v108, v23, v26
	s_nop 0
	v_add_f32_e32 v27, v16, v17
	v_lshlrev_b32_e32 v17, 16, v13
	v_lshlrev_b32_e32 v16, 16, v5
	v_pk_mul_f32 v[20:21], v[18:19], v[16:17]
	s_nop 0
	v_sub_f32_e32 v28, v20, v21
	v_mov_b32_e32 v21, v18
	v_mul_f32_e32 v18, v33, v25
	v_mov_b32_e32 v20, v19
	v_mul_f32_e32 v19, 0.15915494, v18
	v_cos_f32_e32 v18, v19
	v_sin_f32_e32 v19, v19
	v_pk_mul_f32 v[16:17], v[20:21], v[16:17]
	s_nop 0
	v_add_f32_e32 v29, v16, v17
	v_and_b32_e32 v17, 0xffff0000, v13
	v_and_b32_e32 v16, 0xffff0000, v5
	v_pk_mul_f32 v[20:21], v[18:19], v[16:17]
	s_nop 0
	v_sub_f32_e32 v30, v20, v21
	v_mov_b32_e32 v21, v18
	v_mul_f32_e32 v18, v36, v25
	v_mov_b32_e32 v20, v19
	v_mul_f32_e32 v19, 0.15915494, v18
	v_cos_f32_e32 v18, v19
	v_sin_f32_e32 v19, v19
	v_pk_mul_f32 v[16:17], v[20:21], v[16:17]
	v_cvt_pk_bf16_f32 v109, v28, v30
	s_nop 0
	v_add_f32_e32 v31, v16, v17
	v_lshlrev_b32_e32 v17, 16, v14
	v_lshlrev_b32_e32 v16, 16, v6
	v_pk_mul_f32 v[20:21], v[18:19], v[16:17]
	s_nop 0
	v_sub_f32_e32 v32, v20, v21
	v_mov_b32_e32 v21, v18
	v_mul_f32_e32 v18, v39, v25
	v_mov_b32_e32 v20, v19
	v_mul_f32_e32 v19, 0.15915494, v18
	v_cos_f32_e32 v18, v19
	v_sin_f32_e32 v19, v19
	v_pk_mul_f32 v[16:17], v[20:21], v[16:17]
	s_nop 0
	v_add_f32_e32 v33, v16, v17
	v_and_b32_e32 v17, 0xffff0000, v14
	v_and_b32_e32 v16, 0xffff0000, v6
	v_pk_mul_f32 v[20:21], v[18:19], v[16:17]
	s_nop 0
	v_sub_f32_e32 v34, v20, v21
	v_mov_b32_e32 v21, v18
	v_mul_f32_e32 v18, v42, v25
	v_mov_b32_e32 v20, v19
	v_mul_f32_e32 v19, 0.15915494, v18
	v_cos_f32_e32 v18, v19
	v_sin_f32_e32 v19, v19
	v_pk_mul_f32 v[16:17], v[20:21], v[16:17]
	v_cvt_pk_bf16_f32 v110, v32, v34
	s_nop 0
	v_add_f32_e32 v35, v16, v17
	v_lshlrev_b32_e32 v17, 16, v15
	v_lshlrev_b32_e32 v16, 16, v7
	v_pk_mul_f32 v[20:21], v[18:19], v[16:17]
	s_nop 0
	v_sub_f32_e32 v36, v20, v21
	v_mov_b32_e32 v21, v18
	v_mul_f32_e32 v18, v22, v25
	v_mov_b32_e32 v20, v19
	v_mul_f32_e32 v19, 0.15915494, v18
	v_cos_f32_e32 v18, v19
	v_sin_f32_e32 v19, v19
	v_pk_mul_f32 v[16:17], v[20:21], v[16:17]
	s_nop 0
	v_add_f32_e32 v22, v16, v17
	v_and_b32_e32 v17, 0xffff0000, v15
	v_and_b32_e32 v16, 0xffff0000, v7
	v_pk_mul_f32 v[20:21], v[18:19], v[16:17]
	s_nop 0
	v_sub_f32_e32 v25, v20, v21
	v_mov_b32_e32 v20, v19
	v_mov_b32_e32 v21, v18
	v_pk_mul_f32 v[16:17], v[20:21], v[16:17]
	v_cvt_pk_bf16_f32 v111, v36, v25
	v_cvt_pk_bf16_f32 v104, v24, v27
	v_cvt_pk_bf16_f32 v105, v29, v31
	v_cvt_pk_bf16_f32 v106, v33, v35
	s_nop 0
	v_add_f32_e32 v16, v16, v17
	v_cvt_pk_bf16_f32 v107, v22, v16

.LBB0_746:
	v_readlane_b32 s0, v254, 45
	v_readlane_b32 s2, v254, 41
	v_readlane_b32 s3, v254, 48
	v_or_b32_e32 v0, s0, v102
	v_readlane_b32 s0, v254, 49
	v_readlane_b32 s1, v254, 50
	s_or_b32 s4, s3, s2
	s_lshl_b32 s2, s3, 1
	v_readlane_b32 s6, v254, 51
	s_load_dwordx2 s[0:1], s[0:1], 0x90
	v_readlane_b32 s7, v254, 52
	s_add_u32 s5, s6, s2
	s_addc_u32 s6, s7, 0
	s_add_u32 s2, s5, 0x1b801800
	s_addc_u32 s3, s6, 0
	v_or_b32_e32 v178, s4, v89
	v_mov_b64_e32 v[2:3], s[2:3]
	s_movk_i32 s91, 0x2a00
	s_waitcnt lgkmcnt(0)
	v_lshl_add_u64 v[4:5], v[178:179], 2, s[0:1]
	v_mad_i64_i32 v[6:7], s[2:3], v0, s91, v[2:3]
	v_lshlrev_b32_e32 v178, 1, v89
	v_lshl_add_u64 v[6:7], v[6:7], 0, v[178:179]
	global_load_ushort v14, v[6:7], off
	global_load_ushort v24, v[6:7], off offset:32
	global_load_ushort v25, v[6:7], off offset:64
	global_load_ushort v26, v[6:7], off offset:96
	global_load_ushort v27, v[6:7], off offset:128
	global_load_ushort v28, v[6:7], off offset:160
	global_load_ushort v29, v[6:7], off offset:192
	global_load_ushort v30, v[6:7], off offset:224
	global_load_dword v15, v[4:5], off
	v_pk_mul_f32 v[8:9], v[68:69], v[68:69]
	v_pk_mul_f32 v[10:11], v[74:75], v[74:75]
	v_pk_mul_f32 v[6:7], v[64:65], v[64:65]
	v_pk_fma_f32 v[8:9], v[66:67], v[66:67], v[8:9]
	v_mov_b32_e32 v23, v10
	v_mov_b32_e32 v10, v7
	v_pk_mul_f32 v[12:13], v[72:73], v[72:73]
	v_pk_mul_f32 v[18:19], v[62:63], v[62:63]
	v_mov_b32_e32 v22, v6
	v_pk_add_f32 v[8:9], v[10:11], v[8:9] op_sel:[0,1] op_sel_hi:[1,0]
	v_mov_b32_e32 v4, v19
	v_mov_b32_e32 v5, v13
	v_pk_add_f32 v[8:9], v[22:23], v[8:9]
	v_mov_b32_e32 v19, v12
	v_pk_add_f32 v[4:5], v[4:5], v[8:9]
	v_mov_b32_e32 v9, v179
	v_add_u32_e32 v8, s4, v89
	v_lshl_add_u64 v[10:11], v[8:9], 2, s[0:1]
	v_pk_add_f32 v[4:5], v[18:19], v[4:5]
	global_load_dword v18, v[10:11], off offset:64
	v_pk_mul_f32 v[16:17], v[70:71], v[70:71]
	v_pk_mul_f32 v[20:21], v[60:61], v[60:61]
	v_mov_b32_e32 v7, v17
	global_load_dword v17, v[10:11], off offset:128
	global_load_dword v13, v[10:11], off offset:192
	v_mov_b32_e32 v6, v21
	v_mov_b32_e32 v21, v16
	v_pk_add_f32 v[4:5], v[6:7], v[4:5]
	v_ashrrev_i32_e32 v1, 31, v0
	v_pk_add_f32 v[4:5], v[20:21], v[4:5]
	ds_bpermute_b32 v7, v191, v5
	ds_bpermute_b32 v6, v191, v4
	v_lshlrev_b64 v[8:9], 12, v[0:1]
	s_add_u32 s0, s5, 0x29200800
	s_addc_u32 s1, s6, 0
	s_mov_b32 s2, 0x358637bd
	s_waitcnt lgkmcnt(0)
	v_pk_add_f32 v[4:5], v[4:5], v[6:7]
	ds_bpermute_b32 v7, v192, v5
	ds_bpermute_b32 v6, v192, v4
	s_brev_b32 s4, 60
	s_mov_b32 s88, 0x800000
	v_readlane_b32 s92, v254, 16
	v_readlane_b32 s93, v254, 17
	s_waitcnt lgkmcnt(0)
	v_pk_add_f32 v[4:5], v[4:5], v[6:7]
	ds_bpermute_b32 v21, v193, v5
	ds_bpermute_b32 v20, v193, v4
	v_lshl_add_u64 v[6:7], s[0:1], 0, v[8:9]
	v_lshl_add_u64 v[6:7], v[6:7], 0, v[178:179]
	v_readlane_b32 s94, v254, 18
	v_readlane_b32 s95, v254, 19
	s_waitcnt lgkmcnt(0)
	v_pk_add_f32 v[4:5], v[4:5], v[20:21]
	ds_bpermute_b32 v9, v194, v5
	ds_bpermute_b32 v8, v194, v4
	v_readlane_b32 s96, v254, 20
	v_readlane_b32 s74, v254, 21
	v_readlane_b32 s97, v254, 22
	v_readlane_b32 s87, v254, 23
	s_waitcnt lgkmcnt(0)
	v_pk_add_f32 v[8:9], v[4:5], v[8:9]
	v_mov_b64_e32 v[4:5], s[2:3]
	v_pk_fma_f32 v[8:9], v[8:9], s[4:5], v[4:5] op_sel_hi:[1,0,0]
	v_readlane_b32 s73, v254, 15
	v_cmp_gt_f32_e32 vcc, s88, v9
	s_movk_i32 s90, 0x600
	v_readlane_b32 s60, v254, 29
	s_movk_i32 s89, 0x2000
	s_mov_b32 s93, 0x10000
	s_mov_b32 s62, 0x14000
	s_mov_b32 s63, 0x18000
	s_mov_b32 s75, 0x1c000
	s_mov_b32 s61, 0xffff0000
	s_mov_b32 s76, 0x10200
	s_mov_b64 s[78:79], 0x80
	s_waitcnt vmcnt(11)
	v_lshlrev_b32_e32 v1, 16, v14
	s_waitcnt vmcnt(10)
	v_lshlrev_b32_e32 v12, 16, v24
	s_waitcnt vmcnt(9)
	v_lshlrev_b32_e32 v14, 16, v25
	v_mul_f32_e32 v14, 0xbfb8aa3b, v14
	v_exp_f32_e32 v14, v14
	v_mul_f32_e32 v12, 0xbfb8aa3b, v12
	v_exp_f32_e32 v12, v12
	s_waitcnt vmcnt(6)
	v_lshlrev_b32_e32 v20, 16, v28
	v_add_f32_e32 v23, 1.0, v14
	global_load_dword v14, v[10:11], off offset:256
	v_add_f32_e32 v22, 1.0, v12
	v_mul_f32_e32 v12, 0x4b800000, v9
	v_mul_f32_e32 v20, 0xbfb8aa3b, v20
	v_cndmask_b32_e32 v9, v9, v12, vcc
	v_exp_f32_e32 v20, v20
	v_rsq_f32_e32 v9, v9
	v_lshlrev_b32_e32 v16, 16, v26
	s_waitcnt vmcnt(6)
	v_lshlrev_b32_e32 v21, 16, v29
	v_mul_f32_e32 v16, 0xbfb8aa3b, v16
	v_mul_f32_e32 v21, 0xbfb8aa3b, v21
	s_waitcnt vmcnt(5)
	v_lshlrev_b32_e32 v12, 16, v30
	v_exp_f32_e32 v16, v16
	v_exp_f32_e32 v21, v21
	v_mul_f32_e32 v12, 0xbfb8aa3b, v12
	v_add_f32_e32 v25, 1.0, v20
	v_exp_f32_e32 v20, v12
	v_mul_f32_e32 v12, 0x45800000, v9
	v_lshlrev_b32_e32 v19, 16, v27
	v_cndmask_b32_e32 v27, v9, v12, vcc
	v_mul_f32_e32 v9, v66, v27
	v_add_f32_e32 v24, 1.0, v16
	v_add_f32_e32 v26, 1.0, v21
	s_waitcnt vmcnt(4)
	v_mul_f32_e32 v21, v15, v9
	global_load_dword v16, v[10:11], off offset:320
	global_load_dword v12, v[10:11], off offset:384
	global_load_dword v9, v[10:11], off offset:448
	v_mul_f32_e32 v1, 0xbfb8aa3b, v1
	v_exp_f32_e32 v1, v1
	v_add_f32_e32 v11, 1.0, v20
	v_mul_f32_e32 v19, 0xbfb8aa3b, v19
	v_exp_f32_e32 v19, v19
	v_add_f32_e32 v1, 1.0, v1
	v_div_scale_f32 v28, s[2:3], v1, v1, v21
	v_rcp_f32_e32 v29, v28
	v_add_f32_e32 v19, 1.0, v19
	s_mov_b64 s[80:81], 0x2000
	v_readlane_b32 s82, v254, 30
	v_fma_f32 v10, -v28, v29, 1.0
	v_fmac_f32_e32 v29, v10, v29
	v_div_scale_f32 v10, vcc, v21, v1, v21
	v_mul_f32_e32 v20, v10, v29
	v_fma_f32 v30, -v28, v20, v10
	v_fmac_f32_e32 v20, v30, v29
	v_fma_f32 v10, -v28, v20, v10
	v_div_fmas_f32 v10, v10, v29, v20
	v_div_fixup_f32 v1, v10, v1, v21
	v_mul_f32_e32 v10, v68, v27
	s_waitcnt vmcnt(6)
	v_mul_f32_e32 v10, v18, v10
	v_div_scale_f32 v20, s[2:3], v22, v22, v10
	v_rcp_f32_e32 v21, v20
	s_nop 0
	v_cvt_pk_bf16_f32 v1, v1, v1
	global_store_short v[6:7], v1, off
	v_fma_f32 v1, -v20, v21, 1.0
	v_fmac_f32_e32 v21, v1, v21
	v_div_scale_f32 v1, vcc, v10, v22, v10
	v_mul_f32_e32 v28, v1, v21
	v_fma_f32 v29, -v20, v28, v1
	v_fmac_f32_e32 v28, v29, v21
	v_fma_f32 v1, -v20, v28, v1
	v_div_fmas_f32 v1, v1, v21, v28
	v_div_fixup_f32 v1, v1, v22, v10
	v_mul_f32_e32 v10, v75, v27
	s_waitcnt vmcnt(6)
	v_mul_f32_e32 v10, v17, v10
	v_div_scale_f32 v20, s[2:3], v23, v23, v10
	v_rcp_f32_e32 v21, v20
	s_nop 0
	v_cvt_pk_bf16_f32 v1, v1, v1
	global_store_short v[6:7], v1, off offset:32
	v_fma_f32 v1, -v20, v21, 1.0
	v_fmac_f32_e32 v21, v1, v21
	v_div_scale_f32 v1, vcc, v10, v23, v10
	v_mul_f32_e32 v22, v1, v21
	v_fma_f32 v28, -v20, v22, v1
	v_fmac_f32_e32 v22, v28, v21
	v_fma_f32 v1, -v20, v22, v1
	v_div_fmas_f32 v1, v1, v21, v22
	v_div_fixup_f32 v1, v1, v23, v10
	v_mul_f32_e32 v10, v74, v27
	s_waitcnt vmcnt(6)
	v_mul_f32_e32 v10, v13, v10
	v_div_scale_f32 v20, s[2:3], v24, v24, v10
	v_rcp_f32_e32 v21, v20
	s_nop 0
	v_cvt_pk_bf16_f32 v1, v1, v1
	global_store_short v[6:7], v1, off offset:64
	v_fma_f32 v1, -v20, v21, 1.0
	v_fmac_f32_e32 v21, v1, v21
	v_div_scale_f32 v1, vcc, v10, v24, v10
	v_mul_f32_e32 v22, v1, v21
	v_fma_f32 v23, -v20, v22, v1
	v_fmac_f32_e32 v22, v23, v21
	v_fma_f32 v1, -v20, v22, v1
	v_div_fmas_f32 v1, v1, v21, v22
	v_div_fixup_f32 v1, v1, v24, v10
	v_mul_f32_e32 v10, v73, v27
	s_waitcnt vmcnt(6)
	v_mul_f32_e32 v22, v10, v14
	v_div_scale_f32 v23, s[2:3], v19, v19, v22
	v_rcp_f32_e32 v24, v23
	s_nop 0
	v_cvt_pk_bf16_f32 v1, v1, v1
	v_or_b32_e32 v10, 1, v0
	v_mad_i64_i32 v[20:21], s[2:3], v10, s91, v[2:3]
	v_lshl_add_u64 v[20:21], v[20:21], 0, v[178:179]
	global_store_short v[6:7], v1, off offset:96
	v_fma_f32 v1, -v23, v24, 1.0
	global_load_ushort v28, v[20:21], off
	v_fmac_f32_e32 v24, v1, v24
	v_div_scale_f32 v1, vcc, v22, v19, v22
	v_mul_f32_e32 v29, v1, v24
	v_fma_f32 v30, -v23, v29, v1
	v_fmac_f32_e32 v29, v30, v24
	v_fma_f32 v1, -v23, v29, v1
	v_div_fmas_f32 v1, v1, v24, v29
	v_div_fixup_f32 v1, v1, v19, v22
	v_mul_f32_e32 v19, v72, v27
	s_waitcnt vmcnt(7)
	v_mul_f32_e32 v19, v19, v16
	v_div_scale_f32 v22, s[2:3], v25, v25, v19
	v_rcp_f32_e32 v23, v22
	s_nop 0
	v_cvt_pk_bf16_f32 v1, v1, v1
	global_store_short v[6:7], v1, off offset:128
	v_fma_f32 v1, -v22, v23, 1.0
	v_fmac_f32_e32 v23, v1, v23
	v_div_scale_f32 v1, vcc, v19, v25, v19
	v_mul_f32_e32 v24, v1, v23
	v_fma_f32 v29, -v22, v24, v1
	v_fmac_f32_e32 v24, v29, v23
	v_fma_f32 v1, -v22, v24, v1
	global_load_ushort v22, v[20:21], off offset:32
	v_div_fmas_f32 v1, v1, v23, v24
	v_div_fixup_f32 v1, v1, v25, v19
	v_mul_f32_e32 v19, v71, v27
	s_waitcnt vmcnt(8)
	v_mul_f32_e32 v19, v19, v12
	v_div_scale_f32 v23, s[2:3], v26, v26, v19
	v_rcp_f32_e32 v24, v23
	s_nop 0
	v_cvt_pk_bf16_f32 v1, v1, v1
	global_store_short v[6:7], v1, off offset:160
	v_fma_f32 v1, -v23, v24, 1.0
	v_fmac_f32_e32 v24, v1, v24
	v_div_scale_f32 v1, vcc, v19, v26, v19
	v_mul_f32_e32 v25, v1, v24
	v_fma_f32 v29, -v23, v25, v1
	v_fmac_f32_e32 v25, v29, v24
	v_fma_f32 v1, -v23, v25, v1
	v_div_fmas_f32 v1, v1, v24, v25
	v_div_fixup_f32 v1, v1, v26, v19
	global_load_ushort v19, v[20:21], off offset:64
	v_mul_f32_e32 v23, v70, v27
	s_waitcnt vmcnt(9)
	v_mul_f32_e32 v23, v23, v9
	v_div_scale_f32 v24, s[2:3], v11, v11, v23
	v_rcp_f32_e32 v25, v24
	s_nop 0
	v_cvt_pk_bf16_f32 v1, v1, v1
	global_store_short v[6:7], v1, off offset:192
	v_fma_f32 v1, -v24, v25, 1.0
	v_fmac_f32_e32 v25, v1, v25
	v_div_scale_f32 v1, vcc, v23, v11, v23
	v_mul_f32_e32 v26, v1, v25
	v_fma_f32 v27, -v24, v26, v1
	v_fmac_f32_e32 v26, v27, v25
	v_fma_f32 v1, -v24, v26, v1
	v_div_fmas_f32 v1, v1, v25, v26
	v_div_fixup_f32 v1, v1, v11, v23
	global_load_ushort v23, v[20:21], off offset:96
	v_mul_f32_e32 v11, 0x4b800000, v8
	v_cmp_gt_f32_e32 vcc, s88, v8
	v_readlane_b32 s13, v254, 44
	v_readlane_b32 s83, v254, 31
	v_cndmask_b32_e32 v8, v8, v11, vcc
	s_nop 0
	v_cvt_pk_bf16_f32 v1, v1, v1
	global_store_short v[6:7], v1, off offset:224
	global_load_ushort v24, v[20:21], off offset:128
	global_load_ushort v25, v[20:21], off offset:160
	global_load_ushort v26, v[20:21], off offset:192
	global_load_ushort v27, v[20:21], off offset:224
	v_rsq_f32_e32 v8, v8
	v_ashrrev_i32_e32 v11, 31, v10
	s_waitcnt vmcnt(11)
	v_lshlrev_b32_e32 v6, 16, v28
	v_mul_f32_e32 v6, 0xbfb8aa3b, v6
	v_exp_f32_e32 v6, v6
	v_mul_f32_e32 v1, 0x45800000, v8
	v_cndmask_b32_e32 v1, v8, v1, vcc
	v_mul_f32_e32 v7, v67, v1
	v_mul_f32_e32 v8, v15, v7
	v_add_f32_e32 v20, 1.0, v6
	v_div_scale_f32 v21, s[2:3], v20, v20, v8
	v_rcp_f32_e32 v28, v21
	v_lshlrev_b64 v[6:7], 12, v[10:11]
	v_lshl_add_u64 v[6:7], s[0:1], 0, v[6:7]
	v_lshl_add_u64 v[6:7], v[6:7], 0, v[178:179]
	v_fma_f32 v10, -v21, v28, 1.0
	v_fmac_f32_e32 v28, v10, v28
	v_div_scale_f32 v10, vcc, v8, v20, v8
	v_mul_f32_e32 v11, v10, v28
	v_fma_f32 v29, -v21, v11, v10
	v_fmac_f32_e32 v11, v29, v28
	v_fma_f32 v10, -v21, v11, v10
	v_div_fmas_f32 v10, v10, v28, v11
	v_div_fixup_f32 v8, v10, v20, v8
	v_mul_f32_e32 v20, v69, v1
	v_mul_f32_e32 v20, v18, v20
	s_waitcnt vmcnt(9)
	v_lshlrev_b32_e32 v10, 16, v22
	v_mul_f32_e32 v10, 0xbfb8aa3b, v10
	v_exp_f32_e32 v10, v10
	s_nop 0
	v_cvt_pk_bf16_f32 v8, v8, v8
	global_store_short v[6:7], v8, off
	v_add_f32_e32 v10, 1.0, v10
	v_div_scale_f32 v21, s[2:3], v10, v10, v20
	v_rcp_f32_e32 v22, v21
	s_nop 0
	v_fma_f32 v8, -v21, v22, 1.0
	v_fmac_f32_e32 v22, v8, v22
	v_div_scale_f32 v8, vcc, v20, v10, v20
	v_mul_f32_e32 v11, v8, v22
	v_fma_f32 v28, -v21, v11, v8
	v_fmac_f32_e32 v11, v28, v22
	v_fma_f32 v8, -v21, v11, v8
	v_div_fmas_f32 v8, v8, v22, v11
	s_waitcnt vmcnt(8)
	v_lshlrev_b32_e32 v11, 16, v19
	v_mul_f32_e32 v11, 0xbfb8aa3b, v11
	v_exp_f32_e32 v11, v11
	v_div_fixup_f32 v8, v8, v10, v20
	v_mul_f32_e32 v10, v65, v1
	v_mul_f32_e32 v10, v17, v10
	v_add_f32_e32 v11, 1.0, v11
	v_div_scale_f32 v19, s[2:3], v11, v11, v10
	v_rcp_f32_e32 v20, v19
	s_nop 0
	v_cvt_pk_bf16_f32 v8, v8, v8
	global_store_short v[6:7], v8, off offset:32
	v_fma_f32 v8, -v19, v20, 1.0
	v_fmac_f32_e32 v20, v8, v20
	v_div_scale_f32 v8, vcc, v10, v11, v10
	v_mul_f32_e32 v21, v8, v20
	v_fma_f32 v22, -v19, v21, v8
	v_fmac_f32_e32 v21, v22, v20
	v_fma_f32 v8, -v19, v21, v8
	s_waitcnt vmcnt(7)
	v_lshlrev_b32_e32 v19, 16, v23
	v_mul_f32_e32 v19, 0xbfb8aa3b, v19
	v_exp_f32_e32 v19, v19
	v_div_fmas_f32 v8, v8, v20, v21
	v_div_fixup_f32 v8, v8, v11, v10
	v_mul_f32_e32 v10, v64, v1
	v_mul_f32_e32 v10, v13, v10
	v_add_f32_e32 v11, 1.0, v19
	v_div_scale_f32 v19, s[2:3], v11, v11, v10
	v_rcp_f32_e32 v20, v19
	s_nop 0
	v_cvt_pk_bf16_f32 v8, v8, v8
	global_store_short v[6:7], v8, off offset:64
	v_fma_f32 v8, -v19, v20, 1.0
	v_fmac_f32_e32 v20, v8, v20
	v_div_scale_f32 v8, vcc, v10, v11, v10
	v_mul_f32_e32 v21, v8, v20
	v_fma_f32 v22, -v19, v21, v8
	v_fmac_f32_e32 v21, v22, v20
	v_fma_f32 v8, -v19, v21, v8
	s_waitcnt vmcnt(6)
	v_lshlrev_b32_e32 v19, 16, v24
	v_mul_f32_e32 v19, 0xbfb8aa3b, v19
	v_exp_f32_e32 v19, v19
	v_div_fmas_f32 v8, v8, v20, v21
	v_div_fixup_f32 v8, v8, v11, v10
	v_mul_f32_e32 v10, v63, v1
	v_mul_f32_e32 v10, v14, v10
	v_add_f32_e32 v11, 1.0, v19
	v_div_scale_f32 v19, s[2:3], v11, v11, v10
	v_rcp_f32_e32 v20, v19
	s_nop 0
	v_cvt_pk_bf16_f32 v8, v8, v8
	global_store_short v[6:7], v8, off offset:96
	v_fma_f32 v8, -v19, v20, 1.0
	v_fmac_f32_e32 v20, v8, v20
	v_div_scale_f32 v8, vcc, v10, v11, v10
	v_mul_f32_e32 v21, v8, v20
	v_fma_f32 v22, -v19, v21, v8
	v_fmac_f32_e32 v21, v22, v20
	v_fma_f32 v8, -v19, v21, v8
	v_div_fmas_f32 v8, v8, v20, v21
	v_div_fixup_f32 v8, v8, v11, v10
	v_mul_f32_e32 v10, v62, v1
	v_mul_f32_e32 v11, v16, v10
	s_nop 0
	v_cvt_pk_bf16_f32 v8, v8, v8
	v_or_b32_e32 v10, 2, v0
	v_mad_i64_i32 v[20:21], s[2:3], v10, s91, v[2:3]
	v_lshl_add_u64 v[20:21], v[20:21], 0, v[178:179]
	global_load_ushort v28, v[20:21], off
	global_load_ushort v29, v[20:21], off offset:32
	global_load_ushort v30, v[20:21], off offset:64
	global_load_ushort v34, v[20:21], off offset:96
	s_waitcnt vmcnt(10)
	v_lshlrev_b32_e32 v19, 16, v25
	v_mul_f32_e32 v19, 0xbfb8aa3b, v19
	v_exp_f32_e32 v19, v19
	global_store_short v[6:7], v8, off offset:128
	v_or_b32_e32 v0, 3, v0
	v_mad_i64_i32 v[2:3], s[2:3], v0, s91, v[2:3]
	v_add_f32_e32 v19, 1.0, v19
	v_div_scale_f32 v22, s[2:3], v19, v19, v11
	v_rcp_f32_e32 v23, v22
	v_lshl_add_u64 v[2:3], v[2:3], 0, v[178:179]
	v_fma_f32 v8, -v22, v23, 1.0
	v_fmac_f32_e32 v23, v8, v23
	v_div_scale_f32 v8, vcc, v11, v19, v11
	v_mul_f32_e32 v24, v8, v23
	v_fma_f32 v25, -v22, v24, v8
	v_fmac_f32_e32 v24, v25, v23
	v_fma_f32 v8, -v22, v24, v8
	s_waitcnt vmcnt(10)
	v_lshlrev_b32_e32 v22, 16, v26
	v_mul_f32_e32 v22, 0xbfb8aa3b, v22
	v_exp_f32_e32 v22, v22
	v_div_fmas_f32 v8, v8, v23, v24
	v_div_fixup_f32 v8, v8, v19, v11
	v_mul_f32_e32 v11, v61, v1
	v_mul_f32_e32 v11, v12, v11
	v_add_f32_e32 v19, 1.0, v22
	v_div_scale_f32 v22, s[2:3], v19, v19, v11
	v_rcp_f32_e32 v23, v22
	s_nop 0
	v_cvt_pk_bf16_f32 v8, v8, v8
	global_store_short v[6:7], v8, off offset:160
	v_fma_f32 v8, -v22, v23, 1.0
	v_fmac_f32_e32 v23, v8, v23
	v_div_scale_f32 v8, vcc, v11, v19, v11
	v_mul_f32_e32 v24, v8, v23
	v_fma_f32 v25, -v22, v24, v8
	v_fmac_f32_e32 v24, v25, v23
	v_fma_f32 v8, -v22, v24, v8
	v_div_fmas_f32 v8, v8, v23, v24
	v_div_fixup_f32 v8, v8, v19, v11
	s_nop 0
	v_cvt_pk_bf16_f32 v8, v8, v8
	global_store_short v[6:7], v8, off offset:192
	global_load_ushort v19, v[20:21], off offset:128
	global_load_ushort v35, v[20:21], off offset:160
	global_load_ushort v36, v[20:21], off offset:192
	s_waitcnt vmcnt(14)
	v_lshlrev_b32_e32 v22, 16, v27
	v_mul_f32_e32 v22, 0xbfb8aa3b, v22
	v_exp_f32_e32 v22, v22
	v_mul_f32_e32 v1, v60, v1
	v_mul_f32_e32 v1, v9, v1
	v_pk_mul_f32 v[26:27], v[54:55], v[54:55]
	v_add_f32_e32 v11, 1.0, v22
	v_div_scale_f32 v22, s[2:3], v11, v11, v1
	v_rcp_f32_e32 v23, v22
	s_nop 0
	v_fma_f32 v8, -v22, v23, 1.0
	v_fmac_f32_e32 v23, v8, v23
	v_div_scale_f32 v8, vcc, v1, v11, v1
	v_mul_f32_e32 v24, v8, v23
	v_fma_f32 v25, -v22, v24, v8
	v_fmac_f32_e32 v24, v25, v23
	v_fma_f32 v8, -v22, v24, v8
	v_div_fmas_f32 v8, v8, v23, v24
	v_div_fixup_f32 v1, v8, v11, v1
	s_nop 0
	v_cvt_pk_bf16_f32 v1, v1, v1
	global_store_short v[6:7], v1, off offset:224
	global_load_ushort v1, v[20:21], off offset:224
	s_waitcnt vmcnt(11)
	v_lshlrev_b32_e32 v6, 16, v28
	v_mul_f32_e32 v6, 0xbfb8aa3b, v6
	v_ashrrev_i32_e32 v11, 31, v10
	v_exp_f32_e32 v8, v6
	v_lshlrev_b64 v[6:7], 12, v[10:11]
	s_waitcnt vmcnt(10)
	v_lshlrev_b32_e32 v10, 16, v29
	v_mul_f32_e32 v10, 0xbfb8aa3b, v10
	v_exp_f32_e32 v37, v10
	s_waitcnt vmcnt(9)
	v_lshlrev_b32_e32 v10, 16, v30
	v_mul_f32_e32 v10, 0xbfb8aa3b, v10
	v_pk_mul_f32 v[20:21], v[50:51], v[50:51]
	v_pk_mul_f32 v[22:23], v[58:59], v[58:59]
	v_exp_f32_e32 v38, v10
	v_pk_mul_f32 v[10:11], v[48:49], v[48:49]
	v_pk_fma_f32 v[20:21], v[52:53], v[52:53], v[20:21]
	v_mov_b32_e32 v33, v22
	v_mov_b32_e32 v22, v11
	v_pk_mul_f32 v[24:25], v[56:57], v[56:57]
	v_pk_mul_f32 v[28:29], v[46:47], v[46:47]
	v_mov_b32_e32 v32, v10
	v_pk_add_f32 v[10:11], v[22:23], v[20:21] op_sel:[0,1] op_sel_hi:[1,0]
	v_mov_b32_e32 v20, v29
	v_pk_add_f32 v[10:11], v[32:33], v[10:11]
	v_mov_b32_e32 v21, v25
	v_pk_mul_f32 v[30:31], v[44:45], v[44:45]
	v_pk_add_f32 v[10:11], v[20:21], v[10:11]
	v_mov_b32_e32 v29, v24
	v_pk_add_f32 v[10:11], v[28:29], v[10:11]
	v_mov_b32_e32 v20, v31
	v_mov_b32_e32 v21, v27
	v_pk_add_f32 v[10:11], v[20:21], v[10:11]
	v_mov_b32_e32 v31, v26
	v_pk_add_f32 v[10:11], v[30:31], v[10:11]
	ds_bpermute_b32 v21, v191, v11
	ds_bpermute_b32 v20, v191, v10
	v_add_f32_e32 v8, 1.0, v8
	v_add_f32_e32 v22, 1.0, v37
	v_lshl_add_u64 v[6:7], s[0:1], 0, v[6:7]
	v_lshl_add_u64 v[6:7], v[6:7], 0, v[178:179]
	s_waitcnt lgkmcnt(0)
	v_pk_add_f32 v[10:11], v[10:11], v[20:21]
	ds_bpermute_b32 v21, v192, v11
	ds_bpermute_b32 v20, v192, v10
	v_add_f32_e32 v23, 1.0, v38
	s_waitcnt vmcnt(8)
	v_lshlrev_b32_e32 v24, 16, v34
	v_mul_f32_e32 v24, 0xbfb8aa3b, v24
	v_exp_f32_e32 v24, v24
	s_waitcnt lgkmcnt(0)
	v_pk_add_f32 v[10:11], v[10:11], v[20:21]
	ds_bpermute_b32 v21, v193, v11
	ds_bpermute_b32 v20, v193, v10
	v_add_f32_e32 v24, 1.0, v24
	s_waitcnt vmcnt(4)
	v_lshlrev_b32_e32 v19, 16, v19
	s_waitcnt vmcnt(3)
	v_lshlrev_b32_e32 v25, 16, v35
	s_waitcnt vmcnt(2)
	v_lshlrev_b32_e32 v26, 16, v36
	s_waitcnt lgkmcnt(0)
	v_pk_add_f32 v[10:11], v[10:11], v[20:21]
	ds_bpermute_b32 v21, v194, v11
	ds_bpermute_b32 v20, v194, v10
	v_mul_f32_e32 v25, 0xbfb8aa3b, v25
	v_mul_f32_e32 v26, 0xbfb8aa3b, v26
	v_exp_f32_e32 v25, v25
	v_exp_f32_e32 v26, v26
	s_waitcnt lgkmcnt(0)
	v_pk_add_f32 v[10:11], v[10:11], v[20:21]
	v_mul_f32_e32 v19, 0xbfb8aa3b, v19
	v_pk_fma_f32 v[4:5], v[10:11], s[4:5], v[4:5] op_sel_hi:[1,0,0]
	v_add_f32_e32 v21, 1.0, v25
	v_mul_f32_e32 v10, 0x4b800000, v5
	v_cmp_gt_f32_e32 vcc, s88, v5
	v_add_f32_e32 v25, 1.0, v26
	v_exp_f32_e32 v19, v19
	v_cndmask_b32_e32 v5, v5, v10, vcc
	v_rsq_f32_e32 v5, v5
	v_add_f32_e32 v19, 1.0, v19
	v_mul_f32_e32 v10, 0x45800000, v5
	v_cndmask_b32_e32 v5, v5, v10, vcc
	v_mul_f32_e32 v10, v52, v5
	v_mul_f32_e32 v10, v15, v10
	v_div_scale_f32 v11, s[2:3], v8, v8, v10
	v_rcp_f32_e32 v20, v11
	s_waitcnt vmcnt(0)
	v_lshlrev_b32_e32 v1, 16, v1
	v_mul_f32_e32 v1, 0xbfb8aa3b, v1
	v_exp_f32_e32 v1, v1
	v_fma_f32 v26, -v11, v20, 1.0
	v_fmac_f32_e32 v20, v26, v20
	v_div_scale_f32 v26, vcc, v10, v8, v10
	v_mul_f32_e32 v27, v26, v20
	v_fma_f32 v28, -v11, v27, v26
	v_fmac_f32_e32 v27, v28, v20
	v_fma_f32 v11, -v11, v27, v26
	v_div_fmas_f32 v11, v11, v20, v27
	v_div_fixup_f32 v8, v11, v8, v10
	v_mul_f32_e32 v10, v50, v5
	v_mul_f32_e32 v10, v18, v10
	v_div_scale_f32 v11, s[2:3], v22, v22, v10
	v_rcp_f32_e32 v20, v11
	s_nop 0
	v_cvt_pk_bf16_f32 v8, v8, v8
	global_store_short v[6:7], v8, off
	v_fma_f32 v8, -v11, v20, 1.0
	v_fmac_f32_e32 v20, v8, v20
	v_div_scale_f32 v8, vcc, v10, v22, v10
	v_mul_f32_e32 v26, v8, v20
	v_fma_f32 v27, -v11, v26, v8
	v_fmac_f32_e32 v26, v27, v20
	v_fma_f32 v8, -v11, v26, v8
	v_div_fmas_f32 v8, v8, v20, v26
	v_div_fixup_f32 v8, v8, v22, v10
	v_mul_f32_e32 v10, v59, v5
	v_mul_f32_e32 v10, v17, v10
	v_div_scale_f32 v11, s[2:3], v23, v23, v10
	v_rcp_f32_e32 v20, v11
	s_nop 0
	v_cvt_pk_bf16_f32 v8, v8, v8
	global_store_short v[6:7], v8, off offset:32
	v_fma_f32 v8, -v11, v20, 1.0
	v_fmac_f32_e32 v20, v8, v20
	v_div_scale_f32 v8, vcc, v10, v23, v10
	v_mul_f32_e32 v22, v8, v20
	v_fma_f32 v26, -v11, v22, v8
	v_fmac_f32_e32 v22, v26, v20
	v_fma_f32 v8, -v11, v22, v8
	v_div_fmas_f32 v8, v8, v20, v22
	v_div_fixup_f32 v8, v8, v23, v10
	v_mul_f32_e32 v10, v58, v5
	v_mul_f32_e32 v10, v13, v10
	v_div_scale_f32 v11, s[2:3], v24, v24, v10
	v_rcp_f32_e32 v20, v11
	s_nop 0
	v_cvt_pk_bf16_f32 v8, v8, v8
	global_store_short v[6:7], v8, off offset:64
	v_fma_f32 v8, -v11, v20, 1.0
	v_fmac_f32_e32 v20, v8, v20
	v_div_scale_f32 v8, vcc, v10, v24, v10
	v_mul_f32_e32 v22, v8, v20
	v_fma_f32 v23, -v11, v22, v8
	v_fmac_f32_e32 v22, v23, v20
	v_fma_f32 v8, -v11, v22, v8
	v_div_fmas_f32 v8, v8, v20, v22
	v_div_fixup_f32 v8, v8, v24, v10
	v_mul_f32_e32 v10, v57, v5
	v_mul_f32_e32 v10, v14, v10
	v_div_scale_f32 v11, s[2:3], v19, v19, v10
	v_rcp_f32_e32 v20, v11
	s_nop 0
	v_cvt_pk_bf16_f32 v8, v8, v8
	global_store_short v[6:7], v8, off offset:96
	v_fma_f32 v8, -v11, v20, 1.0
	v_fmac_f32_e32 v20, v8, v20
	v_div_scale_f32 v8, vcc, v10, v19, v10
	v_mul_f32_e32 v23, v8, v20
	v_fma_f32 v24, -v11, v23, v8
	v_fmac_f32_e32 v23, v24, v20
	v_fma_f32 v8, -v11, v23, v8
	v_div_fmas_f32 v8, v8, v20, v23
	global_load_ushort v22, v[2:3], off
	v_div_fixup_f32 v8, v8, v19, v10
	v_mul_f32_e32 v10, v56, v5
	v_mul_f32_e32 v10, v16, v10
	v_div_scale_f32 v11, s[2:3], v21, v21, v10
	v_rcp_f32_e32 v19, v11
	s_nop 0
	v_cvt_pk_bf16_f32 v8, v8, v8
	global_store_short v[6:7], v8, off offset:128
	v_fma_f32 v8, -v11, v19, 1.0
	v_fmac_f32_e32 v19, v8, v19
	v_div_scale_f32 v8, vcc, v10, v21, v10
	v_mul_f32_e32 v20, v8, v19
	v_fma_f32 v23, -v11, v20, v8
	v_fmac_f32_e32 v20, v23, v19
	v_fma_f32 v8, -v11, v20, v8
	v_div_fmas_f32 v8, v8, v19, v20
	global_load_ushort v11, v[2:3], off offset:32
	v_div_fixup_f32 v8, v8, v21, v10
	v_mul_f32_e32 v10, v55, v5
	v_mul_f32_e32 v10, v12, v10
	v_div_scale_f32 v19, s[2:3], v25, v25, v10
	v_rcp_f32_e32 v20, v19
	s_nop 0
	v_cvt_pk_bf16_f32 v8, v8, v8
	global_store_short v[6:7], v8, off offset:160
	v_fma_f32 v8, -v19, v20, 1.0
	v_fmac_f32_e32 v20, v8, v20
	v_div_scale_f32 v8, vcc, v10, v25, v10
	v_mul_f32_e32 v21, v8, v20
	v_fma_f32 v23, -v19, v21, v8
	v_fmac_f32_e32 v21, v23, v20
	v_fma_f32 v8, -v19, v21, v8
	v_div_fmas_f32 v8, v8, v20, v21
	v_mul_f32_e32 v5, v54, v5
	v_add_f32_e32 v1, 1.0, v1
	v_div_fixup_f32 v8, v8, v25, v10
	global_load_ushort v10, v[2:3], off offset:64
	v_mul_f32_e32 v5, v9, v5
	v_div_scale_f32 v19, s[2:3], v1, v1, v5
	v_rcp_f32_e32 v20, v19
	s_nop 0
	v_cvt_pk_bf16_f32 v8, v8, v8
	global_store_short v[6:7], v8, off offset:192
	v_fma_f32 v8, -v19, v20, 1.0
	v_fmac_f32_e32 v20, v8, v20
	v_div_scale_f32 v8, vcc, v5, v1, v5
	v_mul_f32_e32 v21, v8, v20
	v_fma_f32 v23, -v19, v21, v8
	v_fmac_f32_e32 v21, v23, v20
	v_fma_f32 v8, -v19, v21, v8
	v_div_fmas_f32 v8, v8, v20, v21
	v_div_fixup_f32 v1, v8, v1, v5
	v_mul_f32_e32 v5, 0x4b800000, v4
	v_cmp_gt_f32_e32 vcc, s88, v4
	s_nop 0
	v_cvt_pk_bf16_f32 v1, v1, v1
	v_cndmask_b32_e32 v4, v4, v5, vcc
	global_load_ushort v5, v[2:3], off offset:96
	v_rsq_f32_e32 v4, v4
	global_store_short v[6:7], v1, off offset:224
	global_load_ushort v6, v[2:3], off offset:128
	s_nop 0
	global_load_ushort v7, v[2:3], off offset:160
	global_load_ushort v8, v[2:3], off offset:192
	s_nop 0
	global_load_ushort v2, v[2:3], off offset:224
	v_mul_f32_e32 v1, 0x45800000, v4
	v_cndmask_b32_e32 v4, v4, v1, vcc
	v_mul_f32_e32 v1, v53, v4
	v_mul_f32_e32 v15, v15, v1
	v_ashrrev_i32_e32 v1, 31, v0
	v_lshlrev_b64 v[0:1], 12, v[0:1]
	v_lshl_add_u64 v[0:1], s[0:1], 0, v[0:1]
	v_lshl_add_u64 v[0:1], v[0:1], 0, v[178:179]
	s_waitcnt vmcnt(11)
	v_lshlrev_b32_e32 v3, 16, v22
	v_mul_f32_e32 v3, 0xbfb8aa3b, v3
	v_exp_f32_e32 v3, v3
	s_waitcnt vmcnt(9)
	v_lshlrev_b32_e32 v11, 16, v11
	v_add_f32_e32 v3, 1.0, v3
	v_div_scale_f32 v19, s[2:3], v3, v3, v15
	v_rcp_f32_e32 v20, v19
	v_mul_f32_e32 v11, 0xbfb8aa3b, v11
	v_exp_f32_e32 v11, v11
	v_fma_f32 v21, -v19, v20, 1.0
	v_fmac_f32_e32 v20, v21, v20
	v_div_scale_f32 v21, vcc, v15, v3, v15
	v_mul_f32_e32 v22, v21, v20
	v_fma_f32 v23, -v19, v22, v21
	v_fmac_f32_e32 v22, v23, v20
	v_fma_f32 v19, -v19, v22, v21
	v_div_fmas_f32 v19, v19, v20, v22
	v_div_fixup_f32 v3, v19, v3, v15
	v_mul_f32_e32 v19, v51, v4
	v_mul_f32_e32 v18, v18, v19
	v_add_f32_e32 v11, 1.0, v11
	v_div_scale_f32 v19, s[0:1], v11, v11, v18
	v_rcp_f32_e32 v20, v19
	s_nop 0
	v_cvt_pk_bf16_f32 v3, v3, v3
	global_store_short v[0:1], v3, off
	v_fma_f32 v3, -v19, v20, 1.0
	v_fmac_f32_e32 v20, v3, v20
	v_div_scale_f32 v3, vcc, v18, v11, v18
	v_mul_f32_e32 v15, v3, v20
	s_waitcnt vmcnt(8)
	v_lshlrev_b32_e32 v10, 16, v10
	v_fma_f32 v21, -v19, v15, v3
	v_mul_f32_e32 v10, 0xbfb8aa3b, v10
	v_fmac_f32_e32 v15, v21, v20
	v_exp_f32_e32 v10, v10
	v_fma_f32 v3, -v19, v15, v3
	v_div_fmas_f32 v3, v3, v20, v15
	v_div_fixup_f32 v3, v3, v11, v18
	v_mul_f32_e32 v11, v49, v4
	v_mul_f32_e32 v11, v17, v11
	v_add_f32_e32 v10, 1.0, v10
	v_div_scale_f32 v15, s[0:1], v10, v10, v11
	v_rcp_f32_e32 v17, v15
	s_nop 0
	v_cvt_pk_bf16_f32 v3, v3, v3
	global_store_short v[0:1], v3, off offset:32
	v_fma_f32 v3, -v15, v17, 1.0
	v_fmac_f32_e32 v17, v3, v17
	v_div_scale_f32 v3, vcc, v11, v10, v11
	v_mul_f32_e32 v18, v3, v17
	s_waitcnt vmcnt(7)
	v_lshlrev_b32_e32 v5, 16, v5
	v_fma_f32 v19, -v15, v18, v3
	v_mul_f32_e32 v5, 0xbfb8aa3b, v5
	v_fmac_f32_e32 v18, v19, v17
	v_exp_f32_e32 v5, v5
	v_fma_f32 v3, -v15, v18, v3
	v_div_fmas_f32 v3, v3, v17, v18
	v_div_fixup_f32 v3, v3, v10, v11
	v_mul_f32_e32 v10, v48, v4
	v_mul_f32_e32 v10, v13, v10
	v_add_f32_e32 v5, 1.0, v5
	v_div_scale_f32 v11, s[0:1], v5, v5, v10
	v_rcp_f32_e32 v13, v11
	s_nop 0
	v_cvt_pk_bf16_f32 v3, v3, v3
	global_store_short v[0:1], v3, off offset:64
	v_fma_f32 v3, -v11, v13, 1.0
	v_fmac_f32_e32 v13, v3, v13
	v_div_scale_f32 v3, vcc, v10, v5, v10
	v_mul_f32_e32 v15, v3, v13
	s_waitcnt vmcnt(6)
	v_lshlrev_b32_e32 v6, 16, v6
	v_fma_f32 v17, -v11, v15, v3
	v_mul_f32_e32 v6, 0xbfb8aa3b, v6
	v_fmac_f32_e32 v15, v17, v13
	v_exp_f32_e32 v6, v6
	v_fma_f32 v3, -v11, v15, v3
	v_div_fmas_f32 v3, v3, v13, v15
	v_div_fixup_f32 v3, v3, v5, v10
	v_mul_f32_e32 v5, v47, v4
	v_mul_f32_e32 v5, v14, v5
	v_add_f32_e32 v6, 1.0, v6
	v_div_scale_f32 v10, s[0:1], v6, v6, v5
	v_rcp_f32_e32 v11, v10
	s_nop 0
	v_cvt_pk_bf16_f32 v3, v3, v3
	global_store_short v[0:1], v3, off offset:96
	v_fma_f32 v3, -v10, v11, 1.0
	v_fmac_f32_e32 v11, v3, v11
	v_div_scale_f32 v3, vcc, v5, v6, v5
	v_mul_f32_e32 v13, v3, v11
	s_waitcnt vmcnt(6)
	v_lshlrev_b32_e32 v7, 16, v7
	v_fma_f32 v14, -v10, v13, v3
	v_mul_f32_e32 v7, 0xbfb8aa3b, v7
	v_fmac_f32_e32 v13, v14, v11
	v_exp_f32_e32 v7, v7
	v_fma_f32 v3, -v10, v13, v3
	v_div_fmas_f32 v3, v3, v11, v13
	v_div_fixup_f32 v3, v3, v6, v5
	v_mul_f32_e32 v5, v46, v4
	v_mul_f32_e32 v5, v16, v5
	v_add_f32_e32 v6, 1.0, v7
	v_div_scale_f32 v7, s[0:1], v6, v6, v5
	v_rcp_f32_e32 v10, v7
	s_nop 0
	v_cvt_pk_bf16_f32 v3, v3, v3
	global_store_short v[0:1], v3, off offset:128
	v_fma_f32 v3, -v7, v10, 1.0
	v_fmac_f32_e32 v10, v3, v10
	v_div_scale_f32 v3, vcc, v5, v6, v5
	v_mul_f32_e32 v11, v3, v10
	v_fma_f32 v13, -v7, v11, v3
	v_fmac_f32_e32 v11, v13, v10
	v_fma_f32 v3, -v7, v11, v3
	s_waitcnt vmcnt(6)
	v_lshlrev_b32_e32 v7, 16, v8
	v_mul_f32_e32 v7, 0xbfb8aa3b, v7
	v_exp_f32_e32 v7, v7
	v_div_fmas_f32 v3, v3, v10, v11
	v_div_fixup_f32 v3, v3, v6, v5
	v_mul_f32_e32 v5, v45, v4
	v_mul_f32_e32 v5, v12, v5
	v_add_f32_e32 v6, 1.0, v7
	v_div_scale_f32 v7, s[0:1], v6, v6, v5
	v_rcp_f32_e32 v8, v7
	s_nop 0
	v_cvt_pk_bf16_f32 v3, v3, v3
	global_store_short v[0:1], v3, off offset:160
	v_fma_f32 v3, -v7, v8, 1.0
	s_waitcnt vmcnt(6)
	v_lshlrev_b32_e32 v2, 16, v2
	v_fmac_f32_e32 v8, v3, v8
	v_div_scale_f32 v3, vcc, v5, v6, v5
	v_mul_f32_e32 v2, 0xbfb8aa3b, v2
	v_mul_f32_e32 v10, v3, v8
	v_exp_f32_e32 v2, v2
	v_fma_f32 v11, -v7, v10, v3
	v_fmac_f32_e32 v10, v11, v8
	v_fma_f32 v3, -v7, v10, v3
	v_mul_f32_e32 v4, v44, v4
	v_div_fmas_f32 v3, v3, v8, v10
	v_mul_f32_e32 v4, v9, v4
	v_add_f32_e32 v2, 1.0, v2
	v_div_fixup_f32 v3, v3, v6, v5
	v_div_scale_f32 v5, s[0:1], v2, v2, v4
	v_rcp_f32_e32 v6, v5
	s_nop 0
	v_cvt_pk_bf16_f32 v3, v3, v3
	global_store_short v[0:1], v3, off offset:192
	v_fma_f32 v3, -v5, v6, 1.0
	v_fmac_f32_e32 v6, v3, v6
	v_div_scale_f32 v3, vcc, v4, v2, v4
	v_mul_f32_e32 v7, v3, v6
	v_fma_f32 v8, -v5, v7, v3
	v_fmac_f32_e32 v7, v8, v6
	v_fma_f32 v3, -v5, v7, v3
	v_div_fmas_f32 v3, v3, v6, v7
	v_div_fixup_f32 v2, v3, v2, v4
	v_bfe_u32 v3, v2, 16, 1
	v_add3_u32 v2, v2, v3, s65
	s_mov_b64 s[0:1], 0
	global_store_short_d16_hi v[0:1], v2, off offset:224

.LBB0_757:
	s_or_b64 exec, exec, s[0:1]
	s_mov_b64 s[0:1], exec
	v_readlane_b32 s2, v254, 46
	v_readlane_b32 s3, v254, 47
	s_and_b64 s[2:3], s[0:1], s[2:3]
	s_mov_b64 exec, s[2:3]
	s_cbranch_execz .LBB0_759
	s_load_dwordx2 s[2:3], s[14:15], 0x88
	v_readlane_b32 s4, v254, 42
	v_readlane_b32 s5, v254, 43
	s_waitcnt lgkmcnt(0)
	s_add_u32 s2, s2, s4
	s_addc_u32 s3, s3, s5
	s_lshl_b32 s4, s11, 2
	v_mov_b32_e32 v92, s4
	global_load_dword v97, v92, s[2:3]
	global_load_dword v98, v92, s[2:3] offset:16
	global_load_dword v99, v92, s[2:3] offset:32
	global_load_dword v100, v92, s[2:3] offset:48
	v_lshl_add_u32 v92, v105, 2, v223
	s_mov_b32 s2, 0xbfb8aa3b
	v_add_u32_e32 v101, 0x18900, v92
	v_add_u32_e32 v106, 0x18d00, v92
	s_mov_b32 s3, 0x3f2aaaab
	s_mov_b32 s4, 0x3f317218
	s_mov_b32 s5, 0x33800000
	v_add_u32_e32 v103, 0x18b00, v92
	v_add_u32_e32 v92, 0x18f00, v92
	s_waitcnt vmcnt(3)
	v_add_f32_e32 v96, v96, v97
	s_waitcnt vmcnt(2)
	v_add_f32_e32 v95, v95, v98
	v_mul_f32_e64 v97, |v95|, s2
	s_waitcnt vmcnt(0)
	v_add_f32_e32 v93, v93, v100
	v_mul_f32_e64 v98, |v93|, s2
	v_add_f32_e32 v94, v94, v99
	ds_write_b32 v101, v96
	v_fma_f32 v99, |v95|, s2, -v97
	v_rndne_f32_e32 v100, v97
	v_fma_f32 v101, |v93|, s2, -v98
	s_mov_b32 s2, 0xb2a5705f
	v_rndne_f32_e32 v107, v98
	v_fma_f32 v99, |v95|, s2, v99
	v_sub_f32_e32 v97, v97, v100
	v_fma_f32 v101, |v93|, s2, v101
	v_sub_f32_e32 v98, v98, v107
	v_add_f32_e32 v97, v97, v99
	v_cvt_i32_f32_e32 v100, v100
	v_add_f32_e32 v98, v98, v101
	v_exp_f32_e32 v97, v97
	v_cvt_i32_f32_e32 v107, v107
	v_exp_f32_e32 v98, v98
	s_mov_b32 s2, 0x42ce8ed0
	ds_write_b32 v106, v94
	v_ldexp_f32 v94, v97, v100
	v_cmp_ngt_f32_e64 vcc, |v95|, s2
	v_ldexp_f32 v97, v98, v107
	v_min_f32_e32 v99, 0, v93
	v_cndmask_b32_e32 v94, 0, v94, vcc
	v_cmp_ngt_f32_e64 vcc, |v93|, s2
	s_mov_b32 s2, 0xc2b17218
	v_min_f32_e32 v96, 0, v95
	v_cndmask_b32_e32 v97, 0, v97, vcc
	v_cmp_nlt_f32_e64 vcc, |v95|, s2
	s_nop 1
	v_cndmask_b32_e32 v98, v221, v94, vcc
	v_cmp_nlt_f32_e64 vcc, |v93|, s2
	s_mov_b32 s2, 0x7f800000
	s_nop 0
	v_cndmask_b32_e32 v93, v221, v97, vcc
	v_add_f32_e32 v97, 1.0, v98
	v_add_f32_e32 v100, 1.0, v93
	v_frexp_mant_f32_e32 v106, v97
	v_cvt_f64_f32_e32 v[94:95], v97
	v_add_f32_e32 v101, -1.0, v97
	v_add_f32_e32 v107, -1.0, v100
	v_frexp_exp_i32_f64_e32 v94, v[94:95]
	v_cmp_gt_f32_e32 vcc, s3, v106
	v_sub_f32_e32 v108, v101, v97
	v_sub_f32_e32 v95, v107, v100
	v_subbrev_co_u32_e32 v94, vcc, 0, v94, vcc
	v_sub_f32_e32 v101, v98, v101
	v_sub_f32_e32 v107, v93, v107
	v_add_f32_e32 v108, 1.0, v108
	v_add_f32_e32 v95, 1.0, v95
	v_sub_u32_e32 v106, 0, v94
	v_add_f32_e32 v101, v101, v108
	v_cvt_f32_i32_e32 v94, v94
	v_add_f32_e32 v107, v107, v95
	v_ldexp_f32 v95, v97, v106
	v_ldexp_f32 v97, v101, v106
	v_add_f32_e32 v101, -1.0, v95
	v_add_f32_e32 v106, 1.0, v95
	v_add_f32_e32 v108, 1.0, v101
	v_add_f32_e32 v109, -1.0, v106
	v_sub_f32_e32 v108, v95, v108
	v_sub_f32_e32 v95, v95, v109
	v_mul_f32_e32 v109, 0x3f317218, v94
	v_add_f32_e32 v108, v97, v108
	v_add_f32_e32 v95, v97, v95
	v_fma_f32 v97, v94, s4, -v109
	v_add_f32_e32 v110, v101, v108
	v_add_f32_e32 v111, v106, v95
	v_fmac_f32_e32 v97, 0xb102e308, v94
	v_sub_f32_e32 v94, v101, v110
	v_sub_f32_e32 v101, v106, v111
	v_rcp_f32_e32 v106, v111
	v_add_f32_e32 v112, v109, v97
	v_add_f32_e32 v95, v95, v101
	v_sub_f32_e32 v101, v112, v109
	v_sub_f32_e32 v97, v97, v101
	v_mul_f32_e32 v101, v110, v106
	v_add_f32_e32 v94, v108, v94
	v_mul_f32_e32 v108, v111, v101
	v_fma_f32 v109, v101, v111, -v108
	v_fmac_f32_e32 v109, v101, v95
	v_add_f32_e32 v113, v108, v109
	v_sub_f32_e32 v114, v110, v113
	v_sub_f32_e32 v108, v113, v108
	v_sub_f32_e32 v110, v110, v114
	v_sub_f32_e32 v108, v108, v109
	v_sub_f32_e32 v109, v110, v113
	v_add_f32_e32 v94, v94, v109
	v_add_f32_e32 v94, v108, v94
	v_add_f32_e32 v108, v114, v94
	v_mul_f32_e32 v109, v106, v108
	v_sub_f32_e32 v110, v114, v108
	v_mul_f32_e32 v113, v111, v109
	v_add_f32_e32 v94, v94, v110
	v_add_f32_e32 v110, v101, v109
	v_fma_f32 v111, v109, v111, -v113
	v_sub_f32_e32 v101, v110, v101
	v_fmac_f32_e32 v111, v109, v95
	v_sub_f32_e32 v95, v109, v101
	v_add_f32_e32 v101, v113, v111
	v_sub_f32_e32 v109, v101, v113
	v_sub_f32_e32 v113, v108, v101
	v_sub_f32_e32 v108, v108, v113
	v_sub_f32_e32 v101, v108, v101
	v_sub_f32_e32 v109, v109, v111
	v_add_f32_e32 v94, v94, v101
	v_add_f32_e32 v94, v109, v94
	v_add_f32_e32 v94, v113, v94
	v_mul_f32_e32 v94, v106, v94
	v_add_f32_e32 v94, v95, v94
	v_add_f32_e32 v95, v110, v94
	v_mul_f32_e32 v101, v95, v95
	v_fmamk_f32 v109, v101, 0x3e9b6dac, v214
	v_sub_f32_e32 v106, v95, v110
	v_ldexp_f32 v108, v95, 1
	v_mul_f32_e32 v95, v95, v101
	v_fmaak_f32 v101, v101, v109, 0x3f2aaada
	v_mul_f32_e32 v95, v95, v101
	v_add_f32_e32 v101, v108, v95
	v_sub_f32_e32 v94, v94, v106
	v_sub_f32_e32 v106, v101, v108
	v_ldexp_f32 v94, v94, 1
	v_sub_f32_e32 v95, v95, v106
	v_add_f32_e32 v94, v94, v95
	v_add_f32_e32 v95, v101, v94
	v_sub_f32_e32 v101, v95, v101
	v_add_f32_e32 v106, v112, v95
	v_sub_f32_e32 v94, v94, v101
	v_sub_f32_e32 v101, v106, v112
	v_sub_f32_e32 v108, v106, v101
	v_sub_f32_e32 v95, v95, v101
	v_add_f32_e32 v101, v97, v94
	v_sub_f32_e32 v108, v112, v108
	v_sub_f32_e32 v109, v101, v97
	v_add_f32_e32 v95, v95, v108
	v_sub_f32_e32 v108, v101, v109
	v_sub_f32_e32 v94, v94, v109
	v_sub_f32_e32 v97, v97, v108
	v_add_f32_e32 v95, v101, v95
	v_add_f32_e32 v94, v94, v97
	v_add_f32_e32 v97, v106, v95
	v_sub_f32_e32 v101, v97, v106
	v_sub_f32_e32 v95, v95, v101
	v_add_f32_e32 v94, v94, v95
	v_add_f32_e32 v94, v97, v94
	v_cmp_neq_f32_e32 vcc, s2, v98
	s_nop 1
	v_cndmask_b32_e32 v94, v221, v94, vcc
	v_cmp_lt_f32_e64 vcc, |v98|, s5
	s_nop 1
	v_cndmask_b32_e32 v94, v94, v98, vcc
	v_sub_f32_e32 v94, v96, v94
	ds_write_b32 v103, v94
	v_frexp_mant_f32_e32 v96, v100
	v_cvt_f64_f32_e32 v[94:95], v100
	v_frexp_exp_i32_f64_e32 v94, v[94:95]
	v_cmp_gt_f32_e32 vcc, s3, v96
	s_nop 1
	v_subbrev_co_u32_e32 v94, vcc, 0, v94, vcc
	v_sub_u32_e32 v95, 0, v94
	v_ldexp_f32 v96, v100, v95
	v_add_f32_e32 v97, -1.0, v96
	v_add_f32_e32 v101, 1.0, v96
	v_add_f32_e32 v98, 1.0, v97
	v_add_f32_e32 v103, -1.0, v101
	v_ldexp_f32 v95, v107, v95
	v_sub_f32_e32 v98, v96, v98
	v_sub_f32_e32 v96, v96, v103
	v_add_f32_e32 v98, v95, v98
	v_add_f32_e32 v95, v95, v96
	v_add_f32_e32 v96, v101, v95
	v_rcp_f32_e32 v103, v96
	v_add_f32_e32 v100, v97, v98
	v_sub_f32_e32 v97, v97, v100
	v_add_f32_e32 v97, v98, v97
	v_sub_f32_e32 v98, v101, v96
	v_add_f32_e32 v95, v95, v98
	v_mul_f32_e32 v98, v100, v103
	v_mul_f32_e32 v101, v96, v98
	v_fma_f32 v106, v98, v96, -v101
	v_fmac_f32_e32 v106, v98, v95
	v_add_f32_e32 v107, v101, v106
	v_sub_f32_e32 v108, v100, v107
	v_sub_f32_e32 v100, v100, v108
	v_sub_f32_e32 v101, v107, v101
	v_sub_f32_e32 v100, v100, v107
	v_add_f32_e32 v97, v97, v100
	v_sub_f32_e32 v100, v101, v106
	v_add_f32_e32 v97, v100, v97
	v_add_f32_e32 v100, v108, v97
	v_mul_f32_e32 v101, v103, v100
	v_mul_f32_e32 v106, v96, v101
	v_fma_f32 v96, v101, v96, -v106
	v_fmac_f32_e32 v96, v101, v95
	v_sub_f32_e32 v95, v108, v100
	v_add_f32_e32 v95, v97, v95
	v_add_f32_e32 v97, v106, v96
	v_sub_f32_e32 v107, v100, v97
	v_sub_f32_e32 v100, v100, v107
	v_sub_f32_e32 v106, v97, v106
	v_sub_f32_e32 v97, v100, v97
	v_add_f32_e32 v95, v95, v97
	v_sub_f32_e32 v96, v106, v96
	v_cvt_f32_i32_e32 v94, v94
	v_add_f32_e32 v95, v96, v95
	v_add_f32_e32 v96, v98, v101
	v_add_f32_e32 v95, v107, v95
	v_sub_f32_e32 v97, v96, v98
	v_mul_f32_e32 v95, v103, v95
	v_sub_f32_e32 v97, v101, v97
	v_add_f32_e32 v95, v97, v95
	v_mul_f32_e32 v101, 0x3f317218, v94
	v_add_f32_e32 v97, v96, v95
	v_fma_f32 v103, v94, s4, -v101
	v_mul_f32_e32 v98, v97, v97
	v_fmac_f32_e32 v103, 0xb102e308, v94
	v_sub_f32_e32 v94, v97, v96
	v_fmamk_f32 v100, v98, 0x3e9b6dac, v214
	v_sub_f32_e32 v94, v95, v94
	v_add_f32_e32 v95, v101, v103
	v_fmaak_f32 v100, v98, v100, 0x3f2aaada
	v_sub_f32_e32 v96, v95, v101
	v_ldexp_f32 v101, v97, 1
	v_mul_f32_e32 v97, v97, v98
	v_mul_f32_e32 v97, v97, v100
	v_add_f32_e32 v98, v101, v97
	v_sub_f32_e32 v100, v98, v101
	v_ldexp_f32 v94, v94, 1
	v_sub_f32_e32 v97, v97, v100
	v_add_f32_e32 v94, v94, v97
	v_add_f32_e32 v97, v98, v94
	v_sub_f32_e32 v98, v97, v98
	v_sub_f32_e32 v94, v94, v98
	v_add_f32_e32 v98, v95, v97
	v_sub_f32_e32 v100, v98, v95
	v_sub_f32_e32 v101, v98, v100
	v_sub_f32_e32 v96, v103, v96
	v_sub_f32_e32 v95, v95, v101
	v_sub_f32_e32 v97, v97, v100
	v_add_f32_e32 v95, v97, v95
	v_add_f32_e32 v97, v96, v94
	v_sub_f32_e32 v100, v97, v96
	v_sub_f32_e32 v101, v97, v100
	v_sub_f32_e32 v96, v96, v101
	v_sub_f32_e32 v94, v94, v100
	v_add_f32_e32 v95, v97, v95
	v_add_f32_e32 v94, v94, v96
	v_add_f32_e32 v96, v98, v95
	v_sub_f32_e32 v97, v96, v98
	v_sub_f32_e32 v95, v95, v97
	v_add_f32_e32 v94, v94, v95
	v_add_f32_e32 v94, v96, v94
	v_cmp_neq_f32_e32 vcc, s2, v93
	s_nop 1
	v_cndmask_b32_e32 v94, v221, v94, vcc
	v_cmp_lt_f32_e64 vcc, |v93|, s5
	s_nop 1
	v_cndmask_b32_e32 v93, v94, v93, vcc
	v_sub_f32_e32 v93, v99, v93
	ds_write_b32 v92, v93
	s_nop 0
	v_cvt_pk_bf16_f32 v81, v81, v81
	v_lshl_add_u32 v92, v105, 1, v223
	v_add_u32_e32 v92, 0x18800, v92
	ds_write_b16 v92, v81

.LBB0_763:
	s_addk_i32 s73, 0x100
	s_add_i32 s73, s73, 0x19100
	s_add_i32 s56, s73, s49
	v_add_u32_e32 v36, s56, v80
	v_lshl_add_u32 v144, v89, 2, s73
	ds_read2_b32 v[142:143], v144 offset0:128 offset1:144
	ds_read_b128 v[36:39], v36
	v_readlane_b32 s56, v254, 55
	v_readlane_b32 s57, v254, 56
	v_cndmask_b32_e64 v154, 0, 1, s[52:53]
	v_cndmask_b32_e64 v155, 0, 1, s[60:61]
	s_waitcnt lgkmcnt(0)
	v_add_f32_e32 v41, v36, v142
	v_cndmask_b32_e64 v40, 0, 1, s[56:57]
	v_mul_f32_e32 v41, 0x3fb8aa3b, v41
	v_readlane_b32 s56, v254, 53
	v_exp_f32_e32 v41, v41
	v_readlane_b32 s57, v254, 54
	v_cndmask_b32_e64 v156, 0, 1, s[80:81]
	v_cndmask_b32_e64 v158, 0, 1, s[78:79]
	v_cndmask_b32_e64 v42, 0, 1, s[56:57]
	v_cndmask_b32_e64 v40, v42, v40, s[58:59]
	v_and_b32_e32 v40, 1, v40
	v_readlane_b32 s56, v254, 59
	v_mul_f32_e32 v41, v106, v41
	v_cmp_eq_u32_e32 vcc, 1, v40
	v_readlane_b32 s57, v254, 60
	v_add_f32_e32 v42, v37, v142
	v_cndmask_b32_e32 v40, 0, v41, vcc
	v_cndmask_b32_e64 v41, 0, 1, s[56:57]
	v_mul_f32_e32 v42, 0x3fb8aa3b, v42
	v_readlane_b32 s56, v254, 57
	v_exp_f32_e32 v42, v42
	v_readlane_b32 s57, v254, 58
	v_cndmask_b32_e64 v156, v158, v156, s[58:59]
	v_and_b32_e32 v156, 1, v156
	v_cndmask_b32_e64 v43, 0, 1, s[56:57]
	v_cndmask_b32_e64 v41, v43, v41, s[58:59]
	v_and_b32_e32 v41, 1, v41
	v_readlane_b32 s56, v254, 63
	v_mul_f32_e32 v42, v107, v42
	v_cmp_eq_u32_e32 vcc, 1, v41
	v_readlane_b32 s57, v255, 0
	v_add_f32_e32 v43, v38, v142
	v_cndmask_b32_e32 v41, 0, v42, vcc
	v_cndmask_b32_e64 v42, 0, 1, s[56:57]
	v_mul_f32_e32 v43, 0x3fb8aa3b, v43
	v_readlane_b32 s56, v254, 61
	v_exp_f32_e32 v43, v43
	v_readlane_b32 s57, v254, 62
	v_cndmask_b32_e64 v159, 0, 1, s[82:83]
	v_cndmask_b32_e64 v160, 0, 1, s[86:87]
	v_cndmask_b32_e64 v141, 0, 1, s[56:57]
	v_cndmask_b32_e64 v42, v141, v42, s[58:59]
	v_and_b32_e32 v42, 1, v42
	v_readlane_b32 s56, v255, 3
	v_mul_f32_e32 v43, v108, v43
	v_cmp_eq_u32_e32 vcc, 1, v42
	v_readlane_b32 s57, v255, 4
	v_add_f32_e32 v141, v39, v142
	v_cndmask_b32_e32 v42, 0, v43, vcc
	v_cndmask_b32_e64 v43, 0, 1, s[56:57]
	v_mul_f32_e32 v141, 0x3fb8aa3b, v141
	v_readlane_b32 s56, v255, 1
	v_exp_f32_e32 v141, v141
	v_readlane_b32 s57, v255, 2
	v_cndmask_b32_e64 v161, 0, 1, s[94:95]
	v_cndmask_b32_e64 v162, 0, 1, s[4:5]
	v_cndmask_b32_e64 v142, 0, 1, s[56:57]
	v_cndmask_b32_e64 v43, v142, v43, s[58:59]
	v_and_b32_e32 v43, 1, v43
	v_readlane_b32 s56, v255, 7
	v_mul_f32_e32 v141, v109, v141
	v_cmp_eq_u32_e32 vcc, 1, v43
	v_readlane_b32 s57, v255, 8
	v_add_f32_e32 v142, v36, v143
	v_cndmask_b32_e32 v43, 0, v141, vcc
	v_cndmask_b32_e64 v141, 0, 1, s[56:57]
	v_mul_f32_e32 v142, 0x3fb8aa3b, v142
	v_readlane_b32 s56, v255, 5
	v_exp_f32_e32 v142, v142
	v_readlane_b32 s57, v255, 6
	v_cndmask_b32_e64 v163, 0, 1, s[2:3]
	v_cndmask_b32_e64 v165, 0, 1, s[14:15]
	v_cndmask_b32_e64 v145, 0, 1, s[56:57]
	v_cndmask_b32_e64 v141, v145, v141, s[58:59]
	v_and_b32_e32 v141, 1, v141
	v_readlane_b32 s56, v255, 11
	v_mul_f32_e32 v142, v110, v142
	v_cmp_eq_u32_e32 vcc, 1, v141
	v_readlane_b32 s57, v255, 12
	v_add_f32_e32 v145, v37, v143
	v_cndmask_b32_e32 v141, 0, v142, vcc
	v_cndmask_b32_e64 v142, 0, 1, s[56:57]
	v_readlane_b32 s56, v255, 9
	v_readlane_b32 s57, v255, 10
	v_mul_f32_e32 v145, 0x3fb8aa3b, v145
	v_exp_f32_e32 v145, v145
	v_cndmask_b32_e64 v146, 0, 1, s[56:57]
	v_cndmask_b32_e64 v142, v146, v142, s[58:59]
	v_readlane_b32 s56, v255, 15
	v_and_b32_e32 v142, 1, v142
	v_readlane_b32 s57, v255, 16
	v_cmp_eq_u32_e32 vcc, 1, v142
	v_add_f32_e32 v146, v38, v143
	v_cndmask_b32_e64 v142, 0, 1, s[56:57]
	v_readlane_b32 s56, v255, 13
	v_readlane_b32 s57, v255, 14
	v_mul_f32_e32 v145, v111, v145
	v_mul_f32_e32 v146, 0x3fb8aa3b, v146
	v_cndmask_b32_e64 v147, 0, 1, s[56:57]
	v_cndmask_b32_e64 v142, v147, v142, s[58:59]
	v_readlane_b32 s56, v255, 19
	v_and_b32_e32 v142, 1, v142
	v_readlane_b32 s57, v255, 20
	v_add_f32_e32 v143, v39, v143
	v_cndmask_b32_e32 v145, 0, v145, vcc
	v_exp_f32_e32 v146, v146
	v_cmp_eq_u32_e32 vcc, 1, v142
	v_cndmask_b32_e64 v142, 0, 1, s[56:57]
	v_mul_f32_e32 v143, 0x3fb8aa3b, v143
	v_readlane_b32 s56, v255, 17
	v_exp_f32_e32 v143, v143
	v_readlane_b32 s57, v255, 18
	v_mul_f32_e32 v146, v112, v146
	v_cndmask_b32_e32 v146, 0, v146, vcc
	v_cndmask_b32_e64 v147, 0, 1, s[56:57]
	v_cndmask_b32_e64 v142, v147, v142, s[58:59]
	v_and_b32_e32 v142, 1, v142
	v_mul_f32_e32 v143, v113, v143
	v_cmp_eq_u32_e32 vcc, 1, v142
	v_readlane_b32 s56, v255, 23
	v_readlane_b32 s57, v255, 24
	v_cndmask_b32_e32 v147, 0, v143, vcc
	ds_read2_b32 v[142:143], v144 offset0:160 offset1:176
	v_cndmask_b32_e64 v148, 0, 1, s[56:57]
	v_readlane_b32 s56, v255, 21
	v_readlane_b32 s57, v255, 22
	v_cndmask_b32_e64 v166, 0, 1, s[18:19]
	s_waitcnt lgkmcnt(0)
	v_add_f32_e32 v149, v36, v142
	v_mul_f32_e32 v149, 0x3fb8aa3b, v149
	v_exp_f32_e32 v149, v149
	v_cndmask_b32_e64 v150, 0, 1, s[56:57]
	v_cndmask_b32_e64 v148, v150, v148, s[58:59]
	v_and_b32_e32 v148, 1, v148
	v_readlane_b32 s56, v255, 27
	v_mul_f32_e32 v149, v114, v149
	v_cmp_eq_u32_e32 vcc, 1, v148
	v_readlane_b32 s57, v255, 28
	v_add_f32_e32 v150, v37, v142
	v_cndmask_b32_e32 v148, 0, v149, vcc
	v_cndmask_b32_e64 v149, 0, 1, s[56:57]
	v_mul_f32_e32 v150, 0x3fb8aa3b, v150
	v_readlane_b32 s56, v255, 25
	v_exp_f32_e32 v150, v150
	v_readlane_b32 s57, v255, 26
	v_cndmask_b32_e64 v167, 0, 1, s[22:23]
	v_mul_f32_e32 v150, v115, v150
	v_cndmask_b32_e64 v151, 0, 1, s[56:57]
	v_cndmask_b32_e64 v149, v151, v149, s[58:59]
	v_and_b32_e32 v149, 1, v149
	v_readlane_b32 s56, v255, 31
	v_cmp_eq_u32_e32 vcc, 1, v149
	v_readlane_b32 s57, v255, 32
	v_add_f32_e32 v151, v38, v142
	v_cndmask_b32_e32 v149, 0, v150, vcc
	v_cndmask_b32_e64 v150, 0, 1, s[56:57]
	v_mul_f32_e32 v151, 0x3fb8aa3b, v151
	v_readlane_b32 s56, v255, 29
	v_exp_f32_e32 v151, v151
	v_readlane_b32 s57, v255, 30
	v_add_f32_e32 v142, v39, v142
	v_mul_f32_e32 v142, 0x3fb8aa3b, v142
	v_cndmask_b32_e64 v152, 0, 1, s[56:57]
	v_cndmask_b32_e64 v150, v152, v150, s[58:59]
	v_and_b32_e32 v150, 1, v150
	v_readlane_b32 s56, v255, 35
	v_mul_f32_e32 v151, v116, v151
	v_cmp_eq_u32_e32 vcc, 1, v150
	v_readlane_b32 s57, v255, 36
	v_exp_f32_e32 v142, v142
	v_cndmask_b32_e32 v150, 0, v151, vcc
	v_cndmask_b32_e64 v151, 0, 1, s[56:57]
	v_readlane_b32 s56, v255, 33
	v_readlane_b32 s57, v255, 34
	v_mul_f32_e32 v142, v117, v142
	s_nop 0
	v_cndmask_b32_e64 v152, 0, 1, s[56:57]
	v_cndmask_b32_e64 v151, v152, v151, s[58:59]
	v_and_b32_e32 v151, 1, v151
	v_readlane_b32 s56, v255, 37
	v_cmp_eq_u32_e32 vcc, 1, v151
	v_add_f32_e32 v152, v36, v143
	v_readlane_b32 s57, v255, 38
	v_cndmask_b32_e32 v151, 0, v142, vcc
	v_cndmask_b32_e64 v142, 0, 1, s[50:51]
	v_mul_f32_e32 v152, 0x3fb8aa3b, v152
	v_cndmask_b32_e64 v153, 0, 1, s[56:57]
	v_exp_f32_e32 v152, v152
	v_cndmask_b32_e64 v142, v153, v142, s[58:59]
	v_and_b32_e32 v142, 1, v142
	v_add_f32_e32 v153, v37, v143
	v_cmp_eq_u32_e32 vcc, 1, v142
	v_cndmask_b32_e64 v142, 0, 1, s[54:55]
	v_mul_f32_e32 v153, 0x3fb8aa3b, v153
	v_exp_f32_e32 v153, v153
	v_cndmask_b32_e64 v142, v154, v142, s[58:59]
	v_mul_f32_e32 v152, v118, v152
	v_and_b32_e32 v142, 1, v142
	v_add_f32_e32 v154, v38, v143
	v_cndmask_b32_e32 v152, 0, v152, vcc
	v_cmp_eq_u32_e32 vcc, 1, v142
	v_cndmask_b32_e64 v142, 0, 1, s[62:63]
	v_mul_f32_e32 v154, 0x3fb8aa3b, v154
	v_add_f32_e32 v143, v39, v143
	v_exp_f32_e32 v154, v154
	v_cndmask_b32_e64 v142, v155, v142, s[58:59]
	v_mul_f32_e32 v143, 0x3fb8aa3b, v143
	v_mul_f32_e32 v153, v119, v153
	v_and_b32_e32 v142, 1, v142
	v_exp_f32_e32 v143, v143
	v_cndmask_b32_e32 v153, 0, v153, vcc
	v_cmp_eq_u32_e32 vcc, 1, v142
	v_cndmask_b32_e64 v142, 0, 1, s[76:77]
	v_cndmask_b32_e64 v155, 0, 1, s[74:75]
	v_cndmask_b32_e64 v142, v155, v142, s[58:59]
	v_mul_f32_e32 v154, v120, v154
	v_and_b32_e32 v142, 1, v142
	v_cndmask_b32_e32 v154, 0, v154, vcc
	v_mul_f32_e32 v143, v121, v143
	v_cmp_eq_u32_e32 vcc, 1, v142
	s_xor_b64 s[56:57], s[58:59], -1
	s_nop 0
	v_cndmask_b32_e32 v155, 0, v143, vcc
	ds_read2_b32 v[142:143], v144 offset0:192 offset1:208
	v_cmp_eq_u32_e32 vcc, 1, v156
	s_waitcnt lgkmcnt(0)
	v_add_f32_e32 v157, v36, v142
	v_mul_f32_e32 v157, 0x3fb8aa3b, v157
	v_exp_f32_e32 v157, v157
	v_add_f32_e32 v158, v37, v142
	v_mul_f32_e32 v158, 0x3fb8aa3b, v158
	v_exp_f32_e32 v158, v158
	v_mul_f32_e32 v157, v122, v157
	v_cndmask_b32_e32 v156, 0, v157, vcc
	v_cndmask_b32_e64 v157, 0, 1, s[84:85]
	v_cndmask_b32_e64 v157, v159, v157, s[58:59]
	v_add_f32_e32 v159, v38, v142
	v_and_b32_e32 v157, 1, v157
	v_mul_f32_e32 v159, 0x3fb8aa3b, v159
	v_mul_f32_e32 v158, v123, v158
	v_cmp_eq_u32_e32 vcc, 1, v157
	v_exp_f32_e32 v159, v159
	v_add_f32_e32 v142, v39, v142
	v_cndmask_b32_e32 v157, 0, v158, vcc
	v_cndmask_b32_e64 v158, 0, 1, s[88:89]
	v_cndmask_b32_e64 v158, v160, v158, s[58:59]
	v_and_b32_e32 v158, 1, v158
	v_mul_f32_e32 v142, 0x3fb8aa3b, v142
	v_mul_f32_e32 v159, v124, v159
	v_cmp_eq_u32_e32 vcc, 1, v158
	v_exp_f32_e32 v142, v142
	v_cndmask_b32_e64 v160, 0, 1, s[90:91]
	v_cndmask_b32_e32 v158, 0, v159, vcc
	v_cndmask_b32_e64 v159, 0, 1, s[92:93]
	v_cndmask_b32_e64 v159, v160, v159, s[58:59]
	v_and_b32_e32 v159, 1, v159
	v_mul_f32_e32 v142, v125, v142
	v_cmp_eq_u32_e32 vcc, 1, v159
	v_add_f32_e32 v160, v36, v143
	v_mul_f32_e32 v160, 0x3fb8aa3b, v160
	v_cndmask_b32_e32 v159, 0, v142, vcc
	v_cndmask_b32_e64 v142, 0, 1, s[96:97]
	v_exp_f32_e32 v160, v160
	v_cndmask_b32_e64 v142, v161, v142, s[58:59]
	v_and_b32_e32 v142, 1, v142
	v_add_f32_e32 v161, v37, v143
	v_cmp_eq_u32_e32 vcc, 1, v142
	v_cndmask_b32_e64 v142, 0, 1, s[6:7]
	v_mul_f32_e32 v161, 0x3fb8aa3b, v161
	v_exp_f32_e32 v161, v161
	v_cndmask_b32_e64 v142, v162, v142, s[58:59]
	v_mul_f32_e32 v160, v126, v160
	v_and_b32_e32 v142, 1, v142
	v_add_f32_e32 v162, v38, v143
	v_cndmask_b32_e32 v160, 0, v160, vcc
	v_cmp_eq_u32_e32 vcc, 1, v142
	v_cndmask_b32_e64 v142, 0, 1, s[0:1]
	v_mul_f32_e32 v162, 0x3fb8aa3b, v162
	v_add_f32_e32 v143, v39, v143
	v_exp_f32_e32 v162, v162
	v_cndmask_b32_e64 v142, v163, v142, s[58:59]
	v_mul_f32_e32 v143, 0x3fb8aa3b, v143
	v_mul_f32_e32 v161, v127, v161
	v_and_b32_e32 v142, 1, v142
	v_exp_f32_e32 v143, v143
	v_cndmask_b32_e32 v161, 0, v161, vcc
	v_cmp_eq_u32_e32 vcc, 1, v142
	v_cndmask_b32_e64 v142, 0, 1, s[12:13]
	v_cndmask_b32_e64 v163, 0, 1, s[8:9]
	v_cndmask_b32_e64 v142, v163, v142, s[58:59]
	v_mul_f32_e32 v162, v128, v162
	v_and_b32_e32 v142, 1, v142
	v_cndmask_b32_e32 v162, 0, v162, vcc
	v_mul_f32_e32 v143, v129, v143
	v_cmp_eq_u32_e32 vcc, 1, v142
	s_nop 1
	v_cndmask_b32_e32 v163, 0, v143, vcc
	ds_read2_b32 v[142:143], v144 offset0:224 offset1:240
	v_cndmask_b32_e64 v144, 0, 1, s[16:17]
	v_cndmask_b32_e64 v144, v165, v144, s[58:59]
	v_and_b32_e32 v144, 1, v144
	v_cmp_eq_u32_e32 vcc, 1, v144
	s_waitcnt lgkmcnt(0)
	v_add_f32_e32 v164, v36, v142
	v_mul_f32_e32 v164, 0x3fb8aa3b, v164
	v_exp_f32_e32 v164, v164
	v_add_f32_e32 v165, v37, v142
	v_mul_f32_e32 v165, 0x3fb8aa3b, v165
	v_exp_f32_e32 v165, v165
	v_mul_f32_e32 v164, v130, v164
	v_cndmask_b32_e32 v144, 0, v164, vcc
	v_cndmask_b32_e64 v164, 0, 1, s[20:21]
	v_cndmask_b32_e64 v164, v166, v164, s[58:59]
	v_add_f32_e32 v166, v38, v142
	v_and_b32_e32 v164, 1, v164
	v_mul_f32_e32 v166, 0x3fb8aa3b, v166
	v_mul_f32_e32 v165, v131, v165
	v_cmp_eq_u32_e32 vcc, 1, v164
	v_exp_f32_e32 v166, v166
	v_add_f32_e32 v142, v39, v142
	v_cndmask_b32_e32 v164, 0, v165, vcc
	v_cndmask_b32_e64 v165, 0, 1, s[24:25]
	v_cndmask_b32_e64 v165, v167, v165, s[58:59]
	v_and_b32_e32 v165, 1, v165
	v_mul_f32_e32 v166, v132, v166
	v_cmp_eq_u32_e32 vcc, 1, v165
	v_mul_f32_e32 v142, 0x3fb8aa3b, v142
	v_cndmask_b32_e64 v167, 0, 1, s[26:27]
	v_cndmask_b32_e32 v165, 0, v166, vcc
	v_cndmask_b32_e64 v166, 0, 1, s[28:29]
	v_exp_f32_e32 v142, v142
	v_cndmask_b32_e64 v166, v167, v166, s[58:59]
	v_and_b32_e32 v166, 1, v166
	v_add_f32_e32 v36, v36, v143
	v_cmp_eq_u32_e32 vcc, 1, v166
	v_cndmask_b32_e64 v166, 0, 1, s[34:35]
	v_mul_f32_e32 v36, 0x3fb8aa3b, v36
	v_cndmask_b32_e64 v167, 0, 1, s[30:31]
	v_exp_f32_e32 v36, v36
	v_cndmask_b32_e64 v166, v167, v166, s[58:59]
	v_mul_f32_e32 v142, v133, v142
	v_and_b32_e32 v166, 1, v166
	v_add_f32_e32 v37, v37, v143
	v_cndmask_b32_e32 v142, 0, v142, vcc
	v_cmp_eq_u32_e32 vcc, 1, v166
	v_cndmask_b32_e64 v166, 0, 1, s[38:39]
	v_mul_f32_e32 v37, 0x3fb8aa3b, v37
	v_cndmask_b32_e64 v167, 0, 1, s[36:37]
	v_exp_f32_e32 v37, v37
	v_cndmask_b32_e64 v166, v167, v166, s[58:59]
	v_mul_f32_e32 v36, v134, v36
	v_and_b32_e32 v166, 1, v166
	v_add_f32_e32 v38, v38, v143
	v_cndmask_b32_e32 v36, 0, v36, vcc
	v_cmp_eq_u32_e32 vcc, 1, v166
	v_cndmask_b32_e64 v166, 0, 1, s[42:43]
	v_mul_f32_e32 v38, 0x3fb8aa3b, v38
	v_cndmask_b32_e64 v167, 0, 1, s[40:41]
	v_exp_f32_e32 v38, v38
	v_cndmask_b32_e64 v166, v167, v166, s[58:59]
	v_mul_f32_e32 v37, v135, v37
	v_and_b32_e32 v166, 1, v166
	v_cndmask_b32_e32 v37, 0, v37, vcc
	v_cmp_eq_u32_e32 vcc, 1, v166
	v_cndmask_b32_e64 v166, 0, 1, s[46:47]
	v_add_f32_e32 v39, v39, v143
	v_cndmask_b32_e64 v143, 0, 1, s[44:45]
	v_cndmask_b32_e64 v143, v143, v166, s[58:59]
	v_mul_f32_e32 v38, v136, v38
	v_and_b32_e32 v143, 1, v143
	v_cndmask_b32_e32 v38, 0, v38, vcc
	v_cmp_eq_u32_e32 vcc, 1, v143
	s_nop 0
	v_cvt_pk_bf16_f32 v40, v40, v40
	ds_write_b16 v139, v40
	v_bfe_u32 v40, v41, 16, 1
	v_add3_u32 v40, v41, v40, s65
	ds_write_b16_d16_hi v139, v40 offset:272
	v_bfe_u32 v40, v42, 16, 1
	v_add3_u32 v40, v42, v40, s65
	ds_write_b16_d16_hi v139, v40 offset:544
	v_bfe_u32 v40, v43, 16, 1
	v_add3_u32 v40, v43, v40, s65
	ds_write_b16_d16_hi v139, v40 offset:816
	v_bfe_u32 v40, v141, 16, 1
	v_add3_u32 v40, v141, v40, s65
	ds_write_b16_d16_hi v139, v40 offset:32
	v_bfe_u32 v40, v145, 16, 1
	v_add3_u32 v40, v145, v40, s65
	ds_write_b16_d16_hi v139, v40 offset:304
	v_bfe_u32 v40, v146, 16, 1
	v_add3_u32 v40, v146, v40, s65
	ds_write_b16_d16_hi v139, v40 offset:576
	v_bfe_u32 v40, v147, 16, 1
	v_add3_u32 v40, v147, v40, s65
	ds_write_b16_d16_hi v139, v40 offset:848
	v_bfe_u32 v40, v148, 16, 1
	v_add3_u32 v40, v148, v40, s65
	ds_write_b16_d16_hi v139, v40 offset:64
	v_bfe_u32 v40, v149, 16, 1
	v_add3_u32 v40, v149, v40, s65
	ds_write_b16_d16_hi v139, v40 offset:336
	v_bfe_u32 v40, v150, 16, 1
	v_add3_u32 v40, v150, v40, s65
	ds_write_b16_d16_hi v139, v40 offset:608
	v_bfe_u32 v40, v151, 16, 1
	v_add3_u32 v40, v151, v40, s65
	ds_write_b16_d16_hi v139, v40 offset:880
	v_bfe_u32 v40, v152, 16, 1
	v_add3_u32 v40, v152, v40, s65
	ds_write_b16_d16_hi v139, v40 offset:96
	v_bfe_u32 v40, v153, 16, 1
	v_add3_u32 v40, v153, v40, s65
	ds_write_b16_d16_hi v139, v40 offset:368
	v_bfe_u32 v40, v154, 16, 1
	v_add3_u32 v40, v154, v40, s65
	ds_write_b16_d16_hi v139, v40 offset:640
	v_bfe_u32 v40, v155, 16, 1
	v_add3_u32 v40, v155, v40, s65
	ds_write_b16_d16_hi v139, v40 offset:912
	v_bfe_u32 v40, v156, 16, 1
	v_add3_u32 v40, v156, v40, s65
	ds_write_b16_d16_hi v139, v40 offset:128
	v_bfe_u32 v40, v157, 16, 1
	v_add3_u32 v40, v157, v40, s65
	ds_write_b16_d16_hi v139, v40 offset:400
	v_bfe_u32 v40, v158, 16, 1
	v_add3_u32 v40, v158, v40, s65
	ds_write_b16_d16_hi v139, v40 offset:672
	v_bfe_u32 v40, v159, 16, 1
	v_add3_u32 v40, v159, v40, s65
	ds_write_b16_d16_hi v139, v40 offset:944
	v_bfe_u32 v40, v160, 16, 1
	v_add3_u32 v40, v160, v40, s65
	ds_write_b16_d16_hi v139, v40 offset:160
	v_bfe_u32 v40, v161, 16, 1
	v_add3_u32 v40, v161, v40, s65
	ds_write_b16_d16_hi v139, v40 offset:432
	v_bfe_u32 v40, v162, 16, 1
	v_add3_u32 v40, v162, v40, s65
	ds_write_b16_d16_hi v139, v40 offset:704
	v_bfe_u32 v40, v163, 16, 1
	v_add3_u32 v40, v163, v40, s65
	ds_write_b16_d16_hi v139, v40 offset:976
	v_bfe_u32 v40, v144, 16, 1
	v_add3_u32 v40, v144, v40, s65
	ds_write_b16_d16_hi v139, v40 offset:192
	v_bfe_u32 v40, v164, 16, 1
	v_add3_u32 v40, v164, v40, s65
	ds_write_b16_d16_hi v139, v40 offset:464
	v_bfe_u32 v40, v165, 16, 1
	v_add3_u32 v40, v165, v40, s65
	ds_write_b16_d16_hi v139, v40 offset:736
	v_bfe_u32 v40, v142, 16, 1
	v_mul_f32_e32 v39, 0x3fb8aa3b, v39
	v_add3_u32 v40, v142, v40, s65
	v_exp_f32_e32 v39, v39
	ds_write_b16_d16_hi v139, v40 offset:1008
	v_bfe_u32 v40, v36, 16, 1
	v_add3_u32 v36, v36, v40, s65
	ds_write_b16_d16_hi v139, v36 offset:224
	v_bfe_u32 v36, v37, 16, 1
	v_add3_u32 v36, v37, v36, s65
	v_mul_f32_e32 v39, v137, v39
	ds_write_b16_d16_hi v139, v36 offset:496
	v_bfe_u32 v36, v38, 16, 1
	v_cndmask_b32_e32 v39, 0, v39, vcc
	v_add3_u32 v36, v38, v36, s65
	ds_write_b16_d16_hi v139, v36 offset:768
	v_bfe_u32 v36, v39, 16, 1
	v_add3_u32 v36, v39, v36, s65
	ds_write_b16_d16_hi v139, v36 offset:1040
	v_add_u32_e32 v36, 0x100, v80
	v_add_u32_e32 v36, 0x18800, v36
	s_waitcnt lgkmcnt(0)
	s_barrier
	ds_read_b128 v[142:145], v36
	ds_read_b128 v[146:149], v36 offset:64
	ds_read_b128 v[40:43], v36 offset:128
	ds_read_b128 v[36:39], v36 offset:192
	ds_read_b64_tr_b16 v[150:151], v76 offset:0
	ds_read_b64_tr_b16 v[152:153], v77 offset:0
	ds_read_b64_tr_b16 v[154:155], v78 offset:0
	ds_read_b64_tr_b16 v[156:157], v79 offset:0
	ds_read_b64_tr_b16 v[158:159], v90 offset:0
	ds_read_b64_tr_b16 v[160:161], v91 offset:0
	ds_read_b64_tr_b16 v[162:163], v92 offset:0
	ds_read_b64_tr_b16 v[164:165], v93 offset:0
	ds_read_b64_tr_b16 v[166:167], v94 offset:0
	ds_read_b64_tr_b16 v[168:169], v95 offset:0
	ds_read_b64_tr_b16 v[170:171], v96 offset:0
	ds_read_b64_tr_b16 v[172:173], v97 offset:0
	ds_read_b64_tr_b16 v[180:181], v98 offset:0
	ds_read_b64_tr_b16 v[182:183], v99 offset:0
	ds_read_b64_tr_b16 v[184:185], v100 offset:0
	ds_read_b64_tr_b16 v[186:187], v101 offset:0
	s_waitcnt lgkmcnt(0)
	ds_read_b64_tr_b16 v[196:197], v76 offset:0x2000
	ds_read_b64_tr_b16 v[198:199], v77 offset:0x2000
	ds_read_b64_tr_b16 v[200:201], v78 offset:0x2000
	ds_read_b64_tr_b16 v[202:203], v79 offset:0x2000
	ds_read_b64_tr_b16 v[204:205], v90 offset:0x2000
	ds_read_b64_tr_b16 v[206:207], v91 offset:0x2000
	ds_read_b64_tr_b16 v[208:209], v92 offset:0x2000
	ds_read_b64_tr_b16 v[210:211], v93 offset:0x2000
	ds_read_b64_tr_b16 v[226:227], v94 offset:0x2000
	ds_read_b64_tr_b16 v[228:229], v95 offset:0x2000
	ds_read_b64_tr_b16 v[230:231], v96 offset:0x2000
	ds_read_b64_tr_b16 v[232:233], v97 offset:0x2000
	ds_read_b64_tr_b16 v[234:235], v98 offset:0x2000
	ds_read_b64_tr_b16 v[236:237], v99 offset:0x2000
	ds_read_b64_tr_b16 v[238:239], v100 offset:0x2000
	ds_read_b64_tr_b16 v[240:241], v101 offset:0x2000
	s_waitcnt lgkmcnt(0)
	s_waitcnt lgkmcnt(3)
	v_cndmask_b32_e64 v145, 0, v145, s[10:11]
	v_cndmask_b32_e64 v144, 0, v144, s[10:11]
	v_cndmask_b32_e64 v143, 0, v143, s[10:11]
	v_cndmask_b32_e64 v142, 0, v142, s[10:11]
	v_mfma_f32_16x16x32_bf16 v[150:153], v[8:11], v[150:153], 0
	v_mfma_f32_16x16x32_bf16 v[154:157], v[8:11], v[154:157], 0
	v_mfma_f32_16x16x32_bf16 v[158:161], v[8:11], v[158:161], 0
	v_mfma_f32_16x16x32_bf16 v[162:165], v[8:11], v[162:165], 0
	v_mfma_f32_16x16x32_bf16 v[166:169], v[8:11], v[166:169], 0
	v_mfma_f32_16x16x32_bf16 v[170:173], v[8:11], v[170:173], 0
	v_mfma_f32_16x16x32_bf16 v[180:183], v[8:11], v[180:183], 0
	v_mfma_f32_16x16x32_bf16 v[184:187], v[8:11], v[184:187], 0
	v_mfma_f32_16x16x32_bf16 v[142:145], v[8:11], v[142:145], 0
	v_mfma_f32_16x16x32_bf16 v[150:153], v[0:3], v[196:199], v[150:153]
	ds_read_b64_tr_b16 v[196:197], v76 offset:0x4000
	ds_read_b64_tr_b16 v[198:199], v77 offset:0x4000
	s_waitcnt lgkmcnt(2)
	v_cndmask_b32_e64 v149, 0, v149, s[10:11]
	v_mfma_f32_16x16x32_bf16 v[154:157], v[0:3], v[200:203], v[154:157]
	ds_read_b64_tr_b16 v[200:201], v78 offset:0x4000
	ds_read_b64_tr_b16 v[202:203], v79 offset:0x4000
	v_cndmask_b32_e64 v148, 0, v148, s[10:11]
	v_mfma_f32_16x16x32_bf16 v[158:161], v[0:3], v[204:207], v[158:161]
	ds_read_b64_tr_b16 v[204:205], v90 offset:0x4000
	ds_read_b64_tr_b16 v[206:207], v91 offset:0x4000
	v_cndmask_b32_e64 v147, 0, v147, s[10:11]
	v_mfma_f32_16x16x32_bf16 v[162:165], v[0:3], v[208:211], v[162:165]
	ds_read_b64_tr_b16 v[208:209], v92 offset:0x4000
	ds_read_b64_tr_b16 v[210:211], v93 offset:0x4000
	v_cndmask_b32_e64 v146, 0, v146, s[10:11]
	v_mfma_f32_16x16x32_bf16 v[166:169], v[0:3], v[226:229], v[166:169]
	ds_read_b64_tr_b16 v[226:227], v94 offset:0x4000
	ds_read_b64_tr_b16 v[228:229], v95 offset:0x4000
	v_mfma_f32_16x16x32_bf16 v[170:173], v[0:3], v[230:233], v[170:173]
	ds_read_b64_tr_b16 v[230:231], v96 offset:0x4000
	ds_read_b64_tr_b16 v[232:233], v97 offset:0x4000
	v_mfma_f32_16x16x32_bf16 v[180:183], v[0:3], v[234:237], v[180:183]
	ds_read_b64_tr_b16 v[234:235], v98 offset:0x4000
	ds_read_b64_tr_b16 v[236:237], v99 offset:0x4000
	v_mfma_f32_16x16x32_bf16 v[184:187], v[0:3], v[238:241], v[184:187]
	ds_read_b64_tr_b16 v[238:239], v100 offset:0x4000
	ds_read_b64_tr_b16 v[240:241], v101 offset:0x4000
	s_waitcnt lgkmcnt(0)
	v_mfma_f32_16x16x32_bf16 v[142:145], v[0:3], v[146:149], v[142:145]
	v_mfma_f32_16x16x32_bf16 v[146:149], v[4:7], v[196:199], v[150:153]
	s_waitcnt lgkmcnt(1)
	v_cndmask_b32_e64 v43, 0, v43, s[10:11]
	v_cndmask_b32_e64 v42, 0, v42, s[10:11]
	v_cndmask_b32_e64 v41, 0, v41, s[10:11]
	v_mfma_f32_16x16x32_bf16 v[150:153], v[4:7], v[200:203], v[154:157]
	v_cndmask_b32_e64 v40, 0, v40, s[10:11]
	v_mfma_f32_16x16x32_bf16 v[154:157], v[4:7], v[204:207], v[158:161]
	ds_read_b64_tr_b16 v[158:159], v76 offset:0x6000
	ds_read_b64_tr_b16 v[160:161], v77 offset:0x6000
	ds_read_b64_tr_b16 v[196:197], v78 offset:0x6000
	ds_read_b64_tr_b16 v[198:199], v79 offset:0x6000
	ds_read_b64_tr_b16 v[200:201], v90 offset:0x6000
	ds_read_b64_tr_b16 v[202:203], v91 offset:0x6000
	ds_read_b64_tr_b16 v[204:205], v92 offset:0x6000
	ds_read_b64_tr_b16 v[206:207], v93 offset:0x6000
	v_mfma_f32_16x16x32_bf16 v[162:165], v[4:7], v[208:211], v[162:165]
	ds_read_b64_tr_b16 v[208:209], v94 offset:0x6000
	ds_read_b64_tr_b16 v[210:211], v95 offset:0x6000
	v_mfma_f32_16x16x32_bf16 v[166:169], v[4:7], v[226:229], v[166:169]
	ds_read_b64_tr_b16 v[226:227], v96 offset:0x6000
	ds_read_b64_tr_b16 v[228:229], v97 offset:0x6000
	v_mfma_f32_16x16x32_bf16 v[170:173], v[4:7], v[230:233], v[170:173]
	ds_read_b64_tr_b16 v[230:231], v98 offset:0x6000
	ds_read_b64_tr_b16 v[232:233], v99 offset:0x6000
	v_mfma_f32_16x16x32_bf16 v[180:183], v[4:7], v[234:237], v[180:183]
	ds_read_b64_tr_b16 v[234:235], v100 offset:0x6000
	ds_read_b64_tr_b16 v[236:237], v101 offset:0x6000
	s_waitcnt lgkmcnt(0)
	v_mfma_f32_16x16x32_bf16 v[184:187], v[4:7], v[238:241], v[184:187]
	v_mfma_f32_16x16x32_bf16 v[40:43], v[4:7], v[40:43], v[142:145]
	v_lshl_add_u32 v141, v103, 2, s73
	v_mfma_f32_16x16x32_bf16 v[142:145], v[12:15], v[158:161], v[146:149]
	s_waitcnt lgkmcnt(0)
	s_nop 1
	v_cndmask_b32_e64 v149, 0, v39, s[10:11]
	v_cndmask_b32_e64 v148, 0, v38, s[10:11]
	v_cndmask_b32_e64 v147, 0, v37, s[10:11]
	v_cndmask_b32_e64 v146, 0, v36, s[10:11]
	ds_read_b128 v[36:39], v141 offset:1536
	ds_read_b128 v[158:161], v141 offset:1024
	v_mfma_f32_16x16x32_bf16 v[150:153], v[12:15], v[196:199], v[150:153]
	s_waitcnt lgkmcnt(0)
	v_pk_mul_f32 v[144:145], v[144:145], v[160:161]
	v_mfma_f32_16x16x32_bf16 v[154:157], v[12:15], v[200:203], v[154:157]
	v_mul_f32_e64 v142, v142, v158
	v_mul_f32_e64 v143, v143, v159
	s_nop 2
	v_pk_mul_f32 v[152:153], v[152:153], v[160:161]
	v_pk_mul_f32 v[150:151], v[150:151], v[158:159]
	v_mfma_f32_16x16x32_bf16 v[40:43], v[12:15], v[146:149], v[40:43]
	v_mfma_f32_16x16x32_bf16 v[162:165], v[12:15], v[204:207], v[162:165]
	v_mul_f32_e64 v156, v156, v160
	v_mul_f32_e64 v157, v157, v161
	s_nop 4
	v_pk_mul_f32 v[146:147], v[158:159], v[40:41]
	v_pk_mul_f32 v[154:155], v[154:155], v[158:159]
	v_mfma_f32_16x16x32_bf16 v[166:169], v[12:15], v[208:211], v[166:169]
	v_mul_f32_e64 v148, v42, v160
	v_mul_f32_e64 v149, v43, v161
	v_pk_mul_f32 v[164:165], v[164:165], v[160:161]
	v_pk_mul_f32 v[162:163], v[162:163], v[158:159]
	v_mfma_f32_16x16x32_bf16 v[170:173], v[12:15], v[226:229], v[170:173]
	v_mfma_f32_16x16x32_bf16 v[180:183], v[12:15], v[230:233], v[180:183]
	s_nop 1
	v_mul_f32_e64 v168, v168, v160
	v_mul_f32_e64 v169, v169, v161
	v_pk_mul_f32 v[166:167], v[166:167], v[158:159]
	s_nop 1
	v_pk_mul_f32 v[172:173], v[172:173], v[160:161]
	v_mfma_f32_16x16x32_bf16 v[184:187], v[12:15], v[234:237], v[184:187]
	v_mul_f32_e64 v170, v170, v158
	v_mul_f32_e64 v171, v171, v159
	v_pk_mul_f32 v[182:183], v[182:183], v[160:161]
	v_pk_mul_f32 v[180:181], v[180:181], v[158:159]
	s_nop 3
	v_pk_mul_f32 v[186:187], v[186:187], v[160:161]
	v_pk_mul_f32 v[184:185], v[184:185], v[158:159]
	ds_read_b128 v[158:161], v140
	ds_read_b128 v[196:199], v140 offset:64
	ds_read_b128 v[200:203], v140 offset:128
	ds_read_b128 v[40:43], v140 offset:192
	ds_read_b64_tr_b16 v[204:205], v76 offset:0x8000
	ds_read_b64_tr_b16 v[206:207], v77 offset:0x8000
	ds_read_b64_tr_b16 v[208:209], v78 offset:0x8000
	ds_read_b64_tr_b16 v[210:211], v79 offset:0x8000
	ds_read_b64_tr_b16 v[226:227], v90 offset:0x8000
	ds_read_b64_tr_b16 v[228:229], v91 offset:0x8000
	ds_read_b64_tr_b16 v[230:231], v92 offset:0x8000
	ds_read_b64_tr_b16 v[232:233], v93 offset:0x8000
	ds_read_b64_tr_b16 v[234:235], v94 offset:0x8000
	ds_read_b64_tr_b16 v[236:237], v95 offset:0x8000
	ds_read_b64_tr_b16 v[238:239], v96 offset:0x8000
	ds_read_b64_tr_b16 v[240:241], v97 offset:0x8000
	ds_read_b64_tr_b16 v[242:243], v98 offset:0x8000
	ds_read_b64_tr_b16 v[244:245], v99 offset:0x8000
	ds_read_b64_tr_b16 v[246:247], v100 offset:0x8000
	ds_read_b64_tr_b16 v[248:249], v101 offset:0x8000
	s_waitcnt lgkmcnt(0)
	s_waitcnt lgkmcnt(3)
	v_mfma_f32_16x16x32_bf16 v[142:145], v[158:161], v[204:207], v[142:145]
	ds_read_b64_tr_b16 v[204:205], v76 offset:0xa000
	ds_read_b64_tr_b16 v[206:207], v77 offset:0xa000
	v_mfma_f32_16x16x32_bf16 v[150:153], v[158:161], v[208:211], v[150:153]
	ds_read_b64_tr_b16 v[208:209], v78 offset:0xa000
	ds_read_b64_tr_b16 v[210:211], v79 offset:0xa000
	v_mfma_f32_16x16x32_bf16 v[154:157], v[158:161], v[226:229], v[154:157]
	ds_read_b64_tr_b16 v[226:227], v90 offset:0xa000
	ds_read_b64_tr_b16 v[228:229], v91 offset:0xa000
	v_mfma_f32_16x16x32_bf16 v[162:165], v[158:161], v[230:233], v[162:165]
	ds_read_b64_tr_b16 v[230:231], v92 offset:0xa000
	ds_read_b64_tr_b16 v[232:233], v93 offset:0xa000
	v_mfma_f32_16x16x32_bf16 v[166:169], v[158:161], v[234:237], v[166:169]
	ds_read_b64_tr_b16 v[234:235], v94 offset:0xa000
	ds_read_b64_tr_b16 v[236:237], v95 offset:0xa000
	v_mfma_f32_16x16x32_bf16 v[170:173], v[158:161], v[238:241], v[170:173]
	ds_read_b64_tr_b16 v[238:239], v96 offset:0xa000
	ds_read_b64_tr_b16 v[240:241], v97 offset:0xa000
	v_mfma_f32_16x16x32_bf16 v[180:183], v[158:161], v[242:245], v[180:183]
	ds_read_b64_tr_b16 v[242:243], v98 offset:0xa000
	ds_read_b64_tr_b16 v[244:245], v99 offset:0xa000
	v_mfma_f32_16x16x32_bf16 v[184:187], v[158:161], v[246:249], v[184:187]
	ds_read_b64_tr_b16 v[246:247], v100 offset:0xa000
	ds_read_b64_tr_b16 v[248:249], v101 offset:0xa000
	s_waitcnt lgkmcnt(0)
	v_mfma_f32_16x16x32_bf16 v[146:149], v[158:161], v[32:35], v[146:149]
	ds_read_b64_tr_b16 v[158:159], v76 offset:0xc000
	ds_read_b64_tr_b16 v[160:161], v77 offset:0xc000
	s_waitcnt lgkmcnt(2)
	v_mfma_f32_16x16x32_bf16 v[142:145], v[196:199], v[204:207], v[142:145]
	ds_read_b64_tr_b16 v[204:205], v78 offset:0xc000
	ds_read_b64_tr_b16 v[206:207], v79 offset:0xc000
	v_mfma_f32_16x16x32_bf16 v[150:153], v[196:199], v[208:211], v[150:153]
	ds_read_b64_tr_b16 v[208:209], v90 offset:0xc000
	ds_read_b64_tr_b16 v[210:211], v91 offset:0xc000
	v_mfma_f32_16x16x32_bf16 v[154:157], v[196:199], v[226:229], v[154:157]
	ds_read_b64_tr_b16 v[226:227], v92 offset:0xc000
	ds_read_b64_tr_b16 v[228:229], v93 offset:0xc000
	v_mfma_f32_16x16x32_bf16 v[162:165], v[196:199], v[230:233], v[162:165]
	ds_read_b64_tr_b16 v[230:231], v94 offset:0xc000
	ds_read_b64_tr_b16 v[232:233], v95 offset:0xc000
	v_mfma_f32_16x16x32_bf16 v[166:169], v[196:199], v[234:237], v[166:169]
	ds_read_b64_tr_b16 v[234:235], v96 offset:0xc000
	ds_read_b64_tr_b16 v[236:237], v97 offset:0xc000
	v_mfma_f32_16x16x32_bf16 v[170:173], v[196:199], v[238:241], v[170:173]
	ds_read_b64_tr_b16 v[238:239], v98 offset:0xc000
	ds_read_b64_tr_b16 v[240:241], v99 offset:0xc000
	v_mfma_f32_16x16x32_bf16 v[180:183], v[196:199], v[242:245], v[180:183]
	ds_read_b64_tr_b16 v[242:243], v100 offset:0xc000
	ds_read_b64_tr_b16 v[244:245], v101 offset:0xc000
	s_waitcnt lgkmcnt(0)
	v_mfma_f32_16x16x32_bf16 v[184:187], v[196:199], v[246:249], v[184:187]
	v_mfma_f32_16x16x32_bf16 v[146:149], v[196:199], v[32:35], v[146:149]
	s_waitcnt lgkmcnt(1)
	v_mfma_f32_16x16x32_bf16 v[142:145], v[200:203], v[158:161], v[142:145]
	ds_read_b64_tr_b16 v[158:159], v76 offset:0xe000
	ds_read_b64_tr_b16 v[160:161], v77 offset:0xe000
	ds_read_b64_tr_b16 v[196:197], v78 offset:0xe000
	ds_read_b64_tr_b16 v[198:199], v79 offset:0xe000
	v_mfma_f32_16x16x32_bf16 v[150:153], v[200:203], v[204:207], v[150:153]
	ds_read_b64_tr_b16 v[204:205], v90 offset:0xe000
	ds_read_b64_tr_b16 v[206:207], v91 offset:0xe000
	v_mfma_f32_16x16x32_bf16 v[154:157], v[200:203], v[208:211], v[154:157]
	ds_read_b64_tr_b16 v[208:209], v92 offset:0xe000
	ds_read_b64_tr_b16 v[210:211], v93 offset:0xe000
	v_mfma_f32_16x16x32_bf16 v[162:165], v[200:203], v[226:229], v[162:165]
	ds_read_b64_tr_b16 v[226:227], v94 offset:0xe000
	ds_read_b64_tr_b16 v[228:229], v95 offset:0xe000
	v_mfma_f32_16x16x32_bf16 v[166:169], v[200:203], v[230:233], v[166:169]
	ds_read_b64_tr_b16 v[230:231], v96 offset:0xe000
	ds_read_b64_tr_b16 v[232:233], v97 offset:0xe000
	v_mfma_f32_16x16x32_bf16 v[170:173], v[200:203], v[234:237], v[170:173]
	ds_read_b64_tr_b16 v[234:235], v98 offset:0xe000
	ds_read_b64_tr_b16 v[236:237], v99 offset:0xe000
	v_mfma_f32_16x16x32_bf16 v[180:183], v[200:203], v[238:241], v[180:183]
	ds_read_b64_tr_b16 v[238:239], v100 offset:0xe000
	ds_read_b64_tr_b16 v[240:241], v101 offset:0xe000
	s_waitcnt lgkmcnt(0)
	v_mfma_f32_16x16x32_bf16 v[184:187], v[200:203], v[242:245], v[184:187]
	v_mfma_f32_16x16x32_bf16 v[146:149], v[200:203], v[32:35], v[146:149]
	s_waitcnt lgkmcnt(0)
	v_mfma_f32_16x16x32_bf16 v[146:149], v[40:43], v[32:35], v[146:149]
	v_max_f32_e32 v37, v37, v37
	v_max_f32_e32 v36, v36, v36
	v_max_f32_e32 v39, v39, v39
	v_mfma_f32_16x16x32_bf16 v[154:157], v[40:43], v[204:207], v[154:157]
	s_movk_i32 s73, 0x800
	s_nop 2
	ds_bpermute_b32 v141, v138, v146
	ds_bpermute_b32 v146, v138, v147
	v_mfma_f32_16x16x32_bf16 v[162:165], v[40:43], v[208:211], v[162:165]
	s_waitcnt lgkmcnt(1)
	v_max_f32_e64 v141, |v141|, |v141|
	s_waitcnt lgkmcnt(0)
	v_max_f32_e64 v146, |v146|, |v146|
	v_max_f32_e32 v146, v146, v37
	v_div_scale_f32 v147, s[58:59], v146, v146, 1.0
	v_mov_b32_e32 v175, v154
	v_rcp_f32_e32 v154, v147
	v_mfma_f32_16x16x32_bf16 v[166:169], v[40:43], v[226:229], v[166:169]
	v_mov_b32_e32 v174, v162
	v_max_f32_e32 v141, v141, v36
	v_fma_f32 v162, -v147, v154, 1.0
	v_fmac_f32_e32 v154, v162, v154
	v_div_scale_f32 v162, vcc, 1.0, v146, 1.0
	v_mfma_f32_16x16x32_bf16 v[170:173], v[40:43], v[230:233], v[170:173]
	s_nop 1
	v_mov_b32_e32 v189, v166
	v_mul_f32_e32 v166, v162, v154
	v_mfma_f32_16x16x32_bf16 v[184:187], v[40:43], v[238:241], v[184:187]
	v_mfma_f32_16x16x32_bf16 v[180:183], v[40:43], v[234:237], v[180:183]
	s_nop 1
	v_mov_b32_e32 v188, v170
	s_nop 3
	v_mov_b32_e32 v36, v184
	v_mfma_f32_16x16x32_bf16 v[142:145], v[40:43], v[158:161], v[142:145]
	v_fma_f32 v158, -v147, v166, v162
	v_fmac_f32_e32 v166, v158, v154
	v_fma_f32 v147, -v147, v166, v162
	v_mfma_f32_16x16x32_bf16 v[40:43], v[40:43], v[196:199], v[150:153]
	v_div_fmas_f32 v147, v147, v154, v166
	v_div_fixup_f32 v147, v147, v146, 1.0
	v_mov_b32_e32 v37, v180
	v_div_scale_f32 v150, s[58:59], v141, v141, 1.0
	v_rcp_f32_e32 v151, v150
	v_mov_b32_e32 v154, v163
	v_mov_b32_e32 v166, v171
	v_mov_b32_e32 v180, v185
	v_fma_f32 v146, -v150, v151, 1.0
	v_fmac_f32_e32 v151, v146, v151
	v_div_scale_f32 v146, vcc, 1.0, v141, 1.0
	v_mul_f32_e32 v152, v146, v151
	v_fma_f32 v153, -v150, v152, v146
	v_fmac_f32_e32 v152, v153, v151
	v_fma_f32 v146, -v150, v152, v146
	v_div_fmas_f32 v146, v146, v151, v152
	v_div_fixup_f32 v146, v146, v141, 1.0
	v_pk_fma_f32 v[68:69], v[40:41], v[146:147], v[68:69]
	ds_bpermute_b32 v40, v138, v149
	v_pk_fma_f32 v[66:67], v[142:143], v[146:147], v[66:67]
	v_pk_fma_f32 v[74:75], v[174:175], v[146:147], v[74:75] op_sel_hi:[1,0,1]
	v_pk_fma_f32 v[72:73], v[188:189], v[146:147], v[72:73] op_sel_hi:[1,0,1]
	v_pk_fma_f32 v[70:71], v[36:37], v[146:147], v[70:71] op_sel_hi:[1,0,1]
	s_waitcnt lgkmcnt(0)
	v_max_f32_e64 v40, |v40|, |v40|
	v_max_f32_e32 v142, v40, v39
	v_div_scale_f32 v143, s[58:59], v142, v142, 1.0
	v_rcp_f32_e32 v146, v143
	v_mov_b32_e32 v36, v147
	v_pk_fma_f32 v[64:65], v[154:155], v[36:37], v[64:65] op_sel_hi:[1,0,1]
	ds_bpermute_b32 v37, v138, v148
	v_fma_f32 v147, -v143, v146, 1.0
	v_fmac_f32_e32 v146, v147, v146
	v_div_scale_f32 v147, vcc, 1.0, v142, 1.0
	v_mul_f32_e32 v148, v147, v146
	s_waitcnt lgkmcnt(0)
	v_pk_fma_f32 v[62:63], v[166:167], v[36:37], v[62:63] op_sel_hi:[1,0,1]
	v_pk_fma_f32 v[60:61], v[180:181], v[36:37], v[60:61] op_sel_hi:[1,0,1]
	v_max_f32_e64 v36, |v37|, |v37|
	v_max_f32_e32 v37, v38, v38
	v_fma_f32 v149, -v143, v148, v147
	v_max_f32_e32 v141, v36, v37
	v_fmac_f32_e32 v148, v149, v146
	v_fma_f32 v143, -v143, v148, v147
	v_div_scale_f32 v147, s[58:59], v141, v141, 1.0
	v_rcp_f32_e32 v149, v147
	v_div_fmas_f32 v143, v143, v146, v148
	v_div_fixup_f32 v143, v143, v142, 1.0
	v_mov_b32_e32 v36, v164
	v_fma_f32 v142, -v147, v149, 1.0
	v_fmac_f32_e32 v149, v142, v149
	v_div_scale_f32 v142, vcc, 1.0, v141, 1.0
	v_mul_f32_e32 v146, v142, v149
	v_fma_f32 v148, -v147, v146, v142
	v_fmac_f32_e32 v146, v148, v149
	v_fma_f32 v142, -v147, v146, v142
	v_div_fmas_f32 v142, v142, v149, v146
	v_mov_b32_e32 v37, v156
	v_div_fixup_f32 v142, v142, v141, 1.0
	v_mov_b32_e32 v38, v172
	v_mov_b32_e32 v39, v168
	v_mov_b32_e32 v40, v186
	v_mov_b32_e32 v41, v182
	v_pk_fma_f32 v[58:59], v[36:37], v[142:143], v[58:59] op_sel_hi:[1,0,1]
	v_mov_b32_e32 v156, v165
	v_mov_b32_e32 v36, v143
	v_mov_b32_e32 v168, v173
	v_mov_b32_e32 v182, v187
	v_pk_fma_f32 v[52:53], v[144:145], v[142:143], v[52:53]
	v_pk_fma_f32 v[50:51], v[42:43], v[142:143], v[50:51]
	v_pk_fma_f32 v[56:57], v[38:39], v[142:143], v[56:57] op_sel_hi:[1,0,1]
	v_pk_fma_f32 v[54:55], v[40:41], v[142:143], v[54:55] op_sel_hi:[1,0,1]
	v_pk_fma_f32 v[48:49], v[156:157], v[36:37], v[48:49] op_sel_hi:[1,0,1]
	v_pk_fma_f32 v[46:47], v[168:169], v[36:37], v[46:47] op_sel_hi:[1,0,1]
	v_pk_fma_f32 v[44:45], v[182:183], v[36:37], v[44:45] op_sel_hi:[1,0,1]
	s_mov_b64 s[58:59], 0
	s_andn2_b64 vcc, exec, s[56:57]
	s_mov_b64 s[56:57], -1
	s_cbranch_vccz .LBB0_746
